# FoX prepare_bias: the 16 per-thread forget-gate loads (issued one at a time in divergent branches, each with a full drain) prefetched together with a per-lane address select; 6 inlined instances
# baseline (speedup 1.0000x reference)
.LBB0_797:
	s_ashr_i32 s44, s62, 31
	s_or_b32 s39, s62, 0xff
	s_lshr_b32 s44, s44, 26
	s_add_i32 s44, s39, s44
	s_ashr_i32 s44, s44, 6
	s_add_i32 s44, s44, 1
	s_min_i32 s18, s44, s18
	s_mov_b64 s[42:43], -1
	s_lshl_b32 s63, s18, 6
	v_mbcnt_lo_u32_b32 v51, -1, 0
	v_mbcnt_hi_u32_b32 v51, -1, v51
	s_andn2_b64 vcc, exec, s[2:3]
	v_add_u32_e32 v50, s87, v51
	s_cbranch_vccz .LBB0_944
	v_lshlrev_b32_e32 v52, 4, v50
	s_xor_b64 s[42:43], s[0:1], -1
	v_cmp_gt_i32_e64 s[0:1], s63, v52
	v_mov_b32_e32 v2, 0
	v_mov_b32_e32 v5, 0
	s_and_saveexec_b64 s[98:99], s[0:1]
	v_mov_b32_e32 v247, 0
	v_subrev_u32_e32 v246, s64, v52
	v_mad_i64_i32 v[244:245], s[100:101], s38, v52, 0
	v_lshl_add_u64 v[242:243], v[246:247], 2, s[40:41]
	v_cmp_le_i32_e64 s[100:101], s64, v52
	v_lshl_add_u64 v[244:245], v[244:245], 2, s[36:37]
	s_nop 1
	v_cndmask_b32_e64 v242, v244, v242, s[100:101]
	v_cndmask_b32_e64 v243, v245, v243, s[100:101]
	global_load_dword v224, v[242:243], off
	v_or_b32_e32 v240, 1, v52
	v_subrev_u32_e32 v246, s64, v240
	v_mad_i64_i32 v[244:245], s[100:101], s38, v240, 0
	v_lshl_add_u64 v[242:243], v[246:247], 2, s[40:41]
	v_cmp_le_i32_e64 s[100:101], s64, v240
	v_lshl_add_u64 v[244:245], v[244:245], 2, s[36:37]
	s_nop 1
	v_cndmask_b32_e64 v242, v244, v242, s[100:101]
	v_cndmask_b32_e64 v243, v245, v243, s[100:101]
	global_load_dword v225, v[242:243], off
	v_or_b32_e32 v240, 2, v52
	v_subrev_u32_e32 v246, s64, v240
	v_mad_i64_i32 v[244:245], s[100:101], s38, v240, 0
	v_lshl_add_u64 v[242:243], v[246:247], 2, s[40:41]
	v_cmp_le_i32_e64 s[100:101], s64, v240
	v_lshl_add_u64 v[244:245], v[244:245], 2, s[36:37]
	s_nop 1
	v_cndmask_b32_e64 v242, v244, v242, s[100:101]
	v_cndmask_b32_e64 v243, v245, v243, s[100:101]
	global_load_dword v226, v[242:243], off
	v_or_b32_e32 v240, 3, v52
	v_subrev_u32_e32 v246, s64, v240
	v_mad_i64_i32 v[244:245], s[100:101], s38, v240, 0
	v_lshl_add_u64 v[242:243], v[246:247], 2, s[40:41]
	v_cmp_le_i32_e64 s[100:101], s64, v240
	v_lshl_add_u64 v[244:245], v[244:245], 2, s[36:37]
	s_nop 1
	v_cndmask_b32_e64 v242, v244, v242, s[100:101]
	v_cndmask_b32_e64 v243, v245, v243, s[100:101]
	global_load_dword v227, v[242:243], off
	v_or_b32_e32 v240, 4, v52
	v_subrev_u32_e32 v246, s64, v240
	v_mad_i64_i32 v[244:245], s[100:101], s38, v240, 0
	v_lshl_add_u64 v[242:243], v[246:247], 2, s[40:41]
	v_cmp_le_i32_e64 s[100:101], s64, v240
	v_lshl_add_u64 v[244:245], v[244:245], 2, s[36:37]
	s_nop 1
	v_cndmask_b32_e64 v242, v244, v242, s[100:101]
	v_cndmask_b32_e64 v243, v245, v243, s[100:101]
	global_load_dword v228, v[242:243], off
	v_or_b32_e32 v240, 5, v52
	v_subrev_u32_e32 v246, s64, v240
	v_mad_i64_i32 v[244:245], s[100:101], s38, v240, 0
	v_lshl_add_u64 v[242:243], v[246:247], 2, s[40:41]
	v_cmp_le_i32_e64 s[100:101], s64, v240
	v_lshl_add_u64 v[244:245], v[244:245], 2, s[36:37]
	s_nop 1
	v_cndmask_b32_e64 v242, v244, v242, s[100:101]
	v_cndmask_b32_e64 v243, v245, v243, s[100:101]
	global_load_dword v229, v[242:243], off
	v_or_b32_e32 v240, 6, v52
	v_subrev_u32_e32 v246, s64, v240
	v_mad_i64_i32 v[244:245], s[100:101], s38, v240, 0
	v_lshl_add_u64 v[242:243], v[246:247], 2, s[40:41]
	v_cmp_le_i32_e64 s[100:101], s64, v240
	v_lshl_add_u64 v[244:245], v[244:245], 2, s[36:37]
	s_nop 1
	v_cndmask_b32_e64 v242, v244, v242, s[100:101]
	v_cndmask_b32_e64 v243, v245, v243, s[100:101]
	global_load_dword v230, v[242:243], off
	v_or_b32_e32 v240, 7, v52
	v_subrev_u32_e32 v246, s64, v240
	v_mad_i64_i32 v[244:245], s[100:101], s38, v240, 0
	v_lshl_add_u64 v[242:243], v[246:247], 2, s[40:41]
	v_cmp_le_i32_e64 s[100:101], s64, v240
	v_lshl_add_u64 v[244:245], v[244:245], 2, s[36:37]
	s_nop 1
	v_cndmask_b32_e64 v242, v244, v242, s[100:101]
	v_cndmask_b32_e64 v243, v245, v243, s[100:101]
	global_load_dword v231, v[242:243], off
	v_or_b32_e32 v240, 8, v52
	v_subrev_u32_e32 v246, s64, v240
	v_mad_i64_i32 v[244:245], s[100:101], s38, v240, 0
	v_lshl_add_u64 v[242:243], v[246:247], 2, s[40:41]
	v_cmp_le_i32_e64 s[100:101], s64, v240
	v_lshl_add_u64 v[244:245], v[244:245], 2, s[36:37]
	s_nop 1
	v_cndmask_b32_e64 v242, v244, v242, s[100:101]
	v_cndmask_b32_e64 v243, v245, v243, s[100:101]
	global_load_dword v232, v[242:243], off
	v_or_b32_e32 v240, 9, v52
	v_subrev_u32_e32 v246, s64, v240
	v_mad_i64_i32 v[244:245], s[100:101], s38, v240, 0
	v_lshl_add_u64 v[242:243], v[246:247], 2, s[40:41]
	v_cmp_le_i32_e64 s[100:101], s64, v240
	v_lshl_add_u64 v[244:245], v[244:245], 2, s[36:37]
	s_nop 1
	v_cndmask_b32_e64 v242, v244, v242, s[100:101]
	v_cndmask_b32_e64 v243, v245, v243, s[100:101]
	global_load_dword v233, v[242:243], off
	v_or_b32_e32 v240, 10, v52
	v_subrev_u32_e32 v246, s64, v240
	v_mad_i64_i32 v[244:245], s[100:101], s38, v240, 0
	v_lshl_add_u64 v[242:243], v[246:247], 2, s[40:41]
	v_cmp_le_i32_e64 s[100:101], s64, v240
	v_lshl_add_u64 v[244:245], v[244:245], 2, s[36:37]
	s_nop 1
	v_cndmask_b32_e64 v242, v244, v242, s[100:101]
	v_cndmask_b32_e64 v243, v245, v243, s[100:101]
	global_load_dword v234, v[242:243], off
	v_or_b32_e32 v240, 11, v52
	v_subrev_u32_e32 v246, s64, v240
	v_mad_i64_i32 v[244:245], s[100:101], s38, v240, 0
	v_lshl_add_u64 v[242:243], v[246:247], 2, s[40:41]
	v_cmp_le_i32_e64 s[100:101], s64, v240
	v_lshl_add_u64 v[244:245], v[244:245], 2, s[36:37]
	s_nop 1
	v_cndmask_b32_e64 v242, v244, v242, s[100:101]
	v_cndmask_b32_e64 v243, v245, v243, s[100:101]
	global_load_dword v235, v[242:243], off
	v_or_b32_e32 v240, 12, v52
	v_subrev_u32_e32 v246, s64, v240
	v_mad_i64_i32 v[244:245], s[100:101], s38, v240, 0
	v_lshl_add_u64 v[242:243], v[246:247], 2, s[40:41]
	v_cmp_le_i32_e64 s[100:101], s64, v240
	v_lshl_add_u64 v[244:245], v[244:245], 2, s[36:37]
	s_nop 1
	v_cndmask_b32_e64 v242, v244, v242, s[100:101]
	v_cndmask_b32_e64 v243, v245, v243, s[100:101]
	global_load_dword v236, v[242:243], off
	v_or_b32_e32 v240, 13, v52
	v_subrev_u32_e32 v246, s64, v240
	v_mad_i64_i32 v[244:245], s[100:101], s38, v240, 0
	v_lshl_add_u64 v[242:243], v[246:247], 2, s[40:41]
	v_cmp_le_i32_e64 s[100:101], s64, v240
	v_lshl_add_u64 v[244:245], v[244:245], 2, s[36:37]
	s_nop 1
	v_cndmask_b32_e64 v242, v244, v242, s[100:101]
	v_cndmask_b32_e64 v243, v245, v243, s[100:101]
	global_load_dword v237, v[242:243], off
	v_or_b32_e32 v240, 14, v52
	v_subrev_u32_e32 v246, s64, v240
	v_mad_i64_i32 v[244:245], s[100:101], s38, v240, 0
	v_lshl_add_u64 v[242:243], v[246:247], 2, s[40:41]
	v_cmp_le_i32_e64 s[100:101], s64, v240
	v_lshl_add_u64 v[244:245], v[244:245], 2, s[36:37]
	s_nop 1
	v_cndmask_b32_e64 v242, v244, v242, s[100:101]
	v_cndmask_b32_e64 v243, v245, v243, s[100:101]
	global_load_dword v238, v[242:243], off
	v_or_b32_e32 v240, 15, v52
	v_subrev_u32_e32 v246, s64, v240
	v_mad_i64_i32 v[244:245], s[100:101], s38, v240, 0
	v_lshl_add_u64 v[242:243], v[246:247], 2, s[40:41]
	v_cmp_le_i32_e64 s[100:101], s64, v240
	v_lshl_add_u64 v[244:245], v[244:245], 2, s[36:37]
	s_nop 1
	v_cndmask_b32_e64 v242, v244, v242, s[100:101]
	v_cndmask_b32_e64 v243, v245, v243, s[100:101]
	global_load_dword v239, v[242:243], off
	s_mov_b64 exec, s[98:99]
	s_waitcnt vmcnt(0)
	s_and_saveexec_b64 s[44:45], s[0:1]
	s_cbranch_execz .LBB0_805
	v_cmp_le_i32_e32 vcc, s64, v52
	s_and_saveexec_b64 s[2:3], vcc
	s_xor_b64 s[46:47], exec, s[2:3]
	s_cbranch_execz .LBB0_801
	v_subrev_u32_e32 v0, s64, v52
	v_lshl_add_u64 v[4:5], v[0:1], 2, s[40:41]
	v_mov_b32_e32 v0, v224
	s_waitcnt vmcnt(0)
	v_mul_f32_e64 v3, |v0|, s92
	v_exp_f32_e32 v3, v3
	v_max_f32_e32 v0, v0, v0
	v_min_f32_e32 v0, 0, v0
	v_add_f32_e32 v3, 1.0, v3
	v_cmp_gt_f32_e32 vcc, s93, v3
	s_nop 1
	v_cndmask_b32_e64 v4, 0, 32, vcc
	v_ldexp_f32 v3, v3, v4
	v_log_f32_e32 v3, v3
	s_nop 0
	v_mul_f32_e32 v4, 0x3f317217, v3
	v_fma_f32 v4, v3, s94, -v4
	v_fmac_f32_e32 v4, 0x3377d1cf, v3
	v_fmac_f32_e32 v4, 0x3f317217, v3
	v_cmp_lt_f32_e64 s[2:3], |v3|, s95
	s_nop 1
	v_cndmask_b32_e64 v3, v3, v4, s[2:3]
	v_cndmask_b32_e32 v4, 0, v203, vcc
	v_sub_f32_e32 v3, v3, v4
	v_sub_f32_e32 v5, v0, v3
.LBB0_801:
	s_andn2_saveexec_b64 s[46:47], s[46:47]
	s_cbranch_execz .LBB0_804
	v_mad_i64_i32 v[4:5], s[2:3], s38, v52, 0
	v_lshl_add_u64 v[4:5], v[4:5], 2, s[36:37]
	v_mov_b32_e32 v5, v224
	s_andn2_b64 vcc, exec, s[42:43]
	s_cbranch_vccnz .LBB0_804
	s_waitcnt vmcnt(0)
	v_mul_f32_e64 v0, |v5|, s92
	v_exp_f32_e32 v0, v0
	s_nop 0
	v_add_f32_e32 v0, 1.0, v0
	v_cmp_gt_f32_e32 vcc, s93, v0
	s_nop 1
	v_cndmask_b32_e64 v3, 0, 32, vcc
	v_ldexp_f32 v0, v0, v3
	v_log_f32_e32 v0, v0
	v_max_f32_e32 v3, v5, v5
	v_min_f32_e32 v3, 0, v3
	v_mul_f32_e32 v4, 0x3f317217, v0
	v_fma_f32 v4, v0, s94, -v4
	v_fmac_f32_e32 v4, 0x3377d1cf, v0
	v_fmac_f32_e32 v4, 0x3f317217, v0
	v_cmp_lt_f32_e64 s[2:3], |v0|, s95
	s_nop 1
	v_cndmask_b32_e64 v0, v0, v4, s[2:3]
	v_cndmask_b32_e32 v4, 0, v203, vcc
	v_sub_f32_e32 v0, v0, v4
	v_sub_f32_e32 v5, v3, v0

.LBB0_805:
	s_or_b64 exec, exec, s[44:45]
	v_or_b32_e32 v53, 1, v52
	s_and_saveexec_b64 s[44:45], s[0:1]
	s_cbranch_execz .LBB0_812
	v_cmp_le_i32_e32 vcc, s64, v53
	s_and_saveexec_b64 s[2:3], vcc
	s_xor_b64 s[46:47], exec, s[2:3]
	s_cbranch_execz .LBB0_808
	v_subrev_u32_e32 v0, s64, v53
	v_lshl_add_u64 v[2:3], v[0:1], 2, s[40:41]
	v_mov_b32_e32 v0, v225
	s_waitcnt vmcnt(0)
	v_mul_f32_e64 v2, |v0|, s92
	v_exp_f32_e32 v2, v2
	v_max_f32_e32 v0, v0, v0
	v_min_f32_e32 v0, 0, v0
	v_add_f32_e32 v2, 1.0, v2
	v_cmp_gt_f32_e32 vcc, s93, v2
	s_nop 1
	v_cndmask_b32_e64 v3, 0, 32, vcc
	v_ldexp_f32 v2, v2, v3
	v_log_f32_e32 v2, v2
	s_nop 0
	v_mul_f32_e32 v3, 0x3f317217, v2
	v_fma_f32 v3, v2, s94, -v3
	v_fmac_f32_e32 v3, 0x3377d1cf, v2
	v_fmac_f32_e32 v3, 0x3f317217, v2
	v_cmp_lt_f32_e64 s[2:3], |v2|, s95
	s_nop 1
	v_cndmask_b32_e64 v2, v2, v3, s[2:3]
	v_cndmask_b32_e32 v3, 0, v203, vcc
	v_sub_f32_e32 v2, v2, v3
	v_sub_f32_e32 v2, v0, v2
.LBB0_808:
	s_andn2_saveexec_b64 s[46:47], s[46:47]
	s_cbranch_execz .LBB0_811
	v_mad_i64_i32 v[2:3], s[2:3], s38, v53, 0
	v_lshl_add_u64 v[2:3], v[2:3], 2, s[36:37]
	v_mov_b32_e32 v2, v225
	s_andn2_b64 vcc, exec, s[42:43]
	s_cbranch_vccnz .LBB0_811
	s_waitcnt vmcnt(0)
	v_mul_f32_e64 v0, |v2|, s92
	v_exp_f32_e32 v0, v0
	v_max_f32_e32 v2, v2, v2
	v_min_f32_e32 v2, 0, v2
	v_add_f32_e32 v0, 1.0, v0
	v_cmp_gt_f32_e32 vcc, s93, v0
	s_nop 1
	v_cndmask_b32_e64 v3, 0, 32, vcc
	v_ldexp_f32 v0, v0, v3
	v_log_f32_e32 v0, v0
	s_nop 0
	v_mul_f32_e32 v3, 0x3f317217, v0
	v_fma_f32 v3, v0, s94, -v3
	v_fmac_f32_e32 v3, 0x3377d1cf, v0
	v_fmac_f32_e32 v3, 0x3f317217, v0
	v_cmp_lt_f32_e64 s[2:3], |v0|, s95
	s_nop 1
	v_cndmask_b32_e64 v0, v0, v3, s[2:3]
	v_cndmask_b32_e32 v3, 0, v203, vcc
	v_sub_f32_e32 v0, v0, v3
	v_sub_f32_e32 v2, v2, v0

.LBB0_812:
	s_or_b64 exec, exec, s[44:45]
	v_or_b32_e32 v54, 2, v52
	v_mov_b32_e32 v4, 0
	v_mov_b32_e32 v3, 0
	s_and_saveexec_b64 s[44:45], s[0:1]
	s_cbranch_execz .LBB0_819
	v_cmp_le_i32_e32 vcc, s64, v54
	s_and_saveexec_b64 s[2:3], vcc
	s_xor_b64 s[46:47], exec, s[2:3]
	s_cbranch_execz .LBB0_815
	v_subrev_u32_e32 v0, s64, v54
	v_lshl_add_u64 v[6:7], v[0:1], 2, s[40:41]
	v_mov_b32_e32 v0, v226
	s_waitcnt vmcnt(0)
	v_mul_f32_e64 v3, |v0|, s92
	v_exp_f32_e32 v3, v3
	v_max_f32_e32 v0, v0, v0
	v_min_f32_e32 v0, 0, v0
	v_add_f32_e32 v3, 1.0, v3
	v_cmp_gt_f32_e32 vcc, s93, v3
	s_nop 1
	v_cndmask_b32_e64 v6, 0, 32, vcc
	v_ldexp_f32 v3, v3, v6
	v_log_f32_e32 v3, v3
	s_nop 0
	v_mul_f32_e32 v6, 0x3f317217, v3
	v_fma_f32 v6, v3, s94, -v6
	v_fmac_f32_e32 v6, 0x3377d1cf, v3
	v_fmac_f32_e32 v6, 0x3f317217, v3
	v_cmp_lt_f32_e64 s[2:3], |v3|, s95
	s_nop 1
	v_cndmask_b32_e64 v3, v3, v6, s[2:3]
	v_cndmask_b32_e32 v6, 0, v203, vcc
	v_sub_f32_e32 v3, v3, v6
	v_sub_f32_e32 v3, v0, v3
.LBB0_815:
	s_andn2_saveexec_b64 s[46:47], s[46:47]
	s_cbranch_execz .LBB0_818
	v_mad_i64_i32 v[6:7], s[2:3], s38, v54, 0
	v_lshl_add_u64 v[6:7], v[6:7], 2, s[36:37]
	v_mov_b32_e32 v3, v226
	s_andn2_b64 vcc, exec, s[42:43]
	s_cbranch_vccnz .LBB0_818
	s_waitcnt vmcnt(0)
	v_mul_f32_e64 v0, |v3|, s92
	v_exp_f32_e32 v0, v0
	v_max_f32_e32 v3, v3, v3
	v_min_f32_e32 v3, 0, v3
	v_add_f32_e32 v0, 1.0, v0
	v_cmp_gt_f32_e32 vcc, s93, v0
	s_nop 1
	v_cndmask_b32_e64 v6, 0, 32, vcc
	v_ldexp_f32 v0, v0, v6
	v_log_f32_e32 v0, v0
	s_nop 0
	v_mul_f32_e32 v6, 0x3f317217, v0
	v_fma_f32 v6, v0, s94, -v6
	v_fmac_f32_e32 v6, 0x3377d1cf, v0
	v_fmac_f32_e32 v6, 0x3f317217, v0
	v_cmp_lt_f32_e64 s[2:3], |v0|, s95
	s_nop 1
	v_cndmask_b32_e64 v0, v0, v6, s[2:3]
	v_cndmask_b32_e32 v6, 0, v203, vcc
	v_sub_f32_e32 v0, v0, v6
	v_sub_f32_e32 v3, v3, v0

.LBB0_819:
	s_or_b64 exec, exec, s[44:45]
	v_or_b32_e32 v55, 3, v52
	s_and_saveexec_b64 s[44:45], s[0:1]
	s_cbranch_execz .LBB0_826
	v_cmp_le_i32_e32 vcc, s64, v55
	s_and_saveexec_b64 s[2:3], vcc
	s_xor_b64 s[46:47], exec, s[2:3]
	s_cbranch_execz .LBB0_822
	v_subrev_u32_e32 v0, s64, v55
	v_lshl_add_u64 v[6:7], v[0:1], 2, s[40:41]
	v_mov_b32_e32 v0, v227
	s_waitcnt vmcnt(0)
	v_mul_f32_e64 v4, |v0|, s92
	v_exp_f32_e32 v4, v4
	v_max_f32_e32 v0, v0, v0
	v_min_f32_e32 v0, 0, v0
	v_add_f32_e32 v4, 1.0, v4
	v_cmp_gt_f32_e32 vcc, s93, v4
	s_nop 1
	v_cndmask_b32_e64 v6, 0, 32, vcc
	v_ldexp_f32 v4, v4, v6
	v_log_f32_e32 v4, v4
	s_nop 0
	v_mul_f32_e32 v6, 0x3f317217, v4
	v_fma_f32 v6, v4, s94, -v6
	v_fmac_f32_e32 v6, 0x3377d1cf, v4
	v_fmac_f32_e32 v6, 0x3f317217, v4
	v_cmp_lt_f32_e64 s[2:3], |v4|, s95
	s_nop 1
	v_cndmask_b32_e64 v4, v4, v6, s[2:3]
	v_cndmask_b32_e32 v6, 0, v203, vcc
	v_sub_f32_e32 v4, v4, v6
	v_sub_f32_e32 v4, v0, v4
.LBB0_822:
	s_andn2_saveexec_b64 s[46:47], s[46:47]
	s_cbranch_execz .LBB0_825
	v_mad_i64_i32 v[6:7], s[2:3], s38, v55, 0
	v_lshl_add_u64 v[6:7], v[6:7], 2, s[36:37]
	v_mov_b32_e32 v4, v227
	s_andn2_b64 vcc, exec, s[42:43]
	s_cbranch_vccnz .LBB0_825
	s_waitcnt vmcnt(0)
	v_mul_f32_e64 v0, |v4|, s92
	v_exp_f32_e32 v0, v0
	v_max_f32_e32 v4, v4, v4
	v_min_f32_e32 v4, 0, v4
	v_add_f32_e32 v0, 1.0, v0
	v_cmp_gt_f32_e32 vcc, s93, v0
	s_nop 1
	v_cndmask_b32_e64 v6, 0, 32, vcc
	v_ldexp_f32 v0, v0, v6
	v_log_f32_e32 v0, v0
	s_nop 0
	v_mul_f32_e32 v6, 0x3f317217, v0
	v_fma_f32 v6, v0, s94, -v6
	v_fmac_f32_e32 v6, 0x3377d1cf, v0
	v_fmac_f32_e32 v6, 0x3f317217, v0
	v_cmp_lt_f32_e64 s[2:3], |v0|, s95
	s_nop 1
	v_cndmask_b32_e64 v0, v0, v6, s[2:3]
	v_cndmask_b32_e32 v6, 0, v203, vcc
	v_sub_f32_e32 v0, v0, v6
	v_sub_f32_e32 v4, v4, v0

.LBB0_826:
	s_or_b64 exec, exec, s[44:45]
	v_or_b32_e32 v56, 4, v52
	v_mov_b32_e32 v7, 0
	v_mov_b32_e32 v6, 0
	s_and_saveexec_b64 s[44:45], s[0:1]
	s_cbranch_execz .LBB0_833
	v_cmp_le_i32_e32 vcc, s64, v56
	s_and_saveexec_b64 s[2:3], vcc
	s_xor_b64 s[46:47], exec, s[2:3]
	s_cbranch_execz .LBB0_829
	v_subrev_u32_e32 v0, s64, v56
	v_lshl_add_u64 v[8:9], v[0:1], 2, s[40:41]
	v_mov_b32_e32 v0, v228
	s_waitcnt vmcnt(0)
	v_mul_f32_e64 v6, |v0|, s92
	v_exp_f32_e32 v6, v6
	v_max_f32_e32 v0, v0, v0
	v_min_f32_e32 v0, 0, v0
	v_add_f32_e32 v6, 1.0, v6
	v_cmp_gt_f32_e32 vcc, s93, v6
	s_nop 1
	v_cndmask_b32_e64 v8, 0, 32, vcc
	v_ldexp_f32 v6, v6, v8
	v_log_f32_e32 v6, v6
	s_nop 0
	v_mul_f32_e32 v8, 0x3f317217, v6
	v_fma_f32 v8, v6, s94, -v8
	v_fmac_f32_e32 v8, 0x3377d1cf, v6
	v_fmac_f32_e32 v8, 0x3f317217, v6
	v_cmp_lt_f32_e64 s[2:3], |v6|, s95
	s_nop 1
	v_cndmask_b32_e64 v6, v6, v8, s[2:3]
	v_cndmask_b32_e32 v8, 0, v203, vcc
	v_sub_f32_e32 v6, v6, v8
	v_sub_f32_e32 v6, v0, v6
.LBB0_829:
	s_andn2_saveexec_b64 s[46:47], s[46:47]
	s_cbranch_execz .LBB0_832
	v_mad_i64_i32 v[8:9], s[2:3], s38, v56, 0
	v_lshl_add_u64 v[8:9], v[8:9], 2, s[36:37]
	v_mov_b32_e32 v6, v228
	s_andn2_b64 vcc, exec, s[42:43]
	s_cbranch_vccnz .LBB0_832
	s_waitcnt vmcnt(0)
	v_mul_f32_e64 v0, |v6|, s92
	v_exp_f32_e32 v0, v0
	v_max_f32_e32 v6, v6, v6
	v_min_f32_e32 v6, 0, v6
	v_add_f32_e32 v0, 1.0, v0
	v_cmp_gt_f32_e32 vcc, s93, v0
	s_nop 1
	v_cndmask_b32_e64 v8, 0, 32, vcc
	v_ldexp_f32 v0, v0, v8
	v_log_f32_e32 v0, v0
	s_nop 0
	v_mul_f32_e32 v8, 0x3f317217, v0
	v_fma_f32 v8, v0, s94, -v8
	v_fmac_f32_e32 v8, 0x3377d1cf, v0
	v_fmac_f32_e32 v8, 0x3f317217, v0
	v_cmp_lt_f32_e64 s[2:3], |v0|, s95
	s_nop 1
	v_cndmask_b32_e64 v0, v0, v8, s[2:3]
	v_cndmask_b32_e32 v8, 0, v203, vcc
	v_sub_f32_e32 v0, v0, v8
	v_sub_f32_e32 v6, v6, v0

.LBB0_833:
	s_or_b64 exec, exec, s[44:45]
	v_or_b32_e32 v57, 5, v52
	s_and_saveexec_b64 s[44:45], s[0:1]
	s_cbranch_execz .LBB0_840
	v_cmp_le_i32_e32 vcc, s64, v57
	s_and_saveexec_b64 s[2:3], vcc
	s_xor_b64 s[46:47], exec, s[2:3]
	s_cbranch_execz .LBB0_836
	v_subrev_u32_e32 v0, s64, v57
	v_lshl_add_u64 v[8:9], v[0:1], 2, s[40:41]
	v_mov_b32_e32 v0, v229
	s_waitcnt vmcnt(0)
	v_mul_f32_e64 v7, |v0|, s92
	v_exp_f32_e32 v7, v7
	v_max_f32_e32 v0, v0, v0
	v_min_f32_e32 v0, 0, v0
	v_add_f32_e32 v7, 1.0, v7
	v_cmp_gt_f32_e32 vcc, s93, v7
	s_nop 1
	v_cndmask_b32_e64 v8, 0, 32, vcc
	v_ldexp_f32 v7, v7, v8
	v_log_f32_e32 v7, v7
	s_nop 0
	v_mul_f32_e32 v8, 0x3f317217, v7
	v_fma_f32 v8, v7, s94, -v8
	v_fmac_f32_e32 v8, 0x3377d1cf, v7
	v_fmac_f32_e32 v8, 0x3f317217, v7
	v_cmp_lt_f32_e64 s[2:3], |v7|, s95
	s_nop 1
	v_cndmask_b32_e64 v7, v7, v8, s[2:3]
	v_cndmask_b32_e32 v8, 0, v203, vcc
	v_sub_f32_e32 v7, v7, v8
	v_sub_f32_e32 v7, v0, v7
.LBB0_836:
	s_andn2_saveexec_b64 s[46:47], s[46:47]
	s_cbranch_execz .LBB0_839
	v_mad_i64_i32 v[8:9], s[2:3], s38, v57, 0
	v_lshl_add_u64 v[8:9], v[8:9], 2, s[36:37]
	v_mov_b32_e32 v7, v229
	s_andn2_b64 vcc, exec, s[42:43]
	s_cbranch_vccnz .LBB0_839
	s_waitcnt vmcnt(0)
	v_mul_f32_e64 v0, |v7|, s92
	v_exp_f32_e32 v0, v0
	v_max_f32_e32 v7, v7, v7
	v_min_f32_e32 v7, 0, v7
	v_add_f32_e32 v0, 1.0, v0
	v_cmp_gt_f32_e32 vcc, s93, v0
	s_nop 1
	v_cndmask_b32_e64 v8, 0, 32, vcc
	v_ldexp_f32 v0, v0, v8
	v_log_f32_e32 v0, v0
	s_nop 0
	v_mul_f32_e32 v8, 0x3f317217, v0
	v_fma_f32 v8, v0, s94, -v8
	v_fmac_f32_e32 v8, 0x3377d1cf, v0
	v_fmac_f32_e32 v8, 0x3f317217, v0
	v_cmp_lt_f32_e64 s[2:3], |v0|, s95
	s_nop 1
	v_cndmask_b32_e64 v0, v0, v8, s[2:3]
	v_cndmask_b32_e32 v8, 0, v203, vcc
	v_sub_f32_e32 v0, v0, v8
	v_sub_f32_e32 v7, v7, v0

.LBB0_840:
	s_or_b64 exec, exec, s[44:45]
	v_or_b32_e32 v58, 6, v52
	v_mov_b32_e32 v9, 0
	v_mov_b32_e32 v8, 0
	s_and_saveexec_b64 s[44:45], s[0:1]
	s_cbranch_execz .LBB0_847
	v_cmp_le_i32_e32 vcc, s64, v58
	s_and_saveexec_b64 s[2:3], vcc
	s_xor_b64 s[46:47], exec, s[2:3]
	s_cbranch_execz .LBB0_843
	v_subrev_u32_e32 v0, s64, v58
	v_lshl_add_u64 v[10:11], v[0:1], 2, s[40:41]
	v_mov_b32_e32 v0, v230
	s_waitcnt vmcnt(0)
	v_mul_f32_e64 v8, |v0|, s92
	v_exp_f32_e32 v8, v8
	v_max_f32_e32 v0, v0, v0
	v_min_f32_e32 v0, 0, v0
	v_add_f32_e32 v8, 1.0, v8
	v_cmp_gt_f32_e32 vcc, s93, v8
	s_nop 1
	v_cndmask_b32_e64 v10, 0, 32, vcc
	v_ldexp_f32 v8, v8, v10
	v_log_f32_e32 v8, v8
	s_nop 0
	v_mul_f32_e32 v10, 0x3f317217, v8
	v_fma_f32 v10, v8, s94, -v10
	v_fmac_f32_e32 v10, 0x3377d1cf, v8
	v_fmac_f32_e32 v10, 0x3f317217, v8
	v_cmp_lt_f32_e64 s[2:3], |v8|, s95
	s_nop 1
	v_cndmask_b32_e64 v8, v8, v10, s[2:3]
	v_cndmask_b32_e32 v10, 0, v203, vcc
	v_sub_f32_e32 v8, v8, v10
	v_sub_f32_e32 v8, v0, v8
.LBB0_843:
	s_andn2_saveexec_b64 s[46:47], s[46:47]
	s_cbranch_execz .LBB0_846
	v_mad_i64_i32 v[10:11], s[2:3], s38, v58, 0
	v_lshl_add_u64 v[10:11], v[10:11], 2, s[36:37]
	v_mov_b32_e32 v8, v230
	s_andn2_b64 vcc, exec, s[42:43]
	s_cbranch_vccnz .LBB0_846
	s_waitcnt vmcnt(0)
	v_mul_f32_e64 v0, |v8|, s92
	v_exp_f32_e32 v0, v0
	v_max_f32_e32 v8, v8, v8
	v_min_f32_e32 v8, 0, v8
	v_add_f32_e32 v0, 1.0, v0
	v_cmp_gt_f32_e32 vcc, s93, v0
	s_nop 1
	v_cndmask_b32_e64 v10, 0, 32, vcc
	v_ldexp_f32 v0, v0, v10
	v_log_f32_e32 v0, v0
	s_nop 0
	v_mul_f32_e32 v10, 0x3f317217, v0
	v_fma_f32 v10, v0, s94, -v10
	v_fmac_f32_e32 v10, 0x3377d1cf, v0
	v_fmac_f32_e32 v10, 0x3f317217, v0
	v_cmp_lt_f32_e64 s[2:3], |v0|, s95
	s_nop 1
	v_cndmask_b32_e64 v0, v0, v10, s[2:3]
	v_cndmask_b32_e32 v10, 0, v203, vcc
	v_sub_f32_e32 v0, v0, v10
	v_sub_f32_e32 v8, v8, v0

.LBB0_847:
	s_or_b64 exec, exec, s[44:45]
	v_or_b32_e32 v59, 7, v52
	s_and_saveexec_b64 s[44:45], s[0:1]
	s_cbranch_execz .LBB0_854
	v_cmp_le_i32_e32 vcc, s64, v59
	s_and_saveexec_b64 s[2:3], vcc
	s_xor_b64 s[46:47], exec, s[2:3]
	s_cbranch_execz .LBB0_850
	v_subrev_u32_e32 v0, s64, v59
	v_lshl_add_u64 v[10:11], v[0:1], 2, s[40:41]
	v_mov_b32_e32 v0, v231
	s_waitcnt vmcnt(0)
	v_mul_f32_e64 v9, |v0|, s92
	v_exp_f32_e32 v9, v9
	v_max_f32_e32 v0, v0, v0
	v_min_f32_e32 v0, 0, v0
	v_add_f32_e32 v9, 1.0, v9
	v_cmp_gt_f32_e32 vcc, s93, v9
	s_nop 1
	v_cndmask_b32_e64 v10, 0, 32, vcc
	v_ldexp_f32 v9, v9, v10
	v_log_f32_e32 v9, v9
	s_nop 0
	v_mul_f32_e32 v10, 0x3f317217, v9
	v_fma_f32 v10, v9, s94, -v10
	v_fmac_f32_e32 v10, 0x3377d1cf, v9
	v_fmac_f32_e32 v10, 0x3f317217, v9
	v_cmp_lt_f32_e64 s[2:3], |v9|, s95
	s_nop 1
	v_cndmask_b32_e64 v9, v9, v10, s[2:3]
	v_cndmask_b32_e32 v10, 0, v203, vcc
	v_sub_f32_e32 v9, v9, v10
	v_sub_f32_e32 v9, v0, v9
.LBB0_850:
	s_andn2_saveexec_b64 s[46:47], s[46:47]
	s_cbranch_execz .LBB0_853
	v_mad_i64_i32 v[10:11], s[2:3], s38, v59, 0
	v_lshl_add_u64 v[10:11], v[10:11], 2, s[36:37]
	v_mov_b32_e32 v9, v231
	s_andn2_b64 vcc, exec, s[42:43]
	s_cbranch_vccnz .LBB0_853
	s_waitcnt vmcnt(0)
	v_mul_f32_e64 v0, |v9|, s92
	v_exp_f32_e32 v0, v0
	v_max_f32_e32 v9, v9, v9
	v_min_f32_e32 v9, 0, v9
	v_add_f32_e32 v0, 1.0, v0
	v_cmp_gt_f32_e32 vcc, s93, v0
	s_nop 1
	v_cndmask_b32_e64 v10, 0, 32, vcc
	v_ldexp_f32 v0, v0, v10
	v_log_f32_e32 v0, v0
	s_nop 0
	v_mul_f32_e32 v10, 0x3f317217, v0
	v_fma_f32 v10, v0, s94, -v10
	v_fmac_f32_e32 v10, 0x3377d1cf, v0
	v_fmac_f32_e32 v10, 0x3f317217, v0
	v_cmp_lt_f32_e64 s[2:3], |v0|, s95
	s_nop 1
	v_cndmask_b32_e64 v0, v0, v10, s[2:3]
	v_cndmask_b32_e32 v10, 0, v203, vcc
	v_sub_f32_e32 v0, v0, v10
	v_sub_f32_e32 v9, v9, v0

.LBB0_854:
	s_or_b64 exec, exec, s[44:45]
	v_or_b32_e32 v60, 8, v52
	v_mov_b32_e32 v11, 0
	v_mov_b32_e32 v10, 0
	s_and_saveexec_b64 s[44:45], s[0:1]
	s_cbranch_execz .LBB0_861
	v_cmp_le_i32_e32 vcc, s64, v60
	s_and_saveexec_b64 s[2:3], vcc
	s_xor_b64 s[46:47], exec, s[2:3]
	s_cbranch_execz .LBB0_857
	v_subrev_u32_e32 v0, s64, v60
	v_lshl_add_u64 v[12:13], v[0:1], 2, s[40:41]
	v_mov_b32_e32 v0, v232
	s_waitcnt vmcnt(0)
	v_mul_f32_e64 v10, |v0|, s92
	v_exp_f32_e32 v10, v10
	v_max_f32_e32 v0, v0, v0
	v_min_f32_e32 v0, 0, v0
	v_add_f32_e32 v10, 1.0, v10
	v_cmp_gt_f32_e32 vcc, s93, v10
	s_nop 1
	v_cndmask_b32_e64 v12, 0, 32, vcc
	v_ldexp_f32 v10, v10, v12
	v_log_f32_e32 v10, v10
	s_nop 0
	v_mul_f32_e32 v12, 0x3f317217, v10
	v_fma_f32 v12, v10, s94, -v12
	v_fmac_f32_e32 v12, 0x3377d1cf, v10
	v_fmac_f32_e32 v12, 0x3f317217, v10
	v_cmp_lt_f32_e64 s[2:3], |v10|, s95
	s_nop 1
	v_cndmask_b32_e64 v10, v10, v12, s[2:3]
	v_cndmask_b32_e32 v12, 0, v203, vcc
	v_sub_f32_e32 v10, v10, v12
	v_sub_f32_e32 v10, v0, v10
.LBB0_857:
	s_andn2_saveexec_b64 s[46:47], s[46:47]
	s_cbranch_execz .LBB0_860
	v_mad_i64_i32 v[12:13], s[2:3], s38, v60, 0
	v_lshl_add_u64 v[12:13], v[12:13], 2, s[36:37]
	v_mov_b32_e32 v10, v232
	s_andn2_b64 vcc, exec, s[42:43]
	s_cbranch_vccnz .LBB0_860
	s_waitcnt vmcnt(0)
	v_mul_f32_e64 v0, |v10|, s92
	v_exp_f32_e32 v0, v0
	v_max_f32_e32 v10, v10, v10
	v_min_f32_e32 v10, 0, v10
	v_add_f32_e32 v0, 1.0, v0
	v_cmp_gt_f32_e32 vcc, s93, v0
	s_nop 1
	v_cndmask_b32_e64 v12, 0, 32, vcc
	v_ldexp_f32 v0, v0, v12
	v_log_f32_e32 v0, v0
	s_nop 0
	v_mul_f32_e32 v12, 0x3f317217, v0
	v_fma_f32 v12, v0, s94, -v12
	v_fmac_f32_e32 v12, 0x3377d1cf, v0
	v_fmac_f32_e32 v12, 0x3f317217, v0
	v_cmp_lt_f32_e64 s[2:3], |v0|, s95
	s_nop 1
	v_cndmask_b32_e64 v0, v0, v12, s[2:3]
	v_cndmask_b32_e32 v12, 0, v203, vcc
	v_sub_f32_e32 v0, v0, v12
	v_sub_f32_e32 v10, v10, v0

.LBB0_861:
	s_or_b64 exec, exec, s[44:45]
	v_or_b32_e32 v62, 9, v52
	s_and_saveexec_b64 s[44:45], s[0:1]
	s_cbranch_execz .LBB0_868
	v_cmp_le_i32_e32 vcc, s64, v62
	s_and_saveexec_b64 s[2:3], vcc
	s_xor_b64 s[46:47], exec, s[2:3]
	s_cbranch_execz .LBB0_864
	v_subrev_u32_e32 v0, s64, v62
	v_lshl_add_u64 v[12:13], v[0:1], 2, s[40:41]
	v_mov_b32_e32 v0, v233
	s_waitcnt vmcnt(0)
	v_mul_f32_e64 v11, |v0|, s92
	v_exp_f32_e32 v11, v11
	v_max_f32_e32 v0, v0, v0
	v_min_f32_e32 v0, 0, v0
	v_add_f32_e32 v11, 1.0, v11
	v_cmp_gt_f32_e32 vcc, s93, v11
	s_nop 1
	v_cndmask_b32_e64 v12, 0, 32, vcc
	v_ldexp_f32 v11, v11, v12
	v_log_f32_e32 v11, v11
	s_nop 0
	v_mul_f32_e32 v12, 0x3f317217, v11
	v_fma_f32 v12, v11, s94, -v12
	v_fmac_f32_e32 v12, 0x3377d1cf, v11
	v_fmac_f32_e32 v12, 0x3f317217, v11
	v_cmp_lt_f32_e64 s[2:3], |v11|, s95
	s_nop 1
	v_cndmask_b32_e64 v11, v11, v12, s[2:3]
	v_cndmask_b32_e32 v12, 0, v203, vcc
	v_sub_f32_e32 v11, v11, v12
	v_sub_f32_e32 v11, v0, v11
.LBB0_864:
	s_andn2_saveexec_b64 s[46:47], s[46:47]
	s_cbranch_execz .LBB0_867
	v_mad_i64_i32 v[12:13], s[2:3], s38, v62, 0
	v_lshl_add_u64 v[12:13], v[12:13], 2, s[36:37]
	v_mov_b32_e32 v11, v233
	s_andn2_b64 vcc, exec, s[42:43]
	s_cbranch_vccnz .LBB0_867
	s_waitcnt vmcnt(0)
	v_mul_f32_e64 v0, |v11|, s92
	v_exp_f32_e32 v0, v0
	v_max_f32_e32 v11, v11, v11
	v_min_f32_e32 v11, 0, v11
	v_add_f32_e32 v0, 1.0, v0
	v_cmp_gt_f32_e32 vcc, s93, v0
	s_nop 1
	v_cndmask_b32_e64 v12, 0, 32, vcc
	v_ldexp_f32 v0, v0, v12
	v_log_f32_e32 v0, v0
	s_nop 0
	v_mul_f32_e32 v12, 0x3f317217, v0
	v_fma_f32 v12, v0, s94, -v12
	v_fmac_f32_e32 v12, 0x3377d1cf, v0
	v_fmac_f32_e32 v12, 0x3f317217, v0
	v_cmp_lt_f32_e64 s[2:3], |v0|, s95
	s_nop 1
	v_cndmask_b32_e64 v0, v0, v12, s[2:3]
	v_cndmask_b32_e32 v12, 0, v203, vcc
	v_sub_f32_e32 v0, v0, v12
	v_sub_f32_e32 v11, v11, v0

.LBB0_868:
	s_or_b64 exec, exec, s[44:45]
	v_or_b32_e32 v64, 10, v52
	v_mov_b32_e32 v13, 0
	v_mov_b32_e32 v12, 0
	s_and_saveexec_b64 s[44:45], s[0:1]
	s_cbranch_execz .LBB0_875
	v_cmp_le_i32_e32 vcc, s64, v64
	s_and_saveexec_b64 s[2:3], vcc
	s_xor_b64 s[46:47], exec, s[2:3]
	s_cbranch_execz .LBB0_871
	v_subrev_u32_e32 v0, s64, v64
	v_lshl_add_u64 v[14:15], v[0:1], 2, s[40:41]
	v_mov_b32_e32 v0, v234
	s_waitcnt vmcnt(0)
	v_mul_f32_e64 v12, |v0|, s92
	v_exp_f32_e32 v12, v12
	v_max_f32_e32 v0, v0, v0
	v_min_f32_e32 v0, 0, v0
	v_add_f32_e32 v12, 1.0, v12
	v_cmp_gt_f32_e32 vcc, s93, v12
	s_nop 1
	v_cndmask_b32_e64 v14, 0, 32, vcc
	v_ldexp_f32 v12, v12, v14
	v_log_f32_e32 v12, v12
	s_nop 0
	v_mul_f32_e32 v14, 0x3f317217, v12
	v_fma_f32 v14, v12, s94, -v14
	v_fmac_f32_e32 v14, 0x3377d1cf, v12
	v_fmac_f32_e32 v14, 0x3f317217, v12
	v_cmp_lt_f32_e64 s[2:3], |v12|, s95
	s_nop 1
	v_cndmask_b32_e64 v12, v12, v14, s[2:3]
	v_cndmask_b32_e32 v14, 0, v203, vcc
	v_sub_f32_e32 v12, v12, v14
	v_sub_f32_e32 v12, v0, v12
.LBB0_871:
	s_andn2_saveexec_b64 s[46:47], s[46:47]
	s_cbranch_execz .LBB0_874
	v_mad_i64_i32 v[14:15], s[2:3], s38, v64, 0
	v_lshl_add_u64 v[14:15], v[14:15], 2, s[36:37]
	v_mov_b32_e32 v12, v234
	s_andn2_b64 vcc, exec, s[42:43]
	s_cbranch_vccnz .LBB0_874
	s_waitcnt vmcnt(0)
	v_mul_f32_e64 v0, |v12|, s92
	v_exp_f32_e32 v0, v0
	v_max_f32_e32 v12, v12, v12
	v_min_f32_e32 v12, 0, v12
	v_add_f32_e32 v0, 1.0, v0
	v_cmp_gt_f32_e32 vcc, s93, v0
	s_nop 1
	v_cndmask_b32_e64 v14, 0, 32, vcc
	v_ldexp_f32 v0, v0, v14
	v_log_f32_e32 v0, v0
	s_nop 0
	v_mul_f32_e32 v14, 0x3f317217, v0
	v_fma_f32 v14, v0, s94, -v14
	v_fmac_f32_e32 v14, 0x3377d1cf, v0
	v_fmac_f32_e32 v14, 0x3f317217, v0
	v_cmp_lt_f32_e64 s[2:3], |v0|, s95
	s_nop 1
	v_cndmask_b32_e64 v0, v0, v14, s[2:3]
	v_cndmask_b32_e32 v14, 0, v203, vcc
	v_sub_f32_e32 v0, v0, v14
	v_sub_f32_e32 v12, v12, v0

.LBB0_875:
	s_or_b64 exec, exec, s[44:45]
	v_or_b32_e32 v65, 11, v52
	s_and_saveexec_b64 s[44:45], s[0:1]
	s_cbranch_execz .LBB0_882
	v_cmp_le_i32_e32 vcc, s64, v65
	s_and_saveexec_b64 s[2:3], vcc
	s_xor_b64 s[46:47], exec, s[2:3]
	s_cbranch_execz .LBB0_878
	v_subrev_u32_e32 v0, s64, v65
	v_lshl_add_u64 v[14:15], v[0:1], 2, s[40:41]
	v_mov_b32_e32 v0, v235
	s_waitcnt vmcnt(0)
	v_mul_f32_e64 v13, |v0|, s92
	v_exp_f32_e32 v13, v13
	v_max_f32_e32 v0, v0, v0
	v_min_f32_e32 v0, 0, v0
	v_add_f32_e32 v13, 1.0, v13
	v_cmp_gt_f32_e32 vcc, s93, v13
	s_nop 1
	v_cndmask_b32_e64 v14, 0, 32, vcc
	v_ldexp_f32 v13, v13, v14
	v_log_f32_e32 v13, v13
	s_nop 0
	v_mul_f32_e32 v14, 0x3f317217, v13
	v_fma_f32 v14, v13, s94, -v14
	v_fmac_f32_e32 v14, 0x3377d1cf, v13
	v_fmac_f32_e32 v14, 0x3f317217, v13
	v_cmp_lt_f32_e64 s[2:3], |v13|, s95
	s_nop 1
	v_cndmask_b32_e64 v13, v13, v14, s[2:3]
	v_cndmask_b32_e32 v14, 0, v203, vcc
	v_sub_f32_e32 v13, v13, v14
	v_sub_f32_e32 v13, v0, v13
.LBB0_878:
	s_andn2_saveexec_b64 s[46:47], s[46:47]
	s_cbranch_execz .LBB0_881
	v_mad_i64_i32 v[14:15], s[2:3], s38, v65, 0
	v_lshl_add_u64 v[14:15], v[14:15], 2, s[36:37]
	v_mov_b32_e32 v13, v235
	s_andn2_b64 vcc, exec, s[42:43]
	s_cbranch_vccnz .LBB0_881
	s_waitcnt vmcnt(0)
	v_mul_f32_e64 v0, |v13|, s92
	v_exp_f32_e32 v0, v0
	v_max_f32_e32 v13, v13, v13
	v_min_f32_e32 v13, 0, v13
	v_add_f32_e32 v0, 1.0, v0
	v_cmp_gt_f32_e32 vcc, s93, v0
	s_nop 1
	v_cndmask_b32_e64 v14, 0, 32, vcc
	v_ldexp_f32 v0, v0, v14
	v_log_f32_e32 v0, v0
	s_nop 0
	v_mul_f32_e32 v14, 0x3f317217, v0
	v_fma_f32 v14, v0, s94, -v14
	v_fmac_f32_e32 v14, 0x3377d1cf, v0
	v_fmac_f32_e32 v14, 0x3f317217, v0
	v_cmp_lt_f32_e64 s[2:3], |v0|, s95
	s_nop 1
	v_cndmask_b32_e64 v0, v0, v14, s[2:3]
	v_cndmask_b32_e32 v14, 0, v203, vcc
	v_sub_f32_e32 v0, v0, v14
	v_sub_f32_e32 v13, v13, v0

.LBB0_882:
	s_or_b64 exec, exec, s[44:45]
	v_or_b32_e32 v61, 12, v52
	v_mov_b32_e32 v15, 0
	v_mov_b32_e32 v14, 0
	s_and_saveexec_b64 s[44:45], s[0:1]
	s_cbranch_execz .LBB0_889
	v_cmp_le_i32_e32 vcc, s64, v61
	s_and_saveexec_b64 s[2:3], vcc
	s_xor_b64 s[46:47], exec, s[2:3]
	s_cbranch_execz .LBB0_885
	v_subrev_u32_e32 v0, s64, v61
	v_lshl_add_u64 v[16:17], v[0:1], 2, s[40:41]
	v_mov_b32_e32 v0, v236
	s_waitcnt vmcnt(0)
	v_mul_f32_e64 v14, |v0|, s92
	v_exp_f32_e32 v14, v14
	v_max_f32_e32 v0, v0, v0
	v_min_f32_e32 v0, 0, v0
	v_add_f32_e32 v14, 1.0, v14
	v_cmp_gt_f32_e32 vcc, s93, v14
	s_nop 1
	v_cndmask_b32_e64 v16, 0, 32, vcc
	v_ldexp_f32 v14, v14, v16
	v_log_f32_e32 v14, v14
	s_nop 0
	v_mul_f32_e32 v16, 0x3f317217, v14
	v_fma_f32 v16, v14, s94, -v16
	v_fmac_f32_e32 v16, 0x3377d1cf, v14
	v_fmac_f32_e32 v16, 0x3f317217, v14
	v_cmp_lt_f32_e64 s[2:3], |v14|, s95
	s_nop 1
	v_cndmask_b32_e64 v14, v14, v16, s[2:3]
	v_cndmask_b32_e32 v16, 0, v203, vcc
	v_sub_f32_e32 v14, v14, v16
	v_sub_f32_e32 v14, v0, v14
.LBB0_885:
	s_andn2_saveexec_b64 s[46:47], s[46:47]
	s_cbranch_execz .LBB0_888
	v_mad_i64_i32 v[16:17], s[2:3], s38, v61, 0
	v_lshl_add_u64 v[16:17], v[16:17], 2, s[36:37]
	v_mov_b32_e32 v14, v236
	s_andn2_b64 vcc, exec, s[42:43]
	s_cbranch_vccnz .LBB0_888
	s_waitcnt vmcnt(0)
	v_mul_f32_e64 v0, |v14|, s92
	v_exp_f32_e32 v0, v0
	v_max_f32_e32 v14, v14, v14
	v_min_f32_e32 v14, 0, v14
	v_add_f32_e32 v0, 1.0, v0
	v_cmp_gt_f32_e32 vcc, s93, v0
	s_nop 1
	v_cndmask_b32_e64 v16, 0, 32, vcc
	v_ldexp_f32 v0, v0, v16
	v_log_f32_e32 v0, v0
	s_nop 0
	v_mul_f32_e32 v16, 0x3f317217, v0
	v_fma_f32 v16, v0, s94, -v16
	v_fmac_f32_e32 v16, 0x3377d1cf, v0
	v_fmac_f32_e32 v16, 0x3f317217, v0
	v_cmp_lt_f32_e64 s[2:3], |v0|, s95
	s_nop 1
	v_cndmask_b32_e64 v0, v0, v16, s[2:3]
	v_cndmask_b32_e32 v16, 0, v203, vcc
	v_sub_f32_e32 v0, v0, v16
	v_sub_f32_e32 v14, v14, v0

.LBB0_889:
	s_or_b64 exec, exec, s[44:45]
	v_or_b32_e32 v63, 13, v52
	s_and_saveexec_b64 s[44:45], s[0:1]
	s_cbranch_execz .LBB0_896
	v_cmp_le_i32_e32 vcc, s64, v63
	s_and_saveexec_b64 s[2:3], vcc
	s_xor_b64 s[46:47], exec, s[2:3]
	s_cbranch_execz .LBB0_892
	v_subrev_u32_e32 v0, s64, v63
	v_lshl_add_u64 v[16:17], v[0:1], 2, s[40:41]
	v_mov_b32_e32 v0, v237
	s_waitcnt vmcnt(0)
	v_mul_f32_e64 v15, |v0|, s92
	v_exp_f32_e32 v15, v15
	v_max_f32_e32 v0, v0, v0
	v_min_f32_e32 v0, 0, v0
	v_add_f32_e32 v15, 1.0, v15
	v_cmp_gt_f32_e32 vcc, s93, v15
	s_nop 1
	v_cndmask_b32_e64 v16, 0, 32, vcc
	v_ldexp_f32 v15, v15, v16
	v_log_f32_e32 v15, v15
	s_nop 0
	v_mul_f32_e32 v16, 0x3f317217, v15
	v_fma_f32 v16, v15, s94, -v16
	v_fmac_f32_e32 v16, 0x3377d1cf, v15
	v_fmac_f32_e32 v16, 0x3f317217, v15
	v_cmp_lt_f32_e64 s[2:3], |v15|, s95
	s_nop 1
	v_cndmask_b32_e64 v15, v15, v16, s[2:3]
	v_cndmask_b32_e32 v16, 0, v203, vcc
	v_sub_f32_e32 v15, v15, v16
	v_sub_f32_e32 v15, v0, v15
.LBB0_892:
	s_andn2_saveexec_b64 s[46:47], s[46:47]
	s_cbranch_execz .LBB0_895
	v_mad_i64_i32 v[16:17], s[2:3], s38, v63, 0
	v_lshl_add_u64 v[16:17], v[16:17], 2, s[36:37]
	v_mov_b32_e32 v15, v237
	s_andn2_b64 vcc, exec, s[42:43]
	s_cbranch_vccnz .LBB0_895
	s_waitcnt vmcnt(0)
	v_mul_f32_e64 v0, |v15|, s92
	v_exp_f32_e32 v0, v0
	v_max_f32_e32 v15, v15, v15
	v_min_f32_e32 v15, 0, v15
	v_add_f32_e32 v0, 1.0, v0
	v_cmp_gt_f32_e32 vcc, s93, v0
	s_nop 1
	v_cndmask_b32_e64 v16, 0, 32, vcc
	v_ldexp_f32 v0, v0, v16
	v_log_f32_e32 v0, v0
	s_nop 0
	v_mul_f32_e32 v16, 0x3f317217, v0
	v_fma_f32 v16, v0, s94, -v16
	v_fmac_f32_e32 v16, 0x3377d1cf, v0
	v_fmac_f32_e32 v16, 0x3f317217, v0
	v_cmp_lt_f32_e64 s[2:3], |v0|, s95
	s_nop 1
	v_cndmask_b32_e64 v0, v0, v16, s[2:3]
	v_cndmask_b32_e32 v16, 0, v203, vcc
	v_sub_f32_e32 v0, v0, v16
	v_sub_f32_e32 v15, v15, v0

.LBB0_896:
	s_or_b64 exec, exec, s[44:45]
	v_or_b32_e32 v66, 14, v52
	v_mov_b32_e32 v17, 0
	v_mov_b32_e32 v16, 0
	s_and_saveexec_b64 s[44:45], s[0:1]
	s_cbranch_execz .LBB0_903
	v_cmp_le_i32_e32 vcc, s64, v66
	s_and_saveexec_b64 s[2:3], vcc
	s_xor_b64 s[46:47], exec, s[2:3]
	s_cbranch_execz .LBB0_899
	v_subrev_u32_e32 v0, s64, v66
	v_lshl_add_u64 v[18:19], v[0:1], 2, s[40:41]
	v_mov_b32_e32 v0, v238
	s_waitcnt vmcnt(0)
	v_mul_f32_e64 v16, |v0|, s92
	v_exp_f32_e32 v16, v16
	v_max_f32_e32 v0, v0, v0
	v_min_f32_e32 v0, 0, v0
	v_add_f32_e32 v16, 1.0, v16
	v_cmp_gt_f32_e32 vcc, s93, v16
	s_nop 1
	v_cndmask_b32_e64 v18, 0, 32, vcc
	v_ldexp_f32 v16, v16, v18
	v_log_f32_e32 v16, v16
	s_nop 0
	v_mul_f32_e32 v18, 0x3f317217, v16
	v_fma_f32 v18, v16, s94, -v18
	v_fmac_f32_e32 v18, 0x3377d1cf, v16
	v_fmac_f32_e32 v18, 0x3f317217, v16
	v_cmp_lt_f32_e64 s[2:3], |v16|, s95
	s_nop 1
	v_cndmask_b32_e64 v16, v16, v18, s[2:3]
	v_cndmask_b32_e32 v18, 0, v203, vcc
	v_sub_f32_e32 v16, v16, v18
	v_sub_f32_e32 v16, v0, v16
.LBB0_899:
	s_andn2_saveexec_b64 s[46:47], s[46:47]
	s_cbranch_execz .LBB0_902
	v_mad_i64_i32 v[18:19], s[2:3], s38, v66, 0
	v_lshl_add_u64 v[18:19], v[18:19], 2, s[36:37]
	v_mov_b32_e32 v16, v238
	s_andn2_b64 vcc, exec, s[42:43]
	s_cbranch_vccnz .LBB0_902
	s_waitcnt vmcnt(0)
	v_mul_f32_e64 v0, |v16|, s92
	v_exp_f32_e32 v0, v0
	v_max_f32_e32 v16, v16, v16
	v_min_f32_e32 v16, 0, v16
	v_add_f32_e32 v0, 1.0, v0
	v_cmp_gt_f32_e32 vcc, s93, v0
	s_nop 1
	v_cndmask_b32_e64 v18, 0, 32, vcc
	v_ldexp_f32 v0, v0, v18
	v_log_f32_e32 v0, v0
	s_nop 0
	v_mul_f32_e32 v18, 0x3f317217, v0
	v_fma_f32 v18, v0, s94, -v18
	v_fmac_f32_e32 v18, 0x3377d1cf, v0
	v_fmac_f32_e32 v18, 0x3f317217, v0
	v_cmp_lt_f32_e64 s[2:3], |v0|, s95
	s_nop 1
	v_cndmask_b32_e64 v0, v0, v18, s[2:3]
	v_cndmask_b32_e32 v18, 0, v203, vcc
	v_sub_f32_e32 v0, v0, v18
	v_sub_f32_e32 v16, v16, v0

.LBB0_903:
	s_or_b64 exec, exec, s[44:45]
	v_or_b32_e32 v67, 15, v52
	s_and_saveexec_b64 s[44:45], s[0:1]
	s_cbranch_execz .LBB0_910
	v_cmp_le_i32_e32 vcc, s64, v67
	s_and_saveexec_b64 s[2:3], vcc
	s_xor_b64 s[46:47], exec, s[2:3]
	s_cbranch_execz .LBB0_906
	v_subrev_u32_e32 v0, s64, v67
	v_lshl_add_u64 v[18:19], v[0:1], 2, s[40:41]
	v_mov_b32_e32 v0, v239
	s_waitcnt vmcnt(0)
	v_mul_f32_e64 v17, |v0|, s92
	v_exp_f32_e32 v17, v17
	v_max_f32_e32 v0, v0, v0
	v_min_f32_e32 v0, 0, v0
	v_add_f32_e32 v17, 1.0, v17
	v_cmp_gt_f32_e32 vcc, s93, v17
	s_nop 1
	v_cndmask_b32_e64 v18, 0, 32, vcc
	v_ldexp_f32 v17, v17, v18
	v_log_f32_e32 v17, v17
	s_nop 0
	v_mul_f32_e32 v18, 0x3f317217, v17
	v_fma_f32 v18, v17, s94, -v18
	v_fmac_f32_e32 v18, 0x3377d1cf, v17
	v_fmac_f32_e32 v18, 0x3f317217, v17
	v_cmp_lt_f32_e64 s[2:3], |v17|, s95
	s_nop 1
	v_cndmask_b32_e64 v17, v17, v18, s[2:3]
	v_cndmask_b32_e32 v18, 0, v203, vcc
	v_sub_f32_e32 v17, v17, v18
	v_sub_f32_e32 v17, v0, v17
.LBB0_906:
	s_andn2_saveexec_b64 s[40:41], s[46:47]
	s_cbranch_execz .LBB0_909
	v_mad_i64_i32 v[18:19], s[2:3], s38, v67, 0
	v_lshl_add_u64 v[18:19], v[18:19], 2, s[36:37]
	v_mov_b32_e32 v17, v239
	s_andn2_b64 vcc, exec, s[42:43]
	s_cbranch_vccnz .LBB0_909
	s_waitcnt vmcnt(0)
	v_mul_f32_e64 v0, |v17|, s92
	v_exp_f32_e32 v0, v0
	v_max_f32_e32 v17, v17, v17
	v_min_f32_e32 v17, 0, v17
	v_add_f32_e32 v0, 1.0, v0
	v_cmp_gt_f32_e32 vcc, s93, v0
	s_nop 1
	v_cndmask_b32_e64 v18, 0, 32, vcc
	v_ldexp_f32 v0, v0, v18
	v_log_f32_e32 v0, v0
	s_nop 0
	v_mul_f32_e32 v18, 0x3f317217, v0
	v_fma_f32 v18, v0, s94, -v18
	v_fmac_f32_e32 v18, 0x3377d1cf, v0
	v_fmac_f32_e32 v18, 0x3f317217, v0
	v_cmp_lt_f32_e64 s[2:3], |v0|, s95
	s_nop 1
	v_cndmask_b32_e64 v0, v0, v18, s[2:3]
	v_cndmask_b32_e32 v18, 0, v203, vcc
	v_sub_f32_e32 v0, v0, v18
	v_sub_f32_e32 v17, v17, v0

.LBB0_1136:
	v_readlane_b32 s13, v253, 5
	s_and_b32 s19, s13, 0xffffffc0
	s_lshr_b32 s13, s96, 6
	s_add_i32 s13, s13, 4
	s_lshr_b32 s18, s88, 6
	s_min_u32 s13, s13, s18
	s_mov_b64 s[2:3], -1
	s_lshl_b32 s25, s13, 6
	v_mbcnt_lo_u32_b32 v19, -1, 0
	v_mbcnt_hi_u32_b32 v19, -1, v19
	s_andn2_b64 vcc, exec, s[16:17]
	v_writelane_b32 v253, s19, 7
	v_add_u32_e32 v18, s19, v19
	s_cbranch_vccz .LBB0_1284
	v_lshlrev_b32_e32 v20, 4, v18
	s_xor_b64 s[16:17], s[4:5], -1
	v_cmp_gt_i32_e64 s[2:3], s25, v20
	v_mov_b32_e32 v14, 0
	v_mov_b32_e32 v0, 0
	s_and_saveexec_b64 s[98:99], s[2:3]
	v_mov_b32_e32 v247, 0
	v_subrev_u32_e32 v246, s22, v20
	v_mad_i64_i32 v[244:245], s[100:101], s12, v20, 0
	v_lshl_add_u64 v[242:243], v[246:247], 2, s[14:15]
	v_cmp_le_i32_e64 s[100:101], s22, v20
	v_lshl_add_u64 v[244:245], v[244:245], 2, s[10:11]
	s_nop 1
	v_cndmask_b32_e64 v242, v244, v242, s[100:101]
	v_cndmask_b32_e64 v243, v245, v243, s[100:101]
	global_load_dword v224, v[242:243], off
	v_or_b32_e32 v240, 1, v20
	v_subrev_u32_e32 v246, s22, v240
	v_mad_i64_i32 v[244:245], s[100:101], s12, v240, 0
	v_lshl_add_u64 v[242:243], v[246:247], 2, s[14:15]
	v_cmp_le_i32_e64 s[100:101], s22, v240
	v_lshl_add_u64 v[244:245], v[244:245], 2, s[10:11]
	s_nop 1
	v_cndmask_b32_e64 v242, v244, v242, s[100:101]
	v_cndmask_b32_e64 v243, v245, v243, s[100:101]
	global_load_dword v225, v[242:243], off
	v_or_b32_e32 v240, 2, v20
	v_subrev_u32_e32 v246, s22, v240
	v_mad_i64_i32 v[244:245], s[100:101], s12, v240, 0
	v_lshl_add_u64 v[242:243], v[246:247], 2, s[14:15]
	v_cmp_le_i32_e64 s[100:101], s22, v240
	v_lshl_add_u64 v[244:245], v[244:245], 2, s[10:11]
	s_nop 1
	v_cndmask_b32_e64 v242, v244, v242, s[100:101]
	v_cndmask_b32_e64 v243, v245, v243, s[100:101]
	global_load_dword v226, v[242:243], off
	v_or_b32_e32 v240, 3, v20
	v_subrev_u32_e32 v246, s22, v240
	v_mad_i64_i32 v[244:245], s[100:101], s12, v240, 0
	v_lshl_add_u64 v[242:243], v[246:247], 2, s[14:15]
	v_cmp_le_i32_e64 s[100:101], s22, v240
	v_lshl_add_u64 v[244:245], v[244:245], 2, s[10:11]
	s_nop 1
	v_cndmask_b32_e64 v242, v244, v242, s[100:101]
	v_cndmask_b32_e64 v243, v245, v243, s[100:101]
	global_load_dword v227, v[242:243], off
	v_or_b32_e32 v240, 4, v20
	v_subrev_u32_e32 v246, s22, v240
	v_mad_i64_i32 v[244:245], s[100:101], s12, v240, 0
	v_lshl_add_u64 v[242:243], v[246:247], 2, s[14:15]
	v_cmp_le_i32_e64 s[100:101], s22, v240
	v_lshl_add_u64 v[244:245], v[244:245], 2, s[10:11]
	s_nop 1
	v_cndmask_b32_e64 v242, v244, v242, s[100:101]
	v_cndmask_b32_e64 v243, v245, v243, s[100:101]
	global_load_dword v228, v[242:243], off
	v_or_b32_e32 v240, 5, v20
	v_subrev_u32_e32 v246, s22, v240
	v_mad_i64_i32 v[244:245], s[100:101], s12, v240, 0
	v_lshl_add_u64 v[242:243], v[246:247], 2, s[14:15]
	v_cmp_le_i32_e64 s[100:101], s22, v240
	v_lshl_add_u64 v[244:245], v[244:245], 2, s[10:11]
	s_nop 1
	v_cndmask_b32_e64 v242, v244, v242, s[100:101]
	v_cndmask_b32_e64 v243, v245, v243, s[100:101]
	global_load_dword v229, v[242:243], off
	v_or_b32_e32 v240, 6, v20
	v_subrev_u32_e32 v246, s22, v240
	v_mad_i64_i32 v[244:245], s[100:101], s12, v240, 0
	v_lshl_add_u64 v[242:243], v[246:247], 2, s[14:15]
	v_cmp_le_i32_e64 s[100:101], s22, v240
	v_lshl_add_u64 v[244:245], v[244:245], 2, s[10:11]
	s_nop 1
	v_cndmask_b32_e64 v242, v244, v242, s[100:101]
	v_cndmask_b32_e64 v243, v245, v243, s[100:101]
	global_load_dword v230, v[242:243], off
	v_or_b32_e32 v240, 7, v20
	v_subrev_u32_e32 v246, s22, v240
	v_mad_i64_i32 v[244:245], s[100:101], s12, v240, 0
	v_lshl_add_u64 v[242:243], v[246:247], 2, s[14:15]
	v_cmp_le_i32_e64 s[100:101], s22, v240
	v_lshl_add_u64 v[244:245], v[244:245], 2, s[10:11]
	s_nop 1
	v_cndmask_b32_e64 v242, v244, v242, s[100:101]
	v_cndmask_b32_e64 v243, v245, v243, s[100:101]
	global_load_dword v231, v[242:243], off
	v_or_b32_e32 v240, 8, v20
	v_subrev_u32_e32 v246, s22, v240
	v_mad_i64_i32 v[244:245], s[100:101], s12, v240, 0
	v_lshl_add_u64 v[242:243], v[246:247], 2, s[14:15]
	v_cmp_le_i32_e64 s[100:101], s22, v240
	v_lshl_add_u64 v[244:245], v[244:245], 2, s[10:11]
	s_nop 1
	v_cndmask_b32_e64 v242, v244, v242, s[100:101]
	v_cndmask_b32_e64 v243, v245, v243, s[100:101]
	global_load_dword v232, v[242:243], off
	v_or_b32_e32 v240, 9, v20
	v_subrev_u32_e32 v246, s22, v240
	v_mad_i64_i32 v[244:245], s[100:101], s12, v240, 0
	v_lshl_add_u64 v[242:243], v[246:247], 2, s[14:15]
	v_cmp_le_i32_e64 s[100:101], s22, v240
	v_lshl_add_u64 v[244:245], v[244:245], 2, s[10:11]
	s_nop 1
	v_cndmask_b32_e64 v242, v244, v242, s[100:101]
	v_cndmask_b32_e64 v243, v245, v243, s[100:101]
	global_load_dword v233, v[242:243], off
	v_or_b32_e32 v240, 10, v20
	v_subrev_u32_e32 v246, s22, v240
	v_mad_i64_i32 v[244:245], s[100:101], s12, v240, 0
	v_lshl_add_u64 v[242:243], v[246:247], 2, s[14:15]
	v_cmp_le_i32_e64 s[100:101], s22, v240
	v_lshl_add_u64 v[244:245], v[244:245], 2, s[10:11]
	s_nop 1
	v_cndmask_b32_e64 v242, v244, v242, s[100:101]
	v_cndmask_b32_e64 v243, v245, v243, s[100:101]
	global_load_dword v234, v[242:243], off
	v_or_b32_e32 v240, 11, v20
	v_subrev_u32_e32 v246, s22, v240
	v_mad_i64_i32 v[244:245], s[100:101], s12, v240, 0
	v_lshl_add_u64 v[242:243], v[246:247], 2, s[14:15]
	v_cmp_le_i32_e64 s[100:101], s22, v240
	v_lshl_add_u64 v[244:245], v[244:245], 2, s[10:11]
	s_nop 1
	v_cndmask_b32_e64 v242, v244, v242, s[100:101]
	v_cndmask_b32_e64 v243, v245, v243, s[100:101]
	global_load_dword v235, v[242:243], off
	v_or_b32_e32 v240, 12, v20
	v_subrev_u32_e32 v246, s22, v240
	v_mad_i64_i32 v[244:245], s[100:101], s12, v240, 0
	v_lshl_add_u64 v[242:243], v[246:247], 2, s[14:15]
	v_cmp_le_i32_e64 s[100:101], s22, v240
	v_lshl_add_u64 v[244:245], v[244:245], 2, s[10:11]
	s_nop 1
	v_cndmask_b32_e64 v242, v244, v242, s[100:101]
	v_cndmask_b32_e64 v243, v245, v243, s[100:101]
	global_load_dword v236, v[242:243], off
	v_or_b32_e32 v240, 13, v20
	v_subrev_u32_e32 v246, s22, v240
	v_mad_i64_i32 v[244:245], s[100:101], s12, v240, 0
	v_lshl_add_u64 v[242:243], v[246:247], 2, s[14:15]
	v_cmp_le_i32_e64 s[100:101], s22, v240
	v_lshl_add_u64 v[244:245], v[244:245], 2, s[10:11]
	s_nop 1
	v_cndmask_b32_e64 v242, v244, v242, s[100:101]
	v_cndmask_b32_e64 v243, v245, v243, s[100:101]
	global_load_dword v237, v[242:243], off
	v_or_b32_e32 v240, 14, v20
	v_subrev_u32_e32 v246, s22, v240
	v_mad_i64_i32 v[244:245], s[100:101], s12, v240, 0
	v_lshl_add_u64 v[242:243], v[246:247], 2, s[14:15]
	v_cmp_le_i32_e64 s[100:101], s22, v240
	v_lshl_add_u64 v[244:245], v[244:245], 2, s[10:11]
	s_nop 1
	v_cndmask_b32_e64 v242, v244, v242, s[100:101]
	v_cndmask_b32_e64 v243, v245, v243, s[100:101]
	global_load_dword v238, v[242:243], off
	v_or_b32_e32 v240, 15, v20
	v_subrev_u32_e32 v246, s22, v240
	v_mad_i64_i32 v[244:245], s[100:101], s12, v240, 0
	v_lshl_add_u64 v[242:243], v[246:247], 2, s[14:15]
	v_cmp_le_i32_e64 s[100:101], s22, v240
	v_lshl_add_u64 v[244:245], v[244:245], 2, s[10:11]
	s_nop 1
	v_cndmask_b32_e64 v242, v244, v242, s[100:101]
	v_cndmask_b32_e64 v243, v245, v243, s[100:101]
	global_load_dword v239, v[242:243], off
	s_mov_b64 exec, s[98:99]
	s_waitcnt vmcnt(0)
	s_and_saveexec_b64 s[18:19], s[2:3]
	s_cbranch_execz .LBB0_1144
	v_cmp_le_i32_e32 vcc, s22, v20
	s_and_saveexec_b64 s[4:5], vcc
	s_xor_b64 s[20:21], exec, s[4:5]
	s_cbranch_execz .LBB0_1140
	v_subrev_u32_e32 v0, s22, v20
	v_mov_b32_e32 v1, 0
	v_lshl_add_u64 v[0:1], v[0:1], 2, s[14:15]
	v_mov_b32_e32 v0, v224
	s_mov_b32 s4, 0xbfb8aa3b
	s_mov_b32 s5, 0x3f317217
	s_mov_b32 s13, 0x7f800000
	s_waitcnt vmcnt(0)
	v_mul_f32_e64 v1, |v0|, s4
	v_exp_f32_e32 v1, v1
	s_mov_b32 s4, 0x800000
	v_max_f32_e32 v0, v0, v0
	v_min_f32_e32 v0, 0, v0
	v_add_f32_e32 v1, 1.0, v1
	v_cmp_gt_f32_e32 vcc, s4, v1
	s_nop 1
	v_cndmask_b32_e64 v2, 0, 32, vcc
	v_ldexp_f32 v1, v1, v2
	v_log_f32_e32 v1, v1
	v_mov_b32_e32 v2, 0x41b17218
	v_cndmask_b32_e32 v2, 0, v2, vcc
	v_mul_f32_e32 v3, 0x3f317217, v1
	v_fma_f32 v3, v1, s5, -v3
	v_fmamk_f32 v3, v1, 0x3377d1cf, v3
	v_fmac_f32_e32 v3, 0x3f317217, v1
	v_cmp_lt_f32_e64 s[4:5], |v1|, s13
	s_nop 1
	v_cndmask_b32_e64 v1, v1, v3, s[4:5]
	v_sub_f32_e32 v1, v1, v2
	v_sub_f32_e32 v0, v0, v1
.LBB0_1140:
	s_andn2_saveexec_b64 s[20:21], s[20:21]
	s_cbranch_execz .LBB0_1143
	v_mad_i64_i32 v[0:1], s[4:5], s12, v20, 0
	v_lshl_add_u64 v[0:1], v[0:1], 2, s[10:11]
	v_mov_b32_e32 v0, v224
	s_andn2_b64 vcc, exec, s[16:17]
	s_cbranch_vccnz .LBB0_1143
	s_mov_b32 s4, 0xbfb8aa3b
	s_waitcnt vmcnt(0)
	v_mul_f32_e64 v1, |v0|, s4
	v_exp_f32_e32 v1, v1
	s_mov_b32 s4, 0x800000
	s_mov_b32 s5, 0x7f800000
	v_max_f32_e32 v0, v0, v0
	v_add_f32_e32 v1, 1.0, v1
	v_cmp_gt_f32_e32 vcc, s4, v1
	s_mov_b32 s4, 0x3f317217
	v_min_f32_e32 v0, 0, v0
	v_cndmask_b32_e64 v2, 0, 32, vcc
	v_ldexp_f32 v1, v1, v2
	v_log_f32_e32 v1, v1
	s_nop 0
	v_mul_f32_e32 v2, 0x3f317217, v1
	v_fma_f32 v2, v1, s4, -v2
	v_fmamk_f32 v2, v1, 0x3377d1cf, v2
	v_fmac_f32_e32 v2, 0x3f317217, v1
	v_cmp_lt_f32_e64 s[4:5], |v1|, s5
	s_nop 1
	v_cndmask_b32_e64 v1, v1, v2, s[4:5]
	v_mov_b32_e32 v2, 0x41b17218
	v_cndmask_b32_e32 v2, 0, v2, vcc
	v_sub_f32_e32 v1, v1, v2
	v_sub_f32_e32 v0, v0, v1

.LBB0_1144:
	s_or_b64 exec, exec, s[18:19]
	v_or_b32_e32 v21, 1, v20
	s_and_saveexec_b64 s[18:19], s[2:3]
	s_cbranch_execz .LBB0_1151
	v_cmp_le_i32_e32 vcc, s22, v21
	s_and_saveexec_b64 s[4:5], vcc
	s_xor_b64 s[20:21], exec, s[4:5]
	s_cbranch_execz .LBB0_1147
	v_subrev_u32_e32 v2, s22, v21
	v_mov_b32_e32 v3, 0
	v_lshl_add_u64 v[2:3], v[2:3], 2, s[14:15]
	v_mov_b32_e32 v1, v225
	s_mov_b32 s4, 0xbfb8aa3b
	s_mov_b32 s5, 0x3f317217
	s_mov_b32 s13, 0x7f800000
	s_waitcnt vmcnt(0)
	v_mul_f32_e64 v2, |v1|, s4
	v_exp_f32_e32 v2, v2
	s_mov_b32 s4, 0x800000
	v_max_f32_e32 v1, v1, v1
	v_min_f32_e32 v1, 0, v1
	v_add_f32_e32 v2, 1.0, v2
	v_cmp_gt_f32_e32 vcc, s4, v2
	s_nop 1
	v_cndmask_b32_e64 v3, 0, 32, vcc
	v_ldexp_f32 v2, v2, v3
	v_log_f32_e32 v2, v2
	v_mov_b32_e32 v3, 0x41b17218
	v_cndmask_b32_e32 v3, 0, v3, vcc
	v_mul_f32_e32 v4, 0x3f317217, v2
	v_fma_f32 v4, v2, s5, -v4
	v_fmamk_f32 v4, v2, 0x3377d1cf, v4
	v_fmac_f32_e32 v4, 0x3f317217, v2
	v_cmp_lt_f32_e64 s[4:5], |v2|, s13
	s_nop 1
	v_cndmask_b32_e64 v2, v2, v4, s[4:5]
	v_sub_f32_e32 v2, v2, v3
	v_sub_f32_e32 v14, v1, v2
.LBB0_1147:
	s_andn2_saveexec_b64 s[20:21], s[20:21]
	s_cbranch_execz .LBB0_1150
	v_mad_i64_i32 v[2:3], s[4:5], s12, v21, 0
	v_lshl_add_u64 v[2:3], v[2:3], 2, s[10:11]
	v_mov_b32_e32 v14, v225
	s_andn2_b64 vcc, exec, s[16:17]
	s_cbranch_vccnz .LBB0_1150
	s_mov_b32 s4, 0xbfb8aa3b
	s_waitcnt vmcnt(0)
	v_mul_f32_e64 v1, |v14|, s4
	v_exp_f32_e32 v1, v1
	s_mov_b32 s4, 0x800000
	s_mov_b32 s5, 0x7f800000
	v_max_f32_e32 v2, v14, v14
	v_add_f32_e32 v1, 1.0, v1
	v_cmp_gt_f32_e32 vcc, s4, v1
	s_mov_b32 s4, 0x3f317217
	v_min_f32_e32 v2, 0, v2
	v_cndmask_b32_e64 v3, 0, 32, vcc
	v_ldexp_f32 v1, v1, v3
	v_log_f32_e32 v1, v1
	s_nop 0
	v_mul_f32_e32 v3, 0x3f317217, v1
	v_fma_f32 v3, v1, s4, -v3
	v_fmamk_f32 v3, v1, 0x3377d1cf, v3
	v_fmac_f32_e32 v3, 0x3f317217, v1
	v_cmp_lt_f32_e64 s[4:5], |v1|, s5
	s_nop 1
	v_cndmask_b32_e64 v1, v1, v3, s[4:5]
	v_mov_b32_e32 v3, 0x41b17218
	v_cndmask_b32_e32 v3, 0, v3, vcc
	v_sub_f32_e32 v1, v1, v3
	v_sub_f32_e32 v14, v2, v1

.LBB0_1151:
	s_or_b64 exec, exec, s[18:19]
	v_or_b32_e32 v22, 2, v20
	v_mov_b32_e32 v12, 0
	v_mov_b32_e32 v15, 0
	s_and_saveexec_b64 s[18:19], s[2:3]
	s_cbranch_execz .LBB0_1158
	v_cmp_le_i32_e32 vcc, s22, v22
	s_and_saveexec_b64 s[4:5], vcc
	s_xor_b64 s[20:21], exec, s[4:5]
	s_cbranch_execz .LBB0_1154
	v_subrev_u32_e32 v2, s22, v22
	v_mov_b32_e32 v3, 0
	v_lshl_add_u64 v[2:3], v[2:3], 2, s[14:15]
	v_mov_b32_e32 v1, v226
	s_mov_b32 s4, 0xbfb8aa3b
	s_mov_b32 s5, 0x3f317217
	s_mov_b32 s13, 0x7f800000
	s_waitcnt vmcnt(0)
	v_mul_f32_e64 v2, |v1|, s4
	v_exp_f32_e32 v2, v2
	s_mov_b32 s4, 0x800000
	v_max_f32_e32 v1, v1, v1
	v_min_f32_e32 v1, 0, v1
	v_add_f32_e32 v2, 1.0, v2
	v_cmp_gt_f32_e32 vcc, s4, v2
	s_nop 1
	v_cndmask_b32_e64 v3, 0, 32, vcc
	v_ldexp_f32 v2, v2, v3
	v_log_f32_e32 v2, v2
	v_mov_b32_e32 v3, 0x41b17218
	v_cndmask_b32_e32 v3, 0, v3, vcc
	v_mul_f32_e32 v4, 0x3f317217, v2
	v_fma_f32 v4, v2, s5, -v4
	v_fmamk_f32 v4, v2, 0x3377d1cf, v4
	v_fmac_f32_e32 v4, 0x3f317217, v2
	v_cmp_lt_f32_e64 s[4:5], |v2|, s13
	s_nop 1
	v_cndmask_b32_e64 v2, v2, v4, s[4:5]
	v_sub_f32_e32 v2, v2, v3
	v_sub_f32_e32 v15, v1, v2
.LBB0_1154:
	s_andn2_saveexec_b64 s[20:21], s[20:21]
	s_cbranch_execz .LBB0_1157
	v_mad_i64_i32 v[2:3], s[4:5], s12, v22, 0
	v_lshl_add_u64 v[2:3], v[2:3], 2, s[10:11]
	v_mov_b32_e32 v15, v226
	s_andn2_b64 vcc, exec, s[16:17]
	s_cbranch_vccnz .LBB0_1157
	s_mov_b32 s4, 0xbfb8aa3b
	s_waitcnt vmcnt(0)
	v_mul_f32_e64 v1, |v15|, s4
	v_exp_f32_e32 v1, v1
	s_mov_b32 s4, 0x800000
	s_mov_b32 s5, 0x7f800000
	v_max_f32_e32 v2, v15, v15
	v_add_f32_e32 v1, 1.0, v1
	v_cmp_gt_f32_e32 vcc, s4, v1
	s_mov_b32 s4, 0x3f317217
	v_min_f32_e32 v2, 0, v2
	v_cndmask_b32_e64 v3, 0, 32, vcc
	v_ldexp_f32 v1, v1, v3
	v_log_f32_e32 v1, v1
	s_nop 0
	v_mul_f32_e32 v3, 0x3f317217, v1
	v_fma_f32 v3, v1, s4, -v3
	v_fmamk_f32 v3, v1, 0x3377d1cf, v3
	v_fmac_f32_e32 v3, 0x3f317217, v1
	v_cmp_lt_f32_e64 s[4:5], |v1|, s5
	s_nop 1
	v_cndmask_b32_e64 v1, v1, v3, s[4:5]
	v_mov_b32_e32 v3, 0x41b17218
	v_cndmask_b32_e32 v3, 0, v3, vcc
	v_sub_f32_e32 v1, v1, v3
	v_sub_f32_e32 v15, v2, v1

.LBB0_1158:
	s_or_b64 exec, exec, s[18:19]
	v_or_b32_e32 v23, 3, v20
	s_and_saveexec_b64 s[18:19], s[2:3]
	s_cbranch_execz .LBB0_1165
	v_cmp_le_i32_e32 vcc, s22, v23
	s_and_saveexec_b64 s[4:5], vcc
	s_xor_b64 s[20:21], exec, s[4:5]
	s_cbranch_execz .LBB0_1161
	v_subrev_u32_e32 v2, s22, v23
	v_mov_b32_e32 v3, 0
	v_lshl_add_u64 v[2:3], v[2:3], 2, s[14:15]
	v_mov_b32_e32 v1, v227
	s_mov_b32 s4, 0xbfb8aa3b
	s_mov_b32 s5, 0x3f317217
	s_mov_b32 s13, 0x7f800000
	s_waitcnt vmcnt(0)
	v_mul_f32_e64 v2, |v1|, s4
	v_exp_f32_e32 v2, v2
	s_mov_b32 s4, 0x800000
	v_max_f32_e32 v1, v1, v1
	v_min_f32_e32 v1, 0, v1
	v_add_f32_e32 v2, 1.0, v2
	v_cmp_gt_f32_e32 vcc, s4, v2
	s_nop 1
	v_cndmask_b32_e64 v3, 0, 32, vcc
	v_ldexp_f32 v2, v2, v3
	v_log_f32_e32 v2, v2
	v_mov_b32_e32 v3, 0x41b17218
	v_cndmask_b32_e32 v3, 0, v3, vcc
	v_mul_f32_e32 v4, 0x3f317217, v2
	v_fma_f32 v4, v2, s5, -v4
	v_fmamk_f32 v4, v2, 0x3377d1cf, v4
	v_fmac_f32_e32 v4, 0x3f317217, v2
	v_cmp_lt_f32_e64 s[4:5], |v2|, s13
	s_nop 1
	v_cndmask_b32_e64 v2, v2, v4, s[4:5]
	v_sub_f32_e32 v2, v2, v3
	v_sub_f32_e32 v12, v1, v2
.LBB0_1161:
	s_andn2_saveexec_b64 s[20:21], s[20:21]
	s_cbranch_execz .LBB0_1164
	v_mad_i64_i32 v[2:3], s[4:5], s12, v23, 0
	v_lshl_add_u64 v[2:3], v[2:3], 2, s[10:11]
	v_mov_b32_e32 v12, v227
	s_andn2_b64 vcc, exec, s[16:17]
	s_cbranch_vccnz .LBB0_1164
	s_mov_b32 s4, 0xbfb8aa3b
	s_waitcnt vmcnt(0)
	v_mul_f32_e64 v1, |v12|, s4
	v_exp_f32_e32 v1, v1
	s_mov_b32 s4, 0x800000
	s_mov_b32 s5, 0x7f800000
	v_max_f32_e32 v2, v12, v12
	v_add_f32_e32 v1, 1.0, v1
	v_cmp_gt_f32_e32 vcc, s4, v1
	s_mov_b32 s4, 0x3f317217
	v_min_f32_e32 v2, 0, v2
	v_cndmask_b32_e64 v3, 0, 32, vcc
	v_ldexp_f32 v1, v1, v3
	v_log_f32_e32 v1, v1
	s_nop 0
	v_mul_f32_e32 v3, 0x3f317217, v1
	v_fma_f32 v3, v1, s4, -v3
	v_fmamk_f32 v3, v1, 0x3377d1cf, v3
	v_fmac_f32_e32 v3, 0x3f317217, v1
	v_cmp_lt_f32_e64 s[4:5], |v1|, s5
	s_nop 1
	v_cndmask_b32_e64 v1, v1, v3, s[4:5]
	v_mov_b32_e32 v3, 0x41b17218
	v_cndmask_b32_e32 v3, 0, v3, vcc
	v_sub_f32_e32 v1, v1, v3
	v_sub_f32_e32 v12, v2, v1

.LBB0_1165:
	s_or_b64 exec, exec, s[18:19]
	v_or_b32_e32 v24, 4, v20
	v_mov_b32_e32 v10, 0
	v_mov_b32_e32 v13, 0
	s_and_saveexec_b64 s[18:19], s[2:3]
	s_cbranch_execz .LBB0_1172
	v_cmp_le_i32_e32 vcc, s22, v24
	s_and_saveexec_b64 s[4:5], vcc
	s_xor_b64 s[20:21], exec, s[4:5]
	s_cbranch_execz .LBB0_1168
	v_subrev_u32_e32 v2, s22, v24
	v_mov_b32_e32 v3, 0
	v_lshl_add_u64 v[2:3], v[2:3], 2, s[14:15]
	v_mov_b32_e32 v1, v228
	s_mov_b32 s4, 0xbfb8aa3b
	s_mov_b32 s5, 0x3f317217
	s_mov_b32 s13, 0x7f800000
	s_waitcnt vmcnt(0)
	v_mul_f32_e64 v2, |v1|, s4
	v_exp_f32_e32 v2, v2
	s_mov_b32 s4, 0x800000
	v_max_f32_e32 v1, v1, v1
	v_min_f32_e32 v1, 0, v1
	v_add_f32_e32 v2, 1.0, v2
	v_cmp_gt_f32_e32 vcc, s4, v2
	s_nop 1
	v_cndmask_b32_e64 v3, 0, 32, vcc
	v_ldexp_f32 v2, v2, v3
	v_log_f32_e32 v2, v2
	v_mov_b32_e32 v3, 0x41b17218
	v_cndmask_b32_e32 v3, 0, v3, vcc
	v_mul_f32_e32 v4, 0x3f317217, v2
	v_fma_f32 v4, v2, s5, -v4
	v_fmamk_f32 v4, v2, 0x3377d1cf, v4
	v_fmac_f32_e32 v4, 0x3f317217, v2
	v_cmp_lt_f32_e64 s[4:5], |v2|, s13
	s_nop 1
	v_cndmask_b32_e64 v2, v2, v4, s[4:5]
	v_sub_f32_e32 v2, v2, v3
	v_sub_f32_e32 v13, v1, v2
.LBB0_1168:
	s_andn2_saveexec_b64 s[20:21], s[20:21]
	s_cbranch_execz .LBB0_1171
	v_mad_i64_i32 v[2:3], s[4:5], s12, v24, 0
	v_lshl_add_u64 v[2:3], v[2:3], 2, s[10:11]
	v_mov_b32_e32 v13, v228
	s_andn2_b64 vcc, exec, s[16:17]
	s_cbranch_vccnz .LBB0_1171
	s_mov_b32 s4, 0xbfb8aa3b
	s_waitcnt vmcnt(0)
	v_mul_f32_e64 v1, |v13|, s4
	v_exp_f32_e32 v1, v1
	s_mov_b32 s4, 0x800000
	s_mov_b32 s5, 0x7f800000
	v_max_f32_e32 v2, v13, v13
	v_add_f32_e32 v1, 1.0, v1
	v_cmp_gt_f32_e32 vcc, s4, v1
	s_mov_b32 s4, 0x3f317217
	v_min_f32_e32 v2, 0, v2
	v_cndmask_b32_e64 v3, 0, 32, vcc
	v_ldexp_f32 v1, v1, v3
	v_log_f32_e32 v1, v1
	s_nop 0
	v_mul_f32_e32 v3, 0x3f317217, v1
	v_fma_f32 v3, v1, s4, -v3
	v_fmamk_f32 v3, v1, 0x3377d1cf, v3
	v_fmac_f32_e32 v3, 0x3f317217, v1
	v_cmp_lt_f32_e64 s[4:5], |v1|, s5
	s_nop 1
	v_cndmask_b32_e64 v1, v1, v3, s[4:5]
	v_mov_b32_e32 v3, 0x41b17218
	v_cndmask_b32_e32 v3, 0, v3, vcc
	v_sub_f32_e32 v1, v1, v3
	v_sub_f32_e32 v13, v2, v1

.LBB0_1172:
	s_or_b64 exec, exec, s[18:19]
	v_or_b32_e32 v25, 5, v20
	s_and_saveexec_b64 s[18:19], s[2:3]
	s_cbranch_execz .LBB0_1179
	v_cmp_le_i32_e32 vcc, s22, v25
	s_and_saveexec_b64 s[4:5], vcc
	s_xor_b64 s[20:21], exec, s[4:5]
	s_cbranch_execz .LBB0_1175
	v_subrev_u32_e32 v2, s22, v25
	v_mov_b32_e32 v3, 0
	v_lshl_add_u64 v[2:3], v[2:3], 2, s[14:15]
	v_mov_b32_e32 v1, v229
	s_mov_b32 s4, 0xbfb8aa3b
	s_mov_b32 s5, 0x3f317217
	s_mov_b32 s13, 0x7f800000
	s_waitcnt vmcnt(0)
	v_mul_f32_e64 v2, |v1|, s4
	v_exp_f32_e32 v2, v2
	s_mov_b32 s4, 0x800000
	v_max_f32_e32 v1, v1, v1
	v_min_f32_e32 v1, 0, v1
	v_add_f32_e32 v2, 1.0, v2
	v_cmp_gt_f32_e32 vcc, s4, v2
	s_nop 1
	v_cndmask_b32_e64 v3, 0, 32, vcc
	v_ldexp_f32 v2, v2, v3
	v_log_f32_e32 v2, v2
	v_mov_b32_e32 v3, 0x41b17218
	v_cndmask_b32_e32 v3, 0, v3, vcc
	v_mul_f32_e32 v4, 0x3f317217, v2
	v_fma_f32 v4, v2, s5, -v4
	v_fmamk_f32 v4, v2, 0x3377d1cf, v4
	v_fmac_f32_e32 v4, 0x3f317217, v2
	v_cmp_lt_f32_e64 s[4:5], |v2|, s13
	s_nop 1
	v_cndmask_b32_e64 v2, v2, v4, s[4:5]
	v_sub_f32_e32 v2, v2, v3
	v_sub_f32_e32 v10, v1, v2
.LBB0_1175:
	s_andn2_saveexec_b64 s[20:21], s[20:21]
	s_cbranch_execz .LBB0_1178
	v_mad_i64_i32 v[2:3], s[4:5], s12, v25, 0
	v_lshl_add_u64 v[2:3], v[2:3], 2, s[10:11]
	v_mov_b32_e32 v10, v229
	s_andn2_b64 vcc, exec, s[16:17]
	s_cbranch_vccnz .LBB0_1178
	s_mov_b32 s4, 0xbfb8aa3b
	s_waitcnt vmcnt(0)
	v_mul_f32_e64 v1, |v10|, s4
	v_exp_f32_e32 v1, v1
	s_mov_b32 s4, 0x800000
	s_mov_b32 s5, 0x7f800000
	v_max_f32_e32 v2, v10, v10
	v_add_f32_e32 v1, 1.0, v1
	v_cmp_gt_f32_e32 vcc, s4, v1
	s_mov_b32 s4, 0x3f317217
	v_min_f32_e32 v2, 0, v2
	v_cndmask_b32_e64 v3, 0, 32, vcc
	v_ldexp_f32 v1, v1, v3
	v_log_f32_e32 v1, v1
	s_nop 0
	v_mul_f32_e32 v3, 0x3f317217, v1
	v_fma_f32 v3, v1, s4, -v3
	v_fmamk_f32 v3, v1, 0x3377d1cf, v3
	v_fmac_f32_e32 v3, 0x3f317217, v1
	v_cmp_lt_f32_e64 s[4:5], |v1|, s5
	s_nop 1
	v_cndmask_b32_e64 v1, v1, v3, s[4:5]
	v_mov_b32_e32 v3, 0x41b17218
	v_cndmask_b32_e32 v3, 0, v3, vcc
	v_sub_f32_e32 v1, v1, v3
	v_sub_f32_e32 v10, v2, v1

.LBB0_1179:
	s_or_b64 exec, exec, s[18:19]
	v_or_b32_e32 v26, 6, v20
	v_mov_b32_e32 v8, 0
	v_mov_b32_e32 v11, 0
	s_and_saveexec_b64 s[18:19], s[2:3]
	s_cbranch_execz .LBB0_1186
	v_cmp_le_i32_e32 vcc, s22, v26
	s_and_saveexec_b64 s[4:5], vcc
	s_xor_b64 s[20:21], exec, s[4:5]
	s_cbranch_execz .LBB0_1182
	v_subrev_u32_e32 v2, s22, v26
	v_mov_b32_e32 v3, 0
	v_lshl_add_u64 v[2:3], v[2:3], 2, s[14:15]
	v_mov_b32_e32 v1, v230
	s_mov_b32 s4, 0xbfb8aa3b
	s_mov_b32 s5, 0x3f317217
	s_mov_b32 s13, 0x7f800000
	s_waitcnt vmcnt(0)
	v_mul_f32_e64 v2, |v1|, s4
	v_exp_f32_e32 v2, v2
	s_mov_b32 s4, 0x800000
	v_max_f32_e32 v1, v1, v1
	v_min_f32_e32 v1, 0, v1
	v_add_f32_e32 v2, 1.0, v2
	v_cmp_gt_f32_e32 vcc, s4, v2
	s_nop 1
	v_cndmask_b32_e64 v3, 0, 32, vcc
	v_ldexp_f32 v2, v2, v3
	v_log_f32_e32 v2, v2
	v_mov_b32_e32 v3, 0x41b17218
	v_cndmask_b32_e32 v3, 0, v3, vcc
	v_mul_f32_e32 v4, 0x3f317217, v2
	v_fma_f32 v4, v2, s5, -v4
	v_fmamk_f32 v4, v2, 0x3377d1cf, v4
	v_fmac_f32_e32 v4, 0x3f317217, v2
	v_cmp_lt_f32_e64 s[4:5], |v2|, s13
	s_nop 1
	v_cndmask_b32_e64 v2, v2, v4, s[4:5]
	v_sub_f32_e32 v2, v2, v3
	v_sub_f32_e32 v11, v1, v2
.LBB0_1182:
	s_andn2_saveexec_b64 s[20:21], s[20:21]
	s_cbranch_execz .LBB0_1185
	v_mad_i64_i32 v[2:3], s[4:5], s12, v26, 0
	v_lshl_add_u64 v[2:3], v[2:3], 2, s[10:11]
	v_mov_b32_e32 v11, v230
	s_andn2_b64 vcc, exec, s[16:17]
	s_cbranch_vccnz .LBB0_1185
	s_mov_b32 s4, 0xbfb8aa3b
	s_waitcnt vmcnt(0)
	v_mul_f32_e64 v1, |v11|, s4
	v_exp_f32_e32 v1, v1
	s_mov_b32 s4, 0x800000
	s_mov_b32 s5, 0x7f800000
	v_max_f32_e32 v2, v11, v11
	v_add_f32_e32 v1, 1.0, v1
	v_cmp_gt_f32_e32 vcc, s4, v1
	s_mov_b32 s4, 0x3f317217
	v_min_f32_e32 v2, 0, v2
	v_cndmask_b32_e64 v3, 0, 32, vcc
	v_ldexp_f32 v1, v1, v3
	v_log_f32_e32 v1, v1
	s_nop 0
	v_mul_f32_e32 v3, 0x3f317217, v1
	v_fma_f32 v3, v1, s4, -v3
	v_fmamk_f32 v3, v1, 0x3377d1cf, v3
	v_fmac_f32_e32 v3, 0x3f317217, v1
	v_cmp_lt_f32_e64 s[4:5], |v1|, s5
	s_nop 1
	v_cndmask_b32_e64 v1, v1, v3, s[4:5]
	v_mov_b32_e32 v3, 0x41b17218
	v_cndmask_b32_e32 v3, 0, v3, vcc
	v_sub_f32_e32 v1, v1, v3
	v_sub_f32_e32 v11, v2, v1

.LBB0_1186:
	s_or_b64 exec, exec, s[18:19]
	v_or_b32_e32 v27, 7, v20
	s_and_saveexec_b64 s[18:19], s[2:3]
	s_cbranch_execz .LBB0_1193
	v_cmp_le_i32_e32 vcc, s22, v27
	s_and_saveexec_b64 s[4:5], vcc
	s_xor_b64 s[20:21], exec, s[4:5]
	s_cbranch_execz .LBB0_1189
	v_subrev_u32_e32 v2, s22, v27
	v_mov_b32_e32 v3, 0
	v_lshl_add_u64 v[2:3], v[2:3], 2, s[14:15]
	v_mov_b32_e32 v1, v231
	s_mov_b32 s4, 0xbfb8aa3b
	s_mov_b32 s5, 0x3f317217
	s_mov_b32 s13, 0x7f800000
	s_waitcnt vmcnt(0)
	v_mul_f32_e64 v2, |v1|, s4
	v_exp_f32_e32 v2, v2
	s_mov_b32 s4, 0x800000
	v_max_f32_e32 v1, v1, v1
	v_min_f32_e32 v1, 0, v1
	v_add_f32_e32 v2, 1.0, v2
	v_cmp_gt_f32_e32 vcc, s4, v2
	s_nop 1
	v_cndmask_b32_e64 v3, 0, 32, vcc
	v_ldexp_f32 v2, v2, v3
	v_log_f32_e32 v2, v2
	v_mov_b32_e32 v3, 0x41b17218
	v_cndmask_b32_e32 v3, 0, v3, vcc
	v_mul_f32_e32 v4, 0x3f317217, v2
	v_fma_f32 v4, v2, s5, -v4
	v_fmamk_f32 v4, v2, 0x3377d1cf, v4
	v_fmac_f32_e32 v4, 0x3f317217, v2
	v_cmp_lt_f32_e64 s[4:5], |v2|, s13
	s_nop 1
	v_cndmask_b32_e64 v2, v2, v4, s[4:5]
	v_sub_f32_e32 v2, v2, v3
	v_sub_f32_e32 v8, v1, v2
.LBB0_1189:
	s_andn2_saveexec_b64 s[20:21], s[20:21]
	s_cbranch_execz .LBB0_1192
	v_mad_i64_i32 v[2:3], s[4:5], s12, v27, 0
	v_lshl_add_u64 v[2:3], v[2:3], 2, s[10:11]
	v_mov_b32_e32 v8, v231
	s_andn2_b64 vcc, exec, s[16:17]
	s_cbranch_vccnz .LBB0_1192
	s_mov_b32 s4, 0xbfb8aa3b
	s_waitcnt vmcnt(0)
	v_mul_f32_e64 v1, |v8|, s4
	v_exp_f32_e32 v1, v1
	s_mov_b32 s4, 0x800000
	s_mov_b32 s5, 0x7f800000
	v_max_f32_e32 v2, v8, v8
	v_add_f32_e32 v1, 1.0, v1
	v_cmp_gt_f32_e32 vcc, s4, v1
	s_mov_b32 s4, 0x3f317217
	v_min_f32_e32 v2, 0, v2
	v_cndmask_b32_e64 v3, 0, 32, vcc
	v_ldexp_f32 v1, v1, v3
	v_log_f32_e32 v1, v1
	s_nop 0
	v_mul_f32_e32 v3, 0x3f317217, v1
	v_fma_f32 v3, v1, s4, -v3
	v_fmamk_f32 v3, v1, 0x3377d1cf, v3
	v_fmac_f32_e32 v3, 0x3f317217, v1
	v_cmp_lt_f32_e64 s[4:5], |v1|, s5
	s_nop 1
	v_cndmask_b32_e64 v1, v1, v3, s[4:5]
	v_mov_b32_e32 v3, 0x41b17218
	v_cndmask_b32_e32 v3, 0, v3, vcc
	v_sub_f32_e32 v1, v1, v3
	v_sub_f32_e32 v8, v2, v1

.LBB0_1193:
	s_or_b64 exec, exec, s[18:19]
	v_or_b32_e32 v28, 8, v20
	v_mov_b32_e32 v6, 0
	v_mov_b32_e32 v9, 0
	s_and_saveexec_b64 s[18:19], s[2:3]
	s_cbranch_execz .LBB0_1200
	v_cmp_le_i32_e32 vcc, s22, v28
	s_and_saveexec_b64 s[4:5], vcc
	s_xor_b64 s[20:21], exec, s[4:5]
	s_cbranch_execz .LBB0_1196
	v_subrev_u32_e32 v2, s22, v28
	v_mov_b32_e32 v3, 0
	v_lshl_add_u64 v[2:3], v[2:3], 2, s[14:15]
	v_mov_b32_e32 v1, v232
	s_mov_b32 s4, 0xbfb8aa3b
	s_mov_b32 s5, 0x3f317217
	s_mov_b32 s13, 0x7f800000
	s_waitcnt vmcnt(0)
	v_mul_f32_e64 v2, |v1|, s4
	v_exp_f32_e32 v2, v2
	s_mov_b32 s4, 0x800000
	v_max_f32_e32 v1, v1, v1
	v_min_f32_e32 v1, 0, v1
	v_add_f32_e32 v2, 1.0, v2
	v_cmp_gt_f32_e32 vcc, s4, v2
	s_nop 1
	v_cndmask_b32_e64 v3, 0, 32, vcc
	v_ldexp_f32 v2, v2, v3
	v_log_f32_e32 v2, v2
	v_mov_b32_e32 v3, 0x41b17218
	v_cndmask_b32_e32 v3, 0, v3, vcc
	v_mul_f32_e32 v4, 0x3f317217, v2
	v_fma_f32 v4, v2, s5, -v4
	v_fmamk_f32 v4, v2, 0x3377d1cf, v4
	v_fmac_f32_e32 v4, 0x3f317217, v2
	v_cmp_lt_f32_e64 s[4:5], |v2|, s13
	s_nop 1
	v_cndmask_b32_e64 v2, v2, v4, s[4:5]
	v_sub_f32_e32 v2, v2, v3
	v_sub_f32_e32 v9, v1, v2
.LBB0_1196:
	s_andn2_saveexec_b64 s[20:21], s[20:21]
	s_cbranch_execz .LBB0_1199
	v_mad_i64_i32 v[2:3], s[4:5], s12, v28, 0
	v_lshl_add_u64 v[2:3], v[2:3], 2, s[10:11]
	v_mov_b32_e32 v9, v232
	s_andn2_b64 vcc, exec, s[16:17]
	s_cbranch_vccnz .LBB0_1199
	s_mov_b32 s4, 0xbfb8aa3b
	s_waitcnt vmcnt(0)
	v_mul_f32_e64 v1, |v9|, s4
	v_exp_f32_e32 v1, v1
	s_mov_b32 s4, 0x800000
	s_mov_b32 s5, 0x7f800000
	v_max_f32_e32 v2, v9, v9
	v_add_f32_e32 v1, 1.0, v1
	v_cmp_gt_f32_e32 vcc, s4, v1
	s_mov_b32 s4, 0x3f317217
	v_min_f32_e32 v2, 0, v2
	v_cndmask_b32_e64 v3, 0, 32, vcc
	v_ldexp_f32 v1, v1, v3
	v_log_f32_e32 v1, v1
	s_nop 0
	v_mul_f32_e32 v3, 0x3f317217, v1
	v_fma_f32 v3, v1, s4, -v3
	v_fmamk_f32 v3, v1, 0x3377d1cf, v3
	v_fmac_f32_e32 v3, 0x3f317217, v1
	v_cmp_lt_f32_e64 s[4:5], |v1|, s5
	s_nop 1
	v_cndmask_b32_e64 v1, v1, v3, s[4:5]
	v_mov_b32_e32 v3, 0x41b17218
	v_cndmask_b32_e32 v3, 0, v3, vcc
	v_sub_f32_e32 v1, v1, v3
	v_sub_f32_e32 v9, v2, v1

.LBB0_1200:
	s_or_b64 exec, exec, s[18:19]
	v_or_b32_e32 v29, 9, v20
	s_and_saveexec_b64 s[18:19], s[2:3]
	s_cbranch_execz .LBB0_1207
	v_cmp_le_i32_e32 vcc, s22, v29
	s_and_saveexec_b64 s[4:5], vcc
	s_xor_b64 s[20:21], exec, s[4:5]
	s_cbranch_execz .LBB0_1203
	v_subrev_u32_e32 v2, s22, v29
	v_mov_b32_e32 v3, 0
	v_lshl_add_u64 v[2:3], v[2:3], 2, s[14:15]
	v_mov_b32_e32 v1, v233
	s_mov_b32 s4, 0xbfb8aa3b
	s_mov_b32 s5, 0x3f317217
	s_mov_b32 s13, 0x7f800000
	s_waitcnt vmcnt(0)
	v_mul_f32_e64 v2, |v1|, s4
	v_exp_f32_e32 v2, v2
	s_mov_b32 s4, 0x800000
	v_max_f32_e32 v1, v1, v1
	v_min_f32_e32 v1, 0, v1
	v_add_f32_e32 v2, 1.0, v2
	v_cmp_gt_f32_e32 vcc, s4, v2
	s_nop 1
	v_cndmask_b32_e64 v3, 0, 32, vcc
	v_ldexp_f32 v2, v2, v3
	v_log_f32_e32 v2, v2
	v_mov_b32_e32 v3, 0x41b17218
	v_cndmask_b32_e32 v3, 0, v3, vcc
	v_mul_f32_e32 v4, 0x3f317217, v2
	v_fma_f32 v4, v2, s5, -v4
	v_fmamk_f32 v4, v2, 0x3377d1cf, v4
	v_fmac_f32_e32 v4, 0x3f317217, v2
	v_cmp_lt_f32_e64 s[4:5], |v2|, s13
	s_nop 1
	v_cndmask_b32_e64 v2, v2, v4, s[4:5]
	v_sub_f32_e32 v2, v2, v3
	v_sub_f32_e32 v6, v1, v2
.LBB0_1203:
	s_andn2_saveexec_b64 s[20:21], s[20:21]
	s_cbranch_execz .LBB0_1206
	v_mad_i64_i32 v[2:3], s[4:5], s12, v29, 0
	v_lshl_add_u64 v[2:3], v[2:3], 2, s[10:11]
	v_mov_b32_e32 v6, v233
	s_andn2_b64 vcc, exec, s[16:17]
	s_cbranch_vccnz .LBB0_1206
	s_mov_b32 s4, 0xbfb8aa3b
	s_waitcnt vmcnt(0)
	v_mul_f32_e64 v1, |v6|, s4
	v_exp_f32_e32 v1, v1
	s_mov_b32 s4, 0x800000
	s_mov_b32 s5, 0x7f800000
	v_max_f32_e32 v2, v6, v6
	v_add_f32_e32 v1, 1.0, v1
	v_cmp_gt_f32_e32 vcc, s4, v1
	s_mov_b32 s4, 0x3f317217
	v_min_f32_e32 v2, 0, v2
	v_cndmask_b32_e64 v3, 0, 32, vcc
	v_ldexp_f32 v1, v1, v3
	v_log_f32_e32 v1, v1
	s_nop 0
	v_mul_f32_e32 v3, 0x3f317217, v1
	v_fma_f32 v3, v1, s4, -v3
	v_fmamk_f32 v3, v1, 0x3377d1cf, v3
	v_fmac_f32_e32 v3, 0x3f317217, v1
	v_cmp_lt_f32_e64 s[4:5], |v1|, s5
	s_nop 1
	v_cndmask_b32_e64 v1, v1, v3, s[4:5]
	v_mov_b32_e32 v3, 0x41b17218
	v_cndmask_b32_e32 v3, 0, v3, vcc
	v_sub_f32_e32 v1, v1, v3
	v_sub_f32_e32 v6, v2, v1

.LBB0_1207:
	s_or_b64 exec, exec, s[18:19]
	v_or_b32_e32 v30, 10, v20
	v_mov_b32_e32 v4, 0
	v_mov_b32_e32 v7, 0
	s_and_saveexec_b64 s[18:19], s[2:3]
	s_cbranch_execz .LBB0_1214
	v_cmp_le_i32_e32 vcc, s22, v30
	s_and_saveexec_b64 s[4:5], vcc
	s_xor_b64 s[20:21], exec, s[4:5]
	s_cbranch_execz .LBB0_1210
	v_subrev_u32_e32 v2, s22, v30
	v_mov_b32_e32 v3, 0
	v_lshl_add_u64 v[2:3], v[2:3], 2, s[14:15]
	v_mov_b32_e32 v1, v234
	s_mov_b32 s4, 0xbfb8aa3b
	s_mov_b32 s5, 0x3f317217
	s_mov_b32 s13, 0x7f800000
	s_waitcnt vmcnt(0)
	v_mul_f32_e64 v2, |v1|, s4
	v_exp_f32_e32 v2, v2
	s_mov_b32 s4, 0x800000
	v_max_f32_e32 v1, v1, v1
	v_min_f32_e32 v1, 0, v1
	v_add_f32_e32 v2, 1.0, v2
	v_cmp_gt_f32_e32 vcc, s4, v2
	s_nop 1
	v_cndmask_b32_e64 v3, 0, 32, vcc
	v_ldexp_f32 v2, v2, v3
	v_log_f32_e32 v2, v2
	v_mov_b32_e32 v3, 0x41b17218
	v_cndmask_b32_e32 v3, 0, v3, vcc
	v_mul_f32_e32 v5, 0x3f317217, v2
	v_fma_f32 v5, v2, s5, -v5
	v_fmamk_f32 v5, v2, 0x3377d1cf, v5
	v_fmac_f32_e32 v5, 0x3f317217, v2
	v_cmp_lt_f32_e64 s[4:5], |v2|, s13
	s_nop 1
	v_cndmask_b32_e64 v2, v2, v5, s[4:5]
	v_sub_f32_e32 v2, v2, v3
	v_sub_f32_e32 v7, v1, v2
.LBB0_1210:
	s_andn2_saveexec_b64 s[20:21], s[20:21]
	s_cbranch_execz .LBB0_1213
	v_mad_i64_i32 v[2:3], s[4:5], s12, v30, 0
	v_lshl_add_u64 v[2:3], v[2:3], 2, s[10:11]
	v_mov_b32_e32 v7, v234
	s_andn2_b64 vcc, exec, s[16:17]
	s_cbranch_vccnz .LBB0_1213
	s_mov_b32 s4, 0xbfb8aa3b
	s_waitcnt vmcnt(0)
	v_mul_f32_e64 v1, |v7|, s4
	v_exp_f32_e32 v1, v1
	s_mov_b32 s4, 0x800000
	s_mov_b32 s5, 0x7f800000
	v_max_f32_e32 v2, v7, v7
	v_add_f32_e32 v1, 1.0, v1
	v_cmp_gt_f32_e32 vcc, s4, v1
	s_mov_b32 s4, 0x3f317217
	v_min_f32_e32 v2, 0, v2
	v_cndmask_b32_e64 v3, 0, 32, vcc
	v_ldexp_f32 v1, v1, v3
	v_log_f32_e32 v1, v1
	s_nop 0
	v_mul_f32_e32 v3, 0x3f317217, v1
	v_fma_f32 v3, v1, s4, -v3
	v_fmamk_f32 v3, v1, 0x3377d1cf, v3
	v_fmac_f32_e32 v3, 0x3f317217, v1
	v_cmp_lt_f32_e64 s[4:5], |v1|, s5
	s_nop 1
	v_cndmask_b32_e64 v1, v1, v3, s[4:5]
	v_mov_b32_e32 v3, 0x41b17218
	v_cndmask_b32_e32 v3, 0, v3, vcc
	v_sub_f32_e32 v1, v1, v3
	v_sub_f32_e32 v7, v2, v1

.LBB0_1214:
	s_or_b64 exec, exec, s[18:19]
	v_or_b32_e32 v31, 11, v20
	s_and_saveexec_b64 s[18:19], s[2:3]
	s_cbranch_execz .LBB0_1221
	v_cmp_le_i32_e32 vcc, s22, v31
	s_and_saveexec_b64 s[4:5], vcc
	s_xor_b64 s[20:21], exec, s[4:5]
	s_cbranch_execz .LBB0_1217
	v_subrev_u32_e32 v2, s22, v31
	v_mov_b32_e32 v3, 0
	v_lshl_add_u64 v[2:3], v[2:3], 2, s[14:15]
	v_mov_b32_e32 v1, v235
	s_mov_b32 s4, 0xbfb8aa3b
	s_mov_b32 s5, 0x3f317217
	s_mov_b32 s13, 0x7f800000
	s_waitcnt vmcnt(0)
	v_mul_f32_e64 v2, |v1|, s4
	v_exp_f32_e32 v2, v2
	s_mov_b32 s4, 0x800000
	v_max_f32_e32 v1, v1, v1
	v_min_f32_e32 v1, 0, v1
	v_add_f32_e32 v2, 1.0, v2
	v_cmp_gt_f32_e32 vcc, s4, v2
	s_nop 1
	v_cndmask_b32_e64 v3, 0, 32, vcc
	v_ldexp_f32 v2, v2, v3
	v_log_f32_e32 v2, v2
	v_mov_b32_e32 v3, 0x41b17218
	v_cndmask_b32_e32 v3, 0, v3, vcc
	v_mul_f32_e32 v4, 0x3f317217, v2
	v_fma_f32 v4, v2, s5, -v4
	v_fmamk_f32 v4, v2, 0x3377d1cf, v4
	v_fmac_f32_e32 v4, 0x3f317217, v2
	v_cmp_lt_f32_e64 s[4:5], |v2|, s13
	s_nop 1
	v_cndmask_b32_e64 v2, v2, v4, s[4:5]
	v_sub_f32_e32 v2, v2, v3
	v_sub_f32_e32 v4, v1, v2
.LBB0_1217:
	s_andn2_saveexec_b64 s[20:21], s[20:21]
	s_cbranch_execz .LBB0_1220
	v_mad_i64_i32 v[2:3], s[4:5], s12, v31, 0
	v_lshl_add_u64 v[2:3], v[2:3], 2, s[10:11]
	v_mov_b32_e32 v4, v235
	s_andn2_b64 vcc, exec, s[16:17]
	s_cbranch_vccnz .LBB0_1220
	s_mov_b32 s4, 0xbfb8aa3b
	s_waitcnt vmcnt(0)
	v_mul_f32_e64 v1, |v4|, s4
	v_exp_f32_e32 v1, v1
	s_mov_b32 s4, 0x800000
	s_mov_b32 s5, 0x7f800000
	v_max_f32_e32 v2, v4, v4
	v_add_f32_e32 v1, 1.0, v1
	v_cmp_gt_f32_e32 vcc, s4, v1
	s_mov_b32 s4, 0x3f317217
	v_min_f32_e32 v2, 0, v2
	v_cndmask_b32_e64 v3, 0, 32, vcc
	v_ldexp_f32 v1, v1, v3
	v_log_f32_e32 v1, v1
	s_nop 0
	v_mul_f32_e32 v3, 0x3f317217, v1
	v_fma_f32 v3, v1, s4, -v3
	v_fmamk_f32 v3, v1, 0x3377d1cf, v3
	v_fmac_f32_e32 v3, 0x3f317217, v1
	v_cmp_lt_f32_e64 s[4:5], |v1|, s5
	s_nop 1
	v_cndmask_b32_e64 v1, v1, v3, s[4:5]
	v_mov_b32_e32 v3, 0x41b17218
	v_cndmask_b32_e32 v3, 0, v3, vcc
	v_sub_f32_e32 v1, v1, v3
	v_sub_f32_e32 v4, v2, v1

.LBB0_1221:
	s_or_b64 exec, exec, s[18:19]
	v_or_b32_e32 v32, 12, v20
	v_mov_b32_e32 v2, 0
	v_mov_b32_e32 v5, 0
	s_and_saveexec_b64 s[18:19], s[2:3]
	s_cbranch_execz .LBB0_1228
	v_cmp_le_i32_e32 vcc, s22, v32
	s_and_saveexec_b64 s[4:5], vcc
	s_xor_b64 s[20:21], exec, s[4:5]
	s_cbranch_execz .LBB0_1224
	v_subrev_u32_e32 v16, s22, v32
	v_mov_b32_e32 v17, 0
	v_lshl_add_u64 v[16:17], v[16:17], 2, s[14:15]
	v_mov_b32_e32 v1, v236
	s_mov_b32 s4, 0xbfb8aa3b
	s_mov_b32 s5, 0x3f317217
	s_mov_b32 s13, 0x7f800000
	s_waitcnt vmcnt(0)
	v_mul_f32_e64 v3, |v1|, s4
	v_exp_f32_e32 v3, v3
	s_mov_b32 s4, 0x800000
	v_max_f32_e32 v1, v1, v1
	v_min_f32_e32 v1, 0, v1
	v_add_f32_e32 v3, 1.0, v3
	v_cmp_gt_f32_e32 vcc, s4, v3
	s_nop 1
	v_cndmask_b32_e64 v5, 0, 32, vcc
	v_ldexp_f32 v3, v3, v5
	v_log_f32_e32 v3, v3
	v_mov_b32_e32 v5, 0x41b17218
	v_cndmask_b32_e32 v5, 0, v5, vcc
	v_mul_f32_e32 v16, 0x3f317217, v3
	v_fma_f32 v16, v3, s5, -v16
	v_fmamk_f32 v16, v3, 0x3377d1cf, v16
	v_fmac_f32_e32 v16, 0x3f317217, v3
	v_cmp_lt_f32_e64 s[4:5], |v3|, s13
	s_nop 1
	v_cndmask_b32_e64 v3, v3, v16, s[4:5]
	v_sub_f32_e32 v3, v3, v5
	v_sub_f32_e32 v5, v1, v3
.LBB0_1224:
	s_andn2_saveexec_b64 s[20:21], s[20:21]
	s_cbranch_execz .LBB0_1227
	v_mad_i64_i32 v[16:17], s[4:5], s12, v32, 0
	v_lshl_add_u64 v[16:17], v[16:17], 2, s[10:11]
	v_mov_b32_e32 v5, v236
	s_andn2_b64 vcc, exec, s[16:17]
	s_cbranch_vccnz .LBB0_1227
	s_mov_b32 s4, 0xbfb8aa3b
	s_waitcnt vmcnt(0)
	v_mul_f32_e64 v1, |v5|, s4
	v_exp_f32_e32 v1, v1
	s_mov_b32 s4, 0x800000
	v_max_f32_e32 v3, v5, v5
	s_mov_b32 s5, 0x7f800000
	v_add_f32_e32 v1, 1.0, v1
	v_cmp_gt_f32_e32 vcc, s4, v1
	s_mov_b32 s4, 0x3f317217
	v_min_f32_e32 v3, 0, v3
	v_cndmask_b32_e64 v5, 0, 32, vcc
	v_ldexp_f32 v1, v1, v5
	v_log_f32_e32 v1, v1
	s_nop 0
	v_mul_f32_e32 v5, 0x3f317217, v1
	v_fma_f32 v5, v1, s4, -v5
	v_fmamk_f32 v5, v1, 0x3377d1cf, v5
	v_fmac_f32_e32 v5, 0x3f317217, v1
	v_cmp_lt_f32_e64 s[4:5], |v1|, s5
	s_nop 1
	v_cndmask_b32_e64 v1, v1, v5, s[4:5]
	v_mov_b32_e32 v5, 0x41b17218
	v_cndmask_b32_e32 v5, 0, v5, vcc
	v_sub_f32_e32 v1, v1, v5
	v_sub_f32_e32 v5, v3, v1

.LBB0_1228:
	s_or_b64 exec, exec, s[18:19]
	v_or_b32_e32 v33, 13, v20
	s_and_saveexec_b64 s[18:19], s[2:3]
	s_cbranch_execz .LBB0_1235
	v_cmp_le_i32_e32 vcc, s22, v33
	s_and_saveexec_b64 s[4:5], vcc
	s_xor_b64 s[20:21], exec, s[4:5]
	s_cbranch_execz .LBB0_1231
	v_subrev_u32_e32 v2, s22, v33
	v_mov_b32_e32 v3, 0
	v_lshl_add_u64 v[2:3], v[2:3], 2, s[14:15]
	v_mov_b32_e32 v1, v237
	s_mov_b32 s4, 0xbfb8aa3b
	s_mov_b32 s5, 0x3f317217
	s_mov_b32 s13, 0x7f800000
	s_waitcnt vmcnt(0)
	v_mul_f32_e64 v2, |v1|, s4
	v_exp_f32_e32 v2, v2
	s_mov_b32 s4, 0x800000
	v_max_f32_e32 v1, v1, v1
	v_min_f32_e32 v1, 0, v1
	v_add_f32_e32 v2, 1.0, v2
	v_cmp_gt_f32_e32 vcc, s4, v2
	s_nop 1
	v_cndmask_b32_e64 v3, 0, 32, vcc
	v_ldexp_f32 v2, v2, v3
	v_log_f32_e32 v2, v2
	v_mov_b32_e32 v3, 0x41b17218
	v_cndmask_b32_e32 v3, 0, v3, vcc
	v_mul_f32_e32 v16, 0x3f317217, v2
	v_fma_f32 v16, v2, s5, -v16
	v_fmamk_f32 v16, v2, 0x3377d1cf, v16
	v_fmac_f32_e32 v16, 0x3f317217, v2
	v_cmp_lt_f32_e64 s[4:5], |v2|, s13
	s_nop 1
	v_cndmask_b32_e64 v2, v2, v16, s[4:5]
	v_sub_f32_e32 v2, v2, v3
	v_sub_f32_e32 v2, v1, v2
.LBB0_1231:
	s_andn2_saveexec_b64 s[20:21], s[20:21]
	s_cbranch_execz .LBB0_1234
	v_mad_i64_i32 v[2:3], s[4:5], s12, v33, 0
	v_lshl_add_u64 v[2:3], v[2:3], 2, s[10:11]
	v_mov_b32_e32 v2, v237
	s_andn2_b64 vcc, exec, s[16:17]
	s_cbranch_vccnz .LBB0_1234
	s_mov_b32 s4, 0xbfb8aa3b
	s_waitcnt vmcnt(0)
	v_mul_f32_e64 v1, |v2|, s4
	v_exp_f32_e32 v1, v1
	s_mov_b32 s4, 0x800000
	s_mov_b32 s5, 0x7f800000
	v_max_f32_e32 v2, v2, v2
	v_add_f32_e32 v1, 1.0, v1
	v_cmp_gt_f32_e32 vcc, s4, v1
	s_mov_b32 s4, 0x3f317217
	v_min_f32_e32 v2, 0, v2
	v_cndmask_b32_e64 v3, 0, 32, vcc
	v_ldexp_f32 v1, v1, v3
	v_log_f32_e32 v1, v1
	s_nop 0
	v_mul_f32_e32 v3, 0x3f317217, v1
	v_fma_f32 v3, v1, s4, -v3
	v_fmamk_f32 v3, v1, 0x3377d1cf, v3
	v_fmac_f32_e32 v3, 0x3f317217, v1
	v_cmp_lt_f32_e64 s[4:5], |v1|, s5
	s_nop 1
	v_cndmask_b32_e64 v1, v1, v3, s[4:5]
	v_mov_b32_e32 v3, 0x41b17218
	v_cndmask_b32_e32 v3, 0, v3, vcc
	v_sub_f32_e32 v1, v1, v3
	v_sub_f32_e32 v2, v2, v1

.LBB0_1235:
	s_or_b64 exec, exec, s[18:19]
	v_or_b32_e32 v34, 14, v20
	v_mov_b32_e32 v16, 0
	v_mov_b32_e32 v3, 0
	s_and_saveexec_b64 s[18:19], s[2:3]
	s_cbranch_execz .LBB0_1242
	v_cmp_le_i32_e32 vcc, s22, v34
	s_and_saveexec_b64 s[4:5], vcc
	s_xor_b64 s[20:21], exec, s[4:5]
	s_cbranch_execz .LBB0_1238
	v_subrev_u32_e32 v36, s22, v34
	v_mov_b32_e32 v37, 0
	v_lshl_add_u64 v[36:37], v[36:37], 2, s[14:15]
	v_mov_b32_e32 v1, v238
	s_mov_b32 s4, 0xbfb8aa3b
	s_mov_b32 s5, 0x3f317217
	s_mov_b32 s13, 0x7f800000
	s_waitcnt vmcnt(0)
	v_mul_f32_e64 v3, |v1|, s4
	v_exp_f32_e32 v3, v3
	s_mov_b32 s4, 0x800000
	v_max_f32_e32 v1, v1, v1
	v_min_f32_e32 v1, 0, v1
	v_add_f32_e32 v3, 1.0, v3
	v_cmp_gt_f32_e32 vcc, s4, v3
	s_nop 1
	v_cndmask_b32_e64 v17, 0, 32, vcc
	v_ldexp_f32 v3, v3, v17
	v_log_f32_e32 v3, v3
	v_mov_b32_e32 v17, 0x41b17218
	v_cndmask_b32_e32 v17, 0, v17, vcc
	v_mul_f32_e32 v35, 0x3f317217, v3
	v_fma_f32 v35, v3, s5, -v35
	v_fmamk_f32 v35, v3, 0x3377d1cf, v35
	v_fmac_f32_e32 v35, 0x3f317217, v3
	v_cmp_lt_f32_e64 s[4:5], |v3|, s13
	s_nop 1
	v_cndmask_b32_e64 v3, v3, v35, s[4:5]
	v_sub_f32_e32 v3, v3, v17
	v_sub_f32_e32 v3, v1, v3
.LBB0_1238:
	s_andn2_saveexec_b64 s[20:21], s[20:21]
	s_cbranch_execz .LBB0_1241
	v_mad_i64_i32 v[36:37], s[4:5], s12, v34, 0
	v_lshl_add_u64 v[36:37], v[36:37], 2, s[10:11]
	v_mov_b32_e32 v3, v238
	s_andn2_b64 vcc, exec, s[16:17]
	s_cbranch_vccnz .LBB0_1241
	s_mov_b32 s4, 0xbfb8aa3b
	s_waitcnt vmcnt(0)
	v_mul_f32_e64 v1, |v3|, s4
	v_exp_f32_e32 v1, v1
	s_mov_b32 s4, 0x800000
	s_mov_b32 s5, 0x7f800000
	v_max_f32_e32 v3, v3, v3
	v_add_f32_e32 v1, 1.0, v1
	v_cmp_gt_f32_e32 vcc, s4, v1
	s_mov_b32 s4, 0x3f317217
	v_min_f32_e32 v3, 0, v3
	v_cndmask_b32_e64 v17, 0, 32, vcc
	v_ldexp_f32 v1, v1, v17
	v_log_f32_e32 v1, v1
	s_nop 0
	v_mul_f32_e32 v17, 0x3f317217, v1
	v_fma_f32 v17, v1, s4, -v17
	v_fmamk_f32 v17, v1, 0x3377d1cf, v17
	v_fmac_f32_e32 v17, 0x3f317217, v1
	v_cmp_lt_f32_e64 s[4:5], |v1|, s5
	s_nop 1
	v_cndmask_b32_e64 v1, v1, v17, s[4:5]
	v_mov_b32_e32 v17, 0x41b17218
	v_cndmask_b32_e32 v17, 0, v17, vcc
	v_sub_f32_e32 v1, v1, v17
	v_sub_f32_e32 v3, v3, v1

.LBB0_1242:
	s_or_b64 exec, exec, s[18:19]
	v_or_b32_e32 v35, 15, v20
	s_and_saveexec_b64 s[18:19], s[2:3]
	s_cbranch_execz .LBB0_1249
	v_cmp_le_i32_e32 vcc, s22, v35
	s_and_saveexec_b64 s[4:5], vcc
	s_xor_b64 s[20:21], exec, s[4:5]
	s_cbranch_execz .LBB0_1245
	v_subrev_u32_e32 v16, s22, v35
	v_mov_b32_e32 v17, 0
	v_lshl_add_u64 v[16:17], v[16:17], 2, s[14:15]
	v_mov_b32_e32 v1, v239
	s_mov_b32 s4, 0xbfb8aa3b
	s_mov_b32 s5, 0x3f317217
	s_mov_b32 s13, 0x7f800000
	s_waitcnt vmcnt(0)
	v_mul_f32_e64 v16, |v1|, s4
	v_exp_f32_e32 v16, v16
	s_mov_b32 s4, 0x800000
	v_max_f32_e32 v1, v1, v1
	v_min_f32_e32 v1, 0, v1
	v_add_f32_e32 v16, 1.0, v16
	v_cmp_gt_f32_e32 vcc, s4, v16
	s_nop 1
	v_cndmask_b32_e64 v17, 0, 32, vcc
	v_ldexp_f32 v16, v16, v17
	v_log_f32_e32 v16, v16
	v_mov_b32_e32 v17, 0x41b17218
	v_cndmask_b32_e32 v17, 0, v17, vcc
	v_mul_f32_e32 v36, 0x3f317217, v16
	v_fma_f32 v36, v16, s5, -v36
	v_fmamk_f32 v36, v16, 0x3377d1cf, v36
	v_fmac_f32_e32 v36, 0x3f317217, v16
	v_cmp_lt_f32_e64 s[4:5], |v16|, s13
	s_nop 1
	v_cndmask_b32_e64 v16, v16, v36, s[4:5]
	v_sub_f32_e32 v16, v16, v17
	v_sub_f32_e32 v16, v1, v16
.LBB0_1245:
	s_andn2_saveexec_b64 s[14:15], s[20:21]
	s_cbranch_execz .LBB0_1248
	v_mad_i64_i32 v[16:17], s[4:5], s12, v35, 0
	v_lshl_add_u64 v[16:17], v[16:17], 2, s[10:11]
	v_mov_b32_e32 v16, v239
	s_andn2_b64 vcc, exec, s[16:17]
	s_cbranch_vccnz .LBB0_1248
	s_mov_b32 s4, 0xbfb8aa3b
	s_waitcnt vmcnt(0)
	v_mul_f32_e64 v1, |v16|, s4
	v_exp_f32_e32 v1, v1
	s_mov_b32 s4, 0x800000
	s_mov_b32 s5, 0x7f800000
	v_max_f32_e32 v16, v16, v16
	v_add_f32_e32 v1, 1.0, v1
	v_cmp_gt_f32_e32 vcc, s4, v1
	s_mov_b32 s4, 0x3f317217
	v_min_f32_e32 v16, 0, v16
	v_cndmask_b32_e64 v17, 0, 32, vcc
	v_ldexp_f32 v1, v1, v17
	v_log_f32_e32 v1, v1
	s_nop 0
	v_mul_f32_e32 v17, 0x3f317217, v1
	v_fma_f32 v17, v1, s4, -v17
	v_fmamk_f32 v17, v1, 0x3377d1cf, v17
	v_fmac_f32_e32 v17, 0x3f317217, v1
	v_cmp_lt_f32_e64 s[4:5], |v1|, s5
	s_nop 1
	v_cndmask_b32_e64 v1, v1, v17, s[4:5]
	v_mov_b32_e32 v17, 0x41b17218
	v_cndmask_b32_e32 v17, 0, v17, vcc
	v_sub_f32_e32 v1, v1, v17
	v_sub_f32_e32 v16, v16, v1

.LBB0_1315:
	s_lshr_b32 s35, s81, 6
	s_add_i32 s35, s35, 4
	s_lshr_b32 s40, s84, 6
	s_xor_b32 s93, s95, 1
	s_min_u32 s35, s35, s40
	s_andn2_b64 vcc, exec, s[4:5]
	v_readlane_b32 s4, v253, 7
	s_mov_b64 s[38:39], -1
	s_lshl_b32 s52, s93, 15
	s_lshl_b32 s35, s35, 6
	v_mbcnt_lo_u32_b32 v50, -1, 0
	v_mbcnt_hi_u32_b32 v50, -1, v50
	s_nop 0
	v_add_u32_e32 v1, s4, v50
	s_cbranch_vccz .LBB0_1463
	v_lshlrev_b32_e32 v51, 4, v1
	s_xor_b64 s[38:39], s[2:3], -1
	v_cmp_gt_i32_e64 s[2:3], s35, v51
	v_mov_b32_e32 v2, 0
	v_mov_b32_e32 v5, 0
	s_and_saveexec_b64 s[98:99], s[2:3]
	v_mov_b32_e32 v247, 0
	v_subrev_u32_e32 v246, s53, v51
	v_mad_i64_i32 v[244:245], s[100:101], s34, v51, 0
	v_lshl_add_u64 v[242:243], v[246:247], 2, s[36:37]
	v_cmp_le_i32_e64 s[100:101], s53, v51
	v_lshl_add_u64 v[244:245], v[244:245], 2, s[30:31]
	s_nop 1
	v_cndmask_b32_e64 v242, v244, v242, s[100:101]
	v_cndmask_b32_e64 v243, v245, v243, s[100:101]
	global_load_dword v224, v[242:243], off
	v_or_b32_e32 v240, 1, v51
	v_subrev_u32_e32 v246, s53, v240
	v_mad_i64_i32 v[244:245], s[100:101], s34, v240, 0
	v_lshl_add_u64 v[242:243], v[246:247], 2, s[36:37]
	v_cmp_le_i32_e64 s[100:101], s53, v240
	v_lshl_add_u64 v[244:245], v[244:245], 2, s[30:31]
	s_nop 1
	v_cndmask_b32_e64 v242, v244, v242, s[100:101]
	v_cndmask_b32_e64 v243, v245, v243, s[100:101]
	global_load_dword v225, v[242:243], off
	v_or_b32_e32 v240, 2, v51
	v_subrev_u32_e32 v246, s53, v240
	v_mad_i64_i32 v[244:245], s[100:101], s34, v240, 0
	v_lshl_add_u64 v[242:243], v[246:247], 2, s[36:37]
	v_cmp_le_i32_e64 s[100:101], s53, v240
	v_lshl_add_u64 v[244:245], v[244:245], 2, s[30:31]
	s_nop 1
	v_cndmask_b32_e64 v242, v244, v242, s[100:101]
	v_cndmask_b32_e64 v243, v245, v243, s[100:101]
	global_load_dword v226, v[242:243], off
	v_or_b32_e32 v240, 3, v51
	v_subrev_u32_e32 v246, s53, v240
	v_mad_i64_i32 v[244:245], s[100:101], s34, v240, 0
	v_lshl_add_u64 v[242:243], v[246:247], 2, s[36:37]
	v_cmp_le_i32_e64 s[100:101], s53, v240
	v_lshl_add_u64 v[244:245], v[244:245], 2, s[30:31]
	s_nop 1
	v_cndmask_b32_e64 v242, v244, v242, s[100:101]
	v_cndmask_b32_e64 v243, v245, v243, s[100:101]
	global_load_dword v227, v[242:243], off
	v_or_b32_e32 v240, 4, v51
	v_subrev_u32_e32 v246, s53, v240
	v_mad_i64_i32 v[244:245], s[100:101], s34, v240, 0
	v_lshl_add_u64 v[242:243], v[246:247], 2, s[36:37]
	v_cmp_le_i32_e64 s[100:101], s53, v240
	v_lshl_add_u64 v[244:245], v[244:245], 2, s[30:31]
	s_nop 1
	v_cndmask_b32_e64 v242, v244, v242, s[100:101]
	v_cndmask_b32_e64 v243, v245, v243, s[100:101]
	global_load_dword v228, v[242:243], off
	v_or_b32_e32 v240, 5, v51
	v_subrev_u32_e32 v246, s53, v240
	v_mad_i64_i32 v[244:245], s[100:101], s34, v240, 0
	v_lshl_add_u64 v[242:243], v[246:247], 2, s[36:37]
	v_cmp_le_i32_e64 s[100:101], s53, v240
	v_lshl_add_u64 v[244:245], v[244:245], 2, s[30:31]
	s_nop 1
	v_cndmask_b32_e64 v242, v244, v242, s[100:101]
	v_cndmask_b32_e64 v243, v245, v243, s[100:101]
	global_load_dword v229, v[242:243], off
	v_or_b32_e32 v240, 6, v51
	v_subrev_u32_e32 v246, s53, v240
	v_mad_i64_i32 v[244:245], s[100:101], s34, v240, 0
	v_lshl_add_u64 v[242:243], v[246:247], 2, s[36:37]
	v_cmp_le_i32_e64 s[100:101], s53, v240
	v_lshl_add_u64 v[244:245], v[244:245], 2, s[30:31]
	s_nop 1
	v_cndmask_b32_e64 v242, v244, v242, s[100:101]
	v_cndmask_b32_e64 v243, v245, v243, s[100:101]
	global_load_dword v230, v[242:243], off
	v_or_b32_e32 v240, 7, v51
	v_subrev_u32_e32 v246, s53, v240
	v_mad_i64_i32 v[244:245], s[100:101], s34, v240, 0
	v_lshl_add_u64 v[242:243], v[246:247], 2, s[36:37]
	v_cmp_le_i32_e64 s[100:101], s53, v240
	v_lshl_add_u64 v[244:245], v[244:245], 2, s[30:31]
	s_nop 1
	v_cndmask_b32_e64 v242, v244, v242, s[100:101]
	v_cndmask_b32_e64 v243, v245, v243, s[100:101]
	global_load_dword v231, v[242:243], off
	v_or_b32_e32 v240, 8, v51
	v_subrev_u32_e32 v246, s53, v240
	v_mad_i64_i32 v[244:245], s[100:101], s34, v240, 0
	v_lshl_add_u64 v[242:243], v[246:247], 2, s[36:37]
	v_cmp_le_i32_e64 s[100:101], s53, v240
	v_lshl_add_u64 v[244:245], v[244:245], 2, s[30:31]
	s_nop 1
	v_cndmask_b32_e64 v242, v244, v242, s[100:101]
	v_cndmask_b32_e64 v243, v245, v243, s[100:101]
	global_load_dword v232, v[242:243], off
	v_or_b32_e32 v240, 9, v51
	v_subrev_u32_e32 v246, s53, v240
	v_mad_i64_i32 v[244:245], s[100:101], s34, v240, 0
	v_lshl_add_u64 v[242:243], v[246:247], 2, s[36:37]
	v_cmp_le_i32_e64 s[100:101], s53, v240
	v_lshl_add_u64 v[244:245], v[244:245], 2, s[30:31]
	s_nop 1
	v_cndmask_b32_e64 v242, v244, v242, s[100:101]
	v_cndmask_b32_e64 v243, v245, v243, s[100:101]
	global_load_dword v233, v[242:243], off
	v_or_b32_e32 v240, 10, v51
	v_subrev_u32_e32 v246, s53, v240
	v_mad_i64_i32 v[244:245], s[100:101], s34, v240, 0
	v_lshl_add_u64 v[242:243], v[246:247], 2, s[36:37]
	v_cmp_le_i32_e64 s[100:101], s53, v240
	v_lshl_add_u64 v[244:245], v[244:245], 2, s[30:31]
	s_nop 1
	v_cndmask_b32_e64 v242, v244, v242, s[100:101]
	v_cndmask_b32_e64 v243, v245, v243, s[100:101]
	global_load_dword v234, v[242:243], off
	v_or_b32_e32 v240, 11, v51
	v_subrev_u32_e32 v246, s53, v240
	v_mad_i64_i32 v[244:245], s[100:101], s34, v240, 0
	v_lshl_add_u64 v[242:243], v[246:247], 2, s[36:37]
	v_cmp_le_i32_e64 s[100:101], s53, v240
	v_lshl_add_u64 v[244:245], v[244:245], 2, s[30:31]
	s_nop 1
	v_cndmask_b32_e64 v242, v244, v242, s[100:101]
	v_cndmask_b32_e64 v243, v245, v243, s[100:101]
	global_load_dword v235, v[242:243], off
	v_or_b32_e32 v240, 12, v51
	v_subrev_u32_e32 v246, s53, v240
	v_mad_i64_i32 v[244:245], s[100:101], s34, v240, 0
	v_lshl_add_u64 v[242:243], v[246:247], 2, s[36:37]
	v_cmp_le_i32_e64 s[100:101], s53, v240
	v_lshl_add_u64 v[244:245], v[244:245], 2, s[30:31]
	s_nop 1
	v_cndmask_b32_e64 v242, v244, v242, s[100:101]
	v_cndmask_b32_e64 v243, v245, v243, s[100:101]
	global_load_dword v236, v[242:243], off
	v_or_b32_e32 v240, 13, v51
	v_subrev_u32_e32 v246, s53, v240
	v_mad_i64_i32 v[244:245], s[100:101], s34, v240, 0
	v_lshl_add_u64 v[242:243], v[246:247], 2, s[36:37]
	v_cmp_le_i32_e64 s[100:101], s53, v240
	v_lshl_add_u64 v[244:245], v[244:245], 2, s[30:31]
	s_nop 1
	v_cndmask_b32_e64 v242, v244, v242, s[100:101]
	v_cndmask_b32_e64 v243, v245, v243, s[100:101]
	global_load_dword v237, v[242:243], off
	v_or_b32_e32 v240, 14, v51
	v_subrev_u32_e32 v246, s53, v240
	v_mad_i64_i32 v[244:245], s[100:101], s34, v240, 0
	v_lshl_add_u64 v[242:243], v[246:247], 2, s[36:37]
	v_cmp_le_i32_e64 s[100:101], s53, v240
	v_lshl_add_u64 v[244:245], v[244:245], 2, s[30:31]
	s_nop 1
	v_cndmask_b32_e64 v242, v244, v242, s[100:101]
	v_cndmask_b32_e64 v243, v245, v243, s[100:101]
	global_load_dword v238, v[242:243], off
	v_or_b32_e32 v240, 15, v51
	v_subrev_u32_e32 v246, s53, v240
	v_mad_i64_i32 v[244:245], s[100:101], s34, v240, 0
	v_lshl_add_u64 v[242:243], v[246:247], 2, s[36:37]
	v_cmp_le_i32_e64 s[100:101], s53, v240
	v_lshl_add_u64 v[244:245], v[244:245], 2, s[30:31]
	s_nop 1
	v_cndmask_b32_e64 v242, v244, v242, s[100:101]
	v_cndmask_b32_e64 v243, v245, v243, s[100:101]
	global_load_dword v239, v[242:243], off
	s_mov_b64 exec, s[98:99]
	s_waitcnt vmcnt(0)
	s_and_saveexec_b64 s[40:41], s[2:3]
	s_cbranch_execz .LBB0_1323
	v_cmp_le_i32_e32 vcc, s53, v51
	s_and_saveexec_b64 s[4:5], vcc
	s_xor_b64 s[42:43], exec, s[4:5]
	s_cbranch_execz .LBB0_1319
	v_subrev_u32_e32 v196, s53, v51
	v_lshl_add_u64 v[4:5], v[196:197], 2, s[36:37]
	v_mov_b32_e32 v3, v224
	s_waitcnt vmcnt(0)
	v_mul_f32_e64 v4, |v3|, s46
	v_exp_f32_e32 v4, v4
	v_max_f32_e32 v3, v3, v3
	v_min_f32_e32 v3, 0, v3
	v_add_f32_e32 v4, 1.0, v4
	v_cmp_gt_f32_e32 vcc, s47, v4
	s_nop 1
	v_cndmask_b32_e64 v5, 0, 32, vcc
	v_ldexp_f32 v4, v4, v5
	v_log_f32_e32 v4, v4
	s_nop 0
	v_mul_f32_e32 v5, 0x3f317217, v4
	v_fma_f32 v5, v4, s48, -v5
	v_fmac_f32_e32 v5, 0x3377d1cf, v4
	v_fmac_f32_e32 v5, 0x3f317217, v4
	v_cmp_lt_f32_e64 s[4:5], |v4|, s49
	s_nop 1
	v_cndmask_b32_e64 v4, v4, v5, s[4:5]
	v_cndmask_b32_e32 v5, 0, v206, vcc
	v_sub_f32_e32 v4, v4, v5
	v_sub_f32_e32 v5, v3, v4
.LBB0_1319:
	s_andn2_saveexec_b64 s[42:43], s[42:43]
	s_cbranch_execz .LBB0_1322
	v_mad_i64_i32 v[4:5], s[4:5], s34, v51, 0
	v_lshl_add_u64 v[4:5], v[4:5], 2, s[30:31]
	v_mov_b32_e32 v5, v224
	s_andn2_b64 vcc, exec, s[38:39]
	s_cbranch_vccnz .LBB0_1322
	s_waitcnt vmcnt(0)
	v_mul_f32_e64 v3, |v5|, s46
	v_exp_f32_e32 v3, v3
	s_nop 0
	v_add_f32_e32 v3, 1.0, v3
	v_cmp_gt_f32_e32 vcc, s47, v3
	s_nop 1
	v_cndmask_b32_e64 v4, 0, 32, vcc
	v_ldexp_f32 v3, v3, v4
	v_log_f32_e32 v3, v3
	v_max_f32_e32 v4, v5, v5
	v_min_f32_e32 v4, 0, v4
	v_mul_f32_e32 v5, 0x3f317217, v3
	v_fma_f32 v5, v3, s48, -v5
	v_fmac_f32_e32 v5, 0x3377d1cf, v3
	v_fmac_f32_e32 v5, 0x3f317217, v3
	v_cmp_lt_f32_e64 s[4:5], |v3|, s49
	s_nop 1
	v_cndmask_b32_e64 v3, v3, v5, s[4:5]
	v_cndmask_b32_e32 v5, 0, v206, vcc
	v_sub_f32_e32 v3, v3, v5
	v_sub_f32_e32 v5, v4, v3

.LBB0_1323:
	s_or_b64 exec, exec, s[40:41]
	v_or_b32_e32 v52, 1, v51
	s_and_saveexec_b64 s[40:41], s[2:3]
	s_cbranch_execz .LBB0_1330
	v_cmp_le_i32_e32 vcc, s53, v52
	s_and_saveexec_b64 s[4:5], vcc
	s_xor_b64 s[42:43], exec, s[4:5]
	s_cbranch_execz .LBB0_1326
	v_subrev_u32_e32 v196, s53, v52
	v_lshl_add_u64 v[2:3], v[196:197], 2, s[36:37]
	v_mov_b32_e32 v2, v225
	s_waitcnt vmcnt(0)
	v_mul_f32_e64 v3, |v2|, s46
	v_exp_f32_e32 v3, v3
	v_max_f32_e32 v2, v2, v2
	v_min_f32_e32 v2, 0, v2
	v_add_f32_e32 v3, 1.0, v3
	v_cmp_gt_f32_e32 vcc, s47, v3
	s_nop 1
	v_cndmask_b32_e64 v4, 0, 32, vcc
	v_ldexp_f32 v3, v3, v4
	v_log_f32_e32 v3, v3
	s_nop 0
	v_mul_f32_e32 v4, 0x3f317217, v3
	v_fma_f32 v4, v3, s48, -v4
	v_fmac_f32_e32 v4, 0x3377d1cf, v3
	v_fmac_f32_e32 v4, 0x3f317217, v3
	v_cmp_lt_f32_e64 s[4:5], |v3|, s49
	s_nop 1
	v_cndmask_b32_e64 v3, v3, v4, s[4:5]
	v_cndmask_b32_e32 v4, 0, v206, vcc
	v_sub_f32_e32 v3, v3, v4
	v_sub_f32_e32 v2, v2, v3
.LBB0_1326:
	s_andn2_saveexec_b64 s[42:43], s[42:43]
	s_cbranch_execz .LBB0_1329
	v_mad_i64_i32 v[2:3], s[4:5], s34, v52, 0
	v_lshl_add_u64 v[2:3], v[2:3], 2, s[30:31]
	v_mov_b32_e32 v2, v225
	s_andn2_b64 vcc, exec, s[38:39]
	s_cbranch_vccnz .LBB0_1329
	s_waitcnt vmcnt(0)
	v_mul_f32_e64 v3, |v2|, s46
	v_exp_f32_e32 v3, v3
	v_max_f32_e32 v2, v2, v2
	v_min_f32_e32 v2, 0, v2
	v_add_f32_e32 v3, 1.0, v3
	v_cmp_gt_f32_e32 vcc, s47, v3
	s_nop 1
	v_cndmask_b32_e64 v4, 0, 32, vcc
	v_ldexp_f32 v3, v3, v4
	v_log_f32_e32 v3, v3
	s_nop 0
	v_mul_f32_e32 v4, 0x3f317217, v3
	v_fma_f32 v4, v3, s48, -v4
	v_fmac_f32_e32 v4, 0x3377d1cf, v3
	v_fmac_f32_e32 v4, 0x3f317217, v3
	v_cmp_lt_f32_e64 s[4:5], |v3|, s49
	s_nop 1
	v_cndmask_b32_e64 v3, v3, v4, s[4:5]
	v_cndmask_b32_e32 v4, 0, v206, vcc
	v_sub_f32_e32 v3, v3, v4
	v_sub_f32_e32 v2, v2, v3

.LBB0_1330:
	s_or_b64 exec, exec, s[40:41]
	v_or_b32_e32 v53, 2, v51
	v_mov_b32_e32 v4, 0
	v_mov_b32_e32 v3, 0
	s_and_saveexec_b64 s[40:41], s[2:3]
	s_cbranch_execz .LBB0_1337
	v_cmp_le_i32_e32 vcc, s53, v53
	s_and_saveexec_b64 s[4:5], vcc
	s_xor_b64 s[42:43], exec, s[4:5]
	s_cbranch_execz .LBB0_1333
	v_subrev_u32_e32 v196, s53, v53
	v_lshl_add_u64 v[6:7], v[196:197], 2, s[36:37]
	v_mov_b32_e32 v3, v226
	s_waitcnt vmcnt(0)
	v_mul_f32_e64 v6, |v3|, s46
	v_exp_f32_e32 v6, v6
	v_max_f32_e32 v3, v3, v3
	v_min_f32_e32 v3, 0, v3
	v_add_f32_e32 v6, 1.0, v6
	v_cmp_gt_f32_e32 vcc, s47, v6
	s_nop 1
	v_cndmask_b32_e64 v7, 0, 32, vcc
	v_ldexp_f32 v6, v6, v7
	v_log_f32_e32 v6, v6
	s_nop 0
	v_mul_f32_e32 v7, 0x3f317217, v6
	v_fma_f32 v7, v6, s48, -v7
	v_fmac_f32_e32 v7, 0x3377d1cf, v6
	v_fmac_f32_e32 v7, 0x3f317217, v6
	v_cmp_lt_f32_e64 s[4:5], |v6|, s49
	s_nop 1
	v_cndmask_b32_e64 v6, v6, v7, s[4:5]
	v_cndmask_b32_e32 v7, 0, v206, vcc
	v_sub_f32_e32 v6, v6, v7
	v_sub_f32_e32 v3, v3, v6
.LBB0_1333:
	s_andn2_saveexec_b64 s[42:43], s[42:43]
	s_cbranch_execz .LBB0_1336
	v_mad_i64_i32 v[6:7], s[4:5], s34, v53, 0
	v_lshl_add_u64 v[6:7], v[6:7], 2, s[30:31]
	v_mov_b32_e32 v3, v226
	s_andn2_b64 vcc, exec, s[38:39]
	s_cbranch_vccnz .LBB0_1336
	s_waitcnt vmcnt(0)
	v_mul_f32_e64 v6, |v3|, s46
	v_exp_f32_e32 v6, v6
	v_max_f32_e32 v3, v3, v3
	v_min_f32_e32 v3, 0, v3
	v_add_f32_e32 v6, 1.0, v6
	v_cmp_gt_f32_e32 vcc, s47, v6
	s_nop 1
	v_cndmask_b32_e64 v7, 0, 32, vcc
	v_ldexp_f32 v6, v6, v7
	v_log_f32_e32 v6, v6
	s_nop 0
	v_mul_f32_e32 v7, 0x3f317217, v6
	v_fma_f32 v7, v6, s48, -v7
	v_fmac_f32_e32 v7, 0x3377d1cf, v6
	v_fmac_f32_e32 v7, 0x3f317217, v6
	v_cmp_lt_f32_e64 s[4:5], |v6|, s49
	s_nop 1
	v_cndmask_b32_e64 v6, v6, v7, s[4:5]
	v_cndmask_b32_e32 v7, 0, v206, vcc
	v_sub_f32_e32 v6, v6, v7
	v_sub_f32_e32 v3, v3, v6

.LBB0_1337:
	s_or_b64 exec, exec, s[40:41]
	v_or_b32_e32 v54, 3, v51
	s_and_saveexec_b64 s[40:41], s[2:3]
	s_cbranch_execz .LBB0_1344
	v_cmp_le_i32_e32 vcc, s53, v54
	s_and_saveexec_b64 s[4:5], vcc
	s_xor_b64 s[42:43], exec, s[4:5]
	s_cbranch_execz .LBB0_1340
	v_subrev_u32_e32 v196, s53, v54
	v_lshl_add_u64 v[6:7], v[196:197], 2, s[36:37]
	v_mov_b32_e32 v4, v227
	s_waitcnt vmcnt(0)
	v_mul_f32_e64 v6, |v4|, s46
	v_exp_f32_e32 v6, v6
	v_max_f32_e32 v4, v4, v4
	v_min_f32_e32 v4, 0, v4
	v_add_f32_e32 v6, 1.0, v6
	v_cmp_gt_f32_e32 vcc, s47, v6
	s_nop 1
	v_cndmask_b32_e64 v7, 0, 32, vcc
	v_ldexp_f32 v6, v6, v7
	v_log_f32_e32 v6, v6
	s_nop 0
	v_mul_f32_e32 v7, 0x3f317217, v6
	v_fma_f32 v7, v6, s48, -v7
	v_fmac_f32_e32 v7, 0x3377d1cf, v6
	v_fmac_f32_e32 v7, 0x3f317217, v6
	v_cmp_lt_f32_e64 s[4:5], |v6|, s49
	s_nop 1
	v_cndmask_b32_e64 v6, v6, v7, s[4:5]
	v_cndmask_b32_e32 v7, 0, v206, vcc
	v_sub_f32_e32 v6, v6, v7
	v_sub_f32_e32 v4, v4, v6
.LBB0_1340:
	s_andn2_saveexec_b64 s[42:43], s[42:43]
	s_cbranch_execz .LBB0_1343
	v_mad_i64_i32 v[6:7], s[4:5], s34, v54, 0
	v_lshl_add_u64 v[6:7], v[6:7], 2, s[30:31]
	v_mov_b32_e32 v4, v227
	s_andn2_b64 vcc, exec, s[38:39]
	s_cbranch_vccnz .LBB0_1343
	s_waitcnt vmcnt(0)
	v_mul_f32_e64 v6, |v4|, s46
	v_exp_f32_e32 v6, v6
	v_max_f32_e32 v4, v4, v4
	v_min_f32_e32 v4, 0, v4
	v_add_f32_e32 v6, 1.0, v6
	v_cmp_gt_f32_e32 vcc, s47, v6
	s_nop 1
	v_cndmask_b32_e64 v7, 0, 32, vcc
	v_ldexp_f32 v6, v6, v7
	v_log_f32_e32 v6, v6
	s_nop 0
	v_mul_f32_e32 v7, 0x3f317217, v6
	v_fma_f32 v7, v6, s48, -v7
	v_fmac_f32_e32 v7, 0x3377d1cf, v6
	v_fmac_f32_e32 v7, 0x3f317217, v6
	v_cmp_lt_f32_e64 s[4:5], |v6|, s49
	s_nop 1
	v_cndmask_b32_e64 v6, v6, v7, s[4:5]
	v_cndmask_b32_e32 v7, 0, v206, vcc
	v_sub_f32_e32 v6, v6, v7
	v_sub_f32_e32 v4, v4, v6

.LBB0_1344:
	s_or_b64 exec, exec, s[40:41]
	v_or_b32_e32 v55, 4, v51
	v_mov_b32_e32 v7, 0
	v_mov_b32_e32 v6, 0
	s_and_saveexec_b64 s[40:41], s[2:3]
	s_cbranch_execz .LBB0_1351
	v_cmp_le_i32_e32 vcc, s53, v55
	s_and_saveexec_b64 s[4:5], vcc
	s_xor_b64 s[42:43], exec, s[4:5]
	s_cbranch_execz .LBB0_1347
	v_subrev_u32_e32 v196, s53, v55
	v_lshl_add_u64 v[8:9], v[196:197], 2, s[36:37]
	v_mov_b32_e32 v6, v228
	s_waitcnt vmcnt(0)
	v_mul_f32_e64 v8, |v6|, s46
	v_exp_f32_e32 v8, v8
	v_max_f32_e32 v6, v6, v6
	v_min_f32_e32 v6, 0, v6
	v_add_f32_e32 v8, 1.0, v8
	v_cmp_gt_f32_e32 vcc, s47, v8
	s_nop 1
	v_cndmask_b32_e64 v9, 0, 32, vcc
	v_ldexp_f32 v8, v8, v9
	v_log_f32_e32 v8, v8
	s_nop 0
	v_mul_f32_e32 v9, 0x3f317217, v8
	v_fma_f32 v9, v8, s48, -v9
	v_fmac_f32_e32 v9, 0x3377d1cf, v8
	v_fmac_f32_e32 v9, 0x3f317217, v8
	v_cmp_lt_f32_e64 s[4:5], |v8|, s49
	s_nop 1
	v_cndmask_b32_e64 v8, v8, v9, s[4:5]
	v_cndmask_b32_e32 v9, 0, v206, vcc
	v_sub_f32_e32 v8, v8, v9
	v_sub_f32_e32 v6, v6, v8
.LBB0_1347:
	s_andn2_saveexec_b64 s[42:43], s[42:43]
	s_cbranch_execz .LBB0_1350
	v_mad_i64_i32 v[8:9], s[4:5], s34, v55, 0
	v_lshl_add_u64 v[8:9], v[8:9], 2, s[30:31]
	v_mov_b32_e32 v6, v228
	s_andn2_b64 vcc, exec, s[38:39]
	s_cbranch_vccnz .LBB0_1350
	s_waitcnt vmcnt(0)
	v_mul_f32_e64 v8, |v6|, s46
	v_exp_f32_e32 v8, v8
	v_max_f32_e32 v6, v6, v6
	v_min_f32_e32 v6, 0, v6
	v_add_f32_e32 v8, 1.0, v8
	v_cmp_gt_f32_e32 vcc, s47, v8
	s_nop 1
	v_cndmask_b32_e64 v9, 0, 32, vcc
	v_ldexp_f32 v8, v8, v9
	v_log_f32_e32 v8, v8
	s_nop 0
	v_mul_f32_e32 v9, 0x3f317217, v8
	v_fma_f32 v9, v8, s48, -v9
	v_fmac_f32_e32 v9, 0x3377d1cf, v8
	v_fmac_f32_e32 v9, 0x3f317217, v8
	v_cmp_lt_f32_e64 s[4:5], |v8|, s49
	s_nop 1
	v_cndmask_b32_e64 v8, v8, v9, s[4:5]
	v_cndmask_b32_e32 v9, 0, v206, vcc
	v_sub_f32_e32 v8, v8, v9
	v_sub_f32_e32 v6, v6, v8

.LBB0_1351:
	s_or_b64 exec, exec, s[40:41]
	v_or_b32_e32 v56, 5, v51
	s_and_saveexec_b64 s[40:41], s[2:3]
	s_cbranch_execz .LBB0_1358
	v_cmp_le_i32_e32 vcc, s53, v56
	s_and_saveexec_b64 s[4:5], vcc
	s_xor_b64 s[42:43], exec, s[4:5]
	s_cbranch_execz .LBB0_1354
	v_subrev_u32_e32 v196, s53, v56
	v_lshl_add_u64 v[8:9], v[196:197], 2, s[36:37]
	v_mov_b32_e32 v7, v229
	s_waitcnt vmcnt(0)
	v_mul_f32_e64 v8, |v7|, s46
	v_exp_f32_e32 v8, v8
	v_max_f32_e32 v7, v7, v7
	v_min_f32_e32 v7, 0, v7
	v_add_f32_e32 v8, 1.0, v8
	v_cmp_gt_f32_e32 vcc, s47, v8
	s_nop 1
	v_cndmask_b32_e64 v9, 0, 32, vcc
	v_ldexp_f32 v8, v8, v9
	v_log_f32_e32 v8, v8
	s_nop 0
	v_mul_f32_e32 v9, 0x3f317217, v8
	v_fma_f32 v9, v8, s48, -v9
	v_fmac_f32_e32 v9, 0x3377d1cf, v8
	v_fmac_f32_e32 v9, 0x3f317217, v8
	v_cmp_lt_f32_e64 s[4:5], |v8|, s49
	s_nop 1
	v_cndmask_b32_e64 v8, v8, v9, s[4:5]
	v_cndmask_b32_e32 v9, 0, v206, vcc
	v_sub_f32_e32 v8, v8, v9
	v_sub_f32_e32 v7, v7, v8
.LBB0_1354:
	s_andn2_saveexec_b64 s[42:43], s[42:43]
	s_cbranch_execz .LBB0_1357
	v_mad_i64_i32 v[8:9], s[4:5], s34, v56, 0
	v_lshl_add_u64 v[8:9], v[8:9], 2, s[30:31]
	v_mov_b32_e32 v7, v229
	s_andn2_b64 vcc, exec, s[38:39]
	s_cbranch_vccnz .LBB0_1357
	s_waitcnt vmcnt(0)
	v_mul_f32_e64 v8, |v7|, s46
	v_exp_f32_e32 v8, v8
	v_max_f32_e32 v7, v7, v7
	v_min_f32_e32 v7, 0, v7
	v_add_f32_e32 v8, 1.0, v8
	v_cmp_gt_f32_e32 vcc, s47, v8
	s_nop 1
	v_cndmask_b32_e64 v9, 0, 32, vcc
	v_ldexp_f32 v8, v8, v9
	v_log_f32_e32 v8, v8
	s_nop 0
	v_mul_f32_e32 v9, 0x3f317217, v8
	v_fma_f32 v9, v8, s48, -v9
	v_fmac_f32_e32 v9, 0x3377d1cf, v8
	v_fmac_f32_e32 v9, 0x3f317217, v8
	v_cmp_lt_f32_e64 s[4:5], |v8|, s49
	s_nop 1
	v_cndmask_b32_e64 v8, v8, v9, s[4:5]
	v_cndmask_b32_e32 v9, 0, v206, vcc
	v_sub_f32_e32 v8, v8, v9
	v_sub_f32_e32 v7, v7, v8

.LBB0_1358:
	s_or_b64 exec, exec, s[40:41]
	v_or_b32_e32 v57, 6, v51
	v_mov_b32_e32 v9, 0
	v_mov_b32_e32 v8, 0
	s_and_saveexec_b64 s[40:41], s[2:3]
	s_cbranch_execz .LBB0_1365
	v_cmp_le_i32_e32 vcc, s53, v57
	s_and_saveexec_b64 s[4:5], vcc
	s_xor_b64 s[42:43], exec, s[4:5]
	s_cbranch_execz .LBB0_1361
	v_subrev_u32_e32 v196, s53, v57
	v_lshl_add_u64 v[10:11], v[196:197], 2, s[36:37]
	v_mov_b32_e32 v8, v230
	s_waitcnt vmcnt(0)
	v_mul_f32_e64 v10, |v8|, s46
	v_exp_f32_e32 v10, v10
	v_max_f32_e32 v8, v8, v8
	v_min_f32_e32 v8, 0, v8
	v_add_f32_e32 v10, 1.0, v10
	v_cmp_gt_f32_e32 vcc, s47, v10
	s_nop 1
	v_cndmask_b32_e64 v11, 0, 32, vcc
	v_ldexp_f32 v10, v10, v11
	v_log_f32_e32 v10, v10
	s_nop 0
	v_mul_f32_e32 v11, 0x3f317217, v10
	v_fma_f32 v11, v10, s48, -v11
	v_fmac_f32_e32 v11, 0x3377d1cf, v10
	v_fmac_f32_e32 v11, 0x3f317217, v10
	v_cmp_lt_f32_e64 s[4:5], |v10|, s49
	s_nop 1
	v_cndmask_b32_e64 v10, v10, v11, s[4:5]
	v_cndmask_b32_e32 v11, 0, v206, vcc
	v_sub_f32_e32 v10, v10, v11
	v_sub_f32_e32 v8, v8, v10
.LBB0_1361:
	s_andn2_saveexec_b64 s[42:43], s[42:43]
	s_cbranch_execz .LBB0_1364
	v_mad_i64_i32 v[10:11], s[4:5], s34, v57, 0
	v_lshl_add_u64 v[10:11], v[10:11], 2, s[30:31]
	v_mov_b32_e32 v8, v230
	s_andn2_b64 vcc, exec, s[38:39]
	s_cbranch_vccnz .LBB0_1364
	s_waitcnt vmcnt(0)
	v_mul_f32_e64 v10, |v8|, s46
	v_exp_f32_e32 v10, v10
	v_max_f32_e32 v8, v8, v8
	v_min_f32_e32 v8, 0, v8
	v_add_f32_e32 v10, 1.0, v10
	v_cmp_gt_f32_e32 vcc, s47, v10
	s_nop 1
	v_cndmask_b32_e64 v11, 0, 32, vcc
	v_ldexp_f32 v10, v10, v11
	v_log_f32_e32 v10, v10
	s_nop 0
	v_mul_f32_e32 v11, 0x3f317217, v10
	v_fma_f32 v11, v10, s48, -v11
	v_fmac_f32_e32 v11, 0x3377d1cf, v10
	v_fmac_f32_e32 v11, 0x3f317217, v10
	v_cmp_lt_f32_e64 s[4:5], |v10|, s49
	s_nop 1
	v_cndmask_b32_e64 v10, v10, v11, s[4:5]
	v_cndmask_b32_e32 v11, 0, v206, vcc
	v_sub_f32_e32 v10, v10, v11
	v_sub_f32_e32 v8, v8, v10

.LBB0_1365:
	s_or_b64 exec, exec, s[40:41]
	v_or_b32_e32 v58, 7, v51
	s_and_saveexec_b64 s[40:41], s[2:3]
	s_cbranch_execz .LBB0_1372
	v_cmp_le_i32_e32 vcc, s53, v58
	s_and_saveexec_b64 s[4:5], vcc
	s_xor_b64 s[42:43], exec, s[4:5]
	s_cbranch_execz .LBB0_1368
	v_subrev_u32_e32 v196, s53, v58
	v_lshl_add_u64 v[10:11], v[196:197], 2, s[36:37]
	v_mov_b32_e32 v9, v231
	s_waitcnt vmcnt(0)
	v_mul_f32_e64 v10, |v9|, s46
	v_exp_f32_e32 v10, v10
	v_max_f32_e32 v9, v9, v9
	v_min_f32_e32 v9, 0, v9
	v_add_f32_e32 v10, 1.0, v10
	v_cmp_gt_f32_e32 vcc, s47, v10
	s_nop 1
	v_cndmask_b32_e64 v11, 0, 32, vcc
	v_ldexp_f32 v10, v10, v11
	v_log_f32_e32 v10, v10
	s_nop 0
	v_mul_f32_e32 v11, 0x3f317217, v10
	v_fma_f32 v11, v10, s48, -v11
	v_fmac_f32_e32 v11, 0x3377d1cf, v10
	v_fmac_f32_e32 v11, 0x3f317217, v10
	v_cmp_lt_f32_e64 s[4:5], |v10|, s49
	s_nop 1
	v_cndmask_b32_e64 v10, v10, v11, s[4:5]
	v_cndmask_b32_e32 v11, 0, v206, vcc
	v_sub_f32_e32 v10, v10, v11
	v_sub_f32_e32 v9, v9, v10
.LBB0_1368:
	s_andn2_saveexec_b64 s[42:43], s[42:43]
	s_cbranch_execz .LBB0_1371
	v_mad_i64_i32 v[10:11], s[4:5], s34, v58, 0
	v_lshl_add_u64 v[10:11], v[10:11], 2, s[30:31]
	v_mov_b32_e32 v9, v231
	s_andn2_b64 vcc, exec, s[38:39]
	s_cbranch_vccnz .LBB0_1371
	s_waitcnt vmcnt(0)
	v_mul_f32_e64 v10, |v9|, s46
	v_exp_f32_e32 v10, v10
	v_max_f32_e32 v9, v9, v9
	v_min_f32_e32 v9, 0, v9
	v_add_f32_e32 v10, 1.0, v10
	v_cmp_gt_f32_e32 vcc, s47, v10
	s_nop 1
	v_cndmask_b32_e64 v11, 0, 32, vcc
	v_ldexp_f32 v10, v10, v11
	v_log_f32_e32 v10, v10
	s_nop 0
	v_mul_f32_e32 v11, 0x3f317217, v10
	v_fma_f32 v11, v10, s48, -v11
	v_fmac_f32_e32 v11, 0x3377d1cf, v10
	v_fmac_f32_e32 v11, 0x3f317217, v10
	v_cmp_lt_f32_e64 s[4:5], |v10|, s49
	s_nop 1
	v_cndmask_b32_e64 v10, v10, v11, s[4:5]
	v_cndmask_b32_e32 v11, 0, v206, vcc
	v_sub_f32_e32 v10, v10, v11
	v_sub_f32_e32 v9, v9, v10

.LBB0_1372:
	s_or_b64 exec, exec, s[40:41]
	v_or_b32_e32 v59, 8, v51
	v_mov_b32_e32 v11, 0
	v_mov_b32_e32 v10, 0
	s_and_saveexec_b64 s[40:41], s[2:3]
	s_cbranch_execz .LBB0_1379
	v_cmp_le_i32_e32 vcc, s53, v59
	s_and_saveexec_b64 s[4:5], vcc
	s_xor_b64 s[42:43], exec, s[4:5]
	s_cbranch_execz .LBB0_1375
	v_subrev_u32_e32 v196, s53, v59
	v_lshl_add_u64 v[12:13], v[196:197], 2, s[36:37]
	v_mov_b32_e32 v10, v232
	s_waitcnt vmcnt(0)
	v_mul_f32_e64 v12, |v10|, s46
	v_exp_f32_e32 v12, v12
	v_max_f32_e32 v10, v10, v10
	v_min_f32_e32 v10, 0, v10
	v_add_f32_e32 v12, 1.0, v12
	v_cmp_gt_f32_e32 vcc, s47, v12
	s_nop 1
	v_cndmask_b32_e64 v13, 0, 32, vcc
	v_ldexp_f32 v12, v12, v13
	v_log_f32_e32 v12, v12
	s_nop 0
	v_mul_f32_e32 v13, 0x3f317217, v12
	v_fma_f32 v13, v12, s48, -v13
	v_fmac_f32_e32 v13, 0x3377d1cf, v12
	v_fmac_f32_e32 v13, 0x3f317217, v12
	v_cmp_lt_f32_e64 s[4:5], |v12|, s49
	s_nop 1
	v_cndmask_b32_e64 v12, v12, v13, s[4:5]
	v_cndmask_b32_e32 v13, 0, v206, vcc
	v_sub_f32_e32 v12, v12, v13
	v_sub_f32_e32 v10, v10, v12
.LBB0_1375:
	s_andn2_saveexec_b64 s[42:43], s[42:43]
	s_cbranch_execz .LBB0_1378
	v_mad_i64_i32 v[12:13], s[4:5], s34, v59, 0
	v_lshl_add_u64 v[12:13], v[12:13], 2, s[30:31]
	v_mov_b32_e32 v10, v232
	s_andn2_b64 vcc, exec, s[38:39]
	s_cbranch_vccnz .LBB0_1378
	s_waitcnt vmcnt(0)
	v_mul_f32_e64 v12, |v10|, s46
	v_exp_f32_e32 v12, v12
	v_max_f32_e32 v10, v10, v10
	v_min_f32_e32 v10, 0, v10
	v_add_f32_e32 v12, 1.0, v12
	v_cmp_gt_f32_e32 vcc, s47, v12
	s_nop 1
	v_cndmask_b32_e64 v13, 0, 32, vcc
	v_ldexp_f32 v12, v12, v13
	v_log_f32_e32 v12, v12
	s_nop 0
	v_mul_f32_e32 v13, 0x3f317217, v12
	v_fma_f32 v13, v12, s48, -v13
	v_fmac_f32_e32 v13, 0x3377d1cf, v12
	v_fmac_f32_e32 v13, 0x3f317217, v12
	v_cmp_lt_f32_e64 s[4:5], |v12|, s49
	s_nop 1
	v_cndmask_b32_e64 v12, v12, v13, s[4:5]
	v_cndmask_b32_e32 v13, 0, v206, vcc
	v_sub_f32_e32 v12, v12, v13
	v_sub_f32_e32 v10, v10, v12

.LBB0_1379:
	s_or_b64 exec, exec, s[40:41]
	v_or_b32_e32 v61, 9, v51
	s_and_saveexec_b64 s[40:41], s[2:3]
	s_cbranch_execz .LBB0_1386
	v_cmp_le_i32_e32 vcc, s53, v61
	s_and_saveexec_b64 s[4:5], vcc
	s_xor_b64 s[42:43], exec, s[4:5]
	s_cbranch_execz .LBB0_1382
	v_subrev_u32_e32 v196, s53, v61
	v_lshl_add_u64 v[12:13], v[196:197], 2, s[36:37]
	v_mov_b32_e32 v11, v233
	s_waitcnt vmcnt(0)
	v_mul_f32_e64 v12, |v11|, s46
	v_exp_f32_e32 v12, v12
	v_max_f32_e32 v11, v11, v11
	v_min_f32_e32 v11, 0, v11
	v_add_f32_e32 v12, 1.0, v12
	v_cmp_gt_f32_e32 vcc, s47, v12
	s_nop 1
	v_cndmask_b32_e64 v13, 0, 32, vcc
	v_ldexp_f32 v12, v12, v13
	v_log_f32_e32 v12, v12
	s_nop 0
	v_mul_f32_e32 v13, 0x3f317217, v12
	v_fma_f32 v13, v12, s48, -v13
	v_fmac_f32_e32 v13, 0x3377d1cf, v12
	v_fmac_f32_e32 v13, 0x3f317217, v12
	v_cmp_lt_f32_e64 s[4:5], |v12|, s49
	s_nop 1
	v_cndmask_b32_e64 v12, v12, v13, s[4:5]
	v_cndmask_b32_e32 v13, 0, v206, vcc
	v_sub_f32_e32 v12, v12, v13
	v_sub_f32_e32 v11, v11, v12
.LBB0_1382:
	s_andn2_saveexec_b64 s[42:43], s[42:43]
	s_cbranch_execz .LBB0_1385
	v_mad_i64_i32 v[12:13], s[4:5], s34, v61, 0
	v_lshl_add_u64 v[12:13], v[12:13], 2, s[30:31]
	v_mov_b32_e32 v11, v233
	s_andn2_b64 vcc, exec, s[38:39]
	s_cbranch_vccnz .LBB0_1385
	s_waitcnt vmcnt(0)
	v_mul_f32_e64 v12, |v11|, s46
	v_exp_f32_e32 v12, v12
	v_max_f32_e32 v11, v11, v11
	v_min_f32_e32 v11, 0, v11
	v_add_f32_e32 v12, 1.0, v12
	v_cmp_gt_f32_e32 vcc, s47, v12
	s_nop 1
	v_cndmask_b32_e64 v13, 0, 32, vcc
	v_ldexp_f32 v12, v12, v13
	v_log_f32_e32 v12, v12
	s_nop 0
	v_mul_f32_e32 v13, 0x3f317217, v12
	v_fma_f32 v13, v12, s48, -v13
	v_fmac_f32_e32 v13, 0x3377d1cf, v12
	v_fmac_f32_e32 v13, 0x3f317217, v12
	v_cmp_lt_f32_e64 s[4:5], |v12|, s49
	s_nop 1
	v_cndmask_b32_e64 v12, v12, v13, s[4:5]
	v_cndmask_b32_e32 v13, 0, v206, vcc
	v_sub_f32_e32 v12, v12, v13
	v_sub_f32_e32 v11, v11, v12

.LBB0_1386:
	s_or_b64 exec, exec, s[40:41]
	v_or_b32_e32 v63, 10, v51
	v_mov_b32_e32 v13, 0
	v_mov_b32_e32 v12, 0
	s_and_saveexec_b64 s[40:41], s[2:3]
	s_cbranch_execz .LBB0_1393
	v_cmp_le_i32_e32 vcc, s53, v63
	s_and_saveexec_b64 s[4:5], vcc
	s_xor_b64 s[42:43], exec, s[4:5]
	s_cbranch_execz .LBB0_1389
	v_subrev_u32_e32 v196, s53, v63
	v_lshl_add_u64 v[14:15], v[196:197], 2, s[36:37]
	v_mov_b32_e32 v12, v234
	s_waitcnt vmcnt(0)
	v_mul_f32_e64 v14, |v12|, s46
	v_exp_f32_e32 v14, v14
	v_max_f32_e32 v12, v12, v12
	v_min_f32_e32 v12, 0, v12
	v_add_f32_e32 v14, 1.0, v14
	v_cmp_gt_f32_e32 vcc, s47, v14
	s_nop 1
	v_cndmask_b32_e64 v15, 0, 32, vcc
	v_ldexp_f32 v14, v14, v15
	v_log_f32_e32 v14, v14
	s_nop 0
	v_mul_f32_e32 v15, 0x3f317217, v14
	v_fma_f32 v15, v14, s48, -v15
	v_fmac_f32_e32 v15, 0x3377d1cf, v14
	v_fmac_f32_e32 v15, 0x3f317217, v14
	v_cmp_lt_f32_e64 s[4:5], |v14|, s49
	s_nop 1
	v_cndmask_b32_e64 v14, v14, v15, s[4:5]
	v_cndmask_b32_e32 v15, 0, v206, vcc
	v_sub_f32_e32 v14, v14, v15
	v_sub_f32_e32 v12, v12, v14
.LBB0_1389:
	s_andn2_saveexec_b64 s[42:43], s[42:43]
	s_cbranch_execz .LBB0_1392
	v_mad_i64_i32 v[14:15], s[4:5], s34, v63, 0
	v_lshl_add_u64 v[14:15], v[14:15], 2, s[30:31]
	v_mov_b32_e32 v12, v234
	s_andn2_b64 vcc, exec, s[38:39]
	s_cbranch_vccnz .LBB0_1392
	s_waitcnt vmcnt(0)
	v_mul_f32_e64 v14, |v12|, s46
	v_exp_f32_e32 v14, v14
	v_max_f32_e32 v12, v12, v12
	v_min_f32_e32 v12, 0, v12
	v_add_f32_e32 v14, 1.0, v14
	v_cmp_gt_f32_e32 vcc, s47, v14
	s_nop 1
	v_cndmask_b32_e64 v15, 0, 32, vcc
	v_ldexp_f32 v14, v14, v15
	v_log_f32_e32 v14, v14
	s_nop 0
	v_mul_f32_e32 v15, 0x3f317217, v14
	v_fma_f32 v15, v14, s48, -v15
	v_fmac_f32_e32 v15, 0x3377d1cf, v14
	v_fmac_f32_e32 v15, 0x3f317217, v14
	v_cmp_lt_f32_e64 s[4:5], |v14|, s49
	s_nop 1
	v_cndmask_b32_e64 v14, v14, v15, s[4:5]
	v_cndmask_b32_e32 v15, 0, v206, vcc
	v_sub_f32_e32 v14, v14, v15
	v_sub_f32_e32 v12, v12, v14

.LBB0_1393:
	s_or_b64 exec, exec, s[40:41]
	v_or_b32_e32 v64, 11, v51
	s_and_saveexec_b64 s[40:41], s[2:3]
	s_cbranch_execz .LBB0_1400
	v_cmp_le_i32_e32 vcc, s53, v64
	s_and_saveexec_b64 s[4:5], vcc
	s_xor_b64 s[42:43], exec, s[4:5]
	s_cbranch_execz .LBB0_1396
	v_subrev_u32_e32 v196, s53, v64
	v_lshl_add_u64 v[14:15], v[196:197], 2, s[36:37]
	v_mov_b32_e32 v13, v235
	s_waitcnt vmcnt(0)
	v_mul_f32_e64 v14, |v13|, s46
	v_exp_f32_e32 v14, v14
	v_max_f32_e32 v13, v13, v13
	v_min_f32_e32 v13, 0, v13
	v_add_f32_e32 v14, 1.0, v14
	v_cmp_gt_f32_e32 vcc, s47, v14
	s_nop 1
	v_cndmask_b32_e64 v15, 0, 32, vcc
	v_ldexp_f32 v14, v14, v15
	v_log_f32_e32 v14, v14
	s_nop 0
	v_mul_f32_e32 v15, 0x3f317217, v14
	v_fma_f32 v15, v14, s48, -v15
	v_fmac_f32_e32 v15, 0x3377d1cf, v14
	v_fmac_f32_e32 v15, 0x3f317217, v14
	v_cmp_lt_f32_e64 s[4:5], |v14|, s49
	s_nop 1
	v_cndmask_b32_e64 v14, v14, v15, s[4:5]
	v_cndmask_b32_e32 v15, 0, v206, vcc
	v_sub_f32_e32 v14, v14, v15
	v_sub_f32_e32 v13, v13, v14
.LBB0_1396:
	s_andn2_saveexec_b64 s[42:43], s[42:43]
	s_cbranch_execz .LBB0_1399
	v_mad_i64_i32 v[14:15], s[4:5], s34, v64, 0
	v_lshl_add_u64 v[14:15], v[14:15], 2, s[30:31]
	v_mov_b32_e32 v13, v235
	s_andn2_b64 vcc, exec, s[38:39]
	s_cbranch_vccnz .LBB0_1399
	s_waitcnt vmcnt(0)
	v_mul_f32_e64 v14, |v13|, s46
	v_exp_f32_e32 v14, v14
	v_max_f32_e32 v13, v13, v13
	v_min_f32_e32 v13, 0, v13
	v_add_f32_e32 v14, 1.0, v14
	v_cmp_gt_f32_e32 vcc, s47, v14
	s_nop 1
	v_cndmask_b32_e64 v15, 0, 32, vcc
	v_ldexp_f32 v14, v14, v15
	v_log_f32_e32 v14, v14
	s_nop 0
	v_mul_f32_e32 v15, 0x3f317217, v14
	v_fma_f32 v15, v14, s48, -v15
	v_fmac_f32_e32 v15, 0x3377d1cf, v14
	v_fmac_f32_e32 v15, 0x3f317217, v14
	v_cmp_lt_f32_e64 s[4:5], |v14|, s49
	s_nop 1
	v_cndmask_b32_e64 v14, v14, v15, s[4:5]
	v_cndmask_b32_e32 v15, 0, v206, vcc
	v_sub_f32_e32 v14, v14, v15
	v_sub_f32_e32 v13, v13, v14

.LBB0_1400:
	s_or_b64 exec, exec, s[40:41]
	v_or_b32_e32 v60, 12, v51
	v_mov_b32_e32 v15, 0
	v_mov_b32_e32 v14, 0
	s_and_saveexec_b64 s[40:41], s[2:3]
	s_cbranch_execz .LBB0_1407
	v_cmp_le_i32_e32 vcc, s53, v60
	s_and_saveexec_b64 s[4:5], vcc
	s_xor_b64 s[42:43], exec, s[4:5]
	s_cbranch_execz .LBB0_1403
	v_subrev_u32_e32 v196, s53, v60
	v_lshl_add_u64 v[16:17], v[196:197], 2, s[36:37]
	v_mov_b32_e32 v14, v236
	s_waitcnt vmcnt(0)
	v_mul_f32_e64 v16, |v14|, s46
	v_exp_f32_e32 v16, v16
	v_max_f32_e32 v14, v14, v14
	v_min_f32_e32 v14, 0, v14
	v_add_f32_e32 v16, 1.0, v16
	v_cmp_gt_f32_e32 vcc, s47, v16
	s_nop 1
	v_cndmask_b32_e64 v17, 0, 32, vcc
	v_ldexp_f32 v16, v16, v17
	v_log_f32_e32 v16, v16
	s_nop 0
	v_mul_f32_e32 v17, 0x3f317217, v16
	v_fma_f32 v17, v16, s48, -v17
	v_fmac_f32_e32 v17, 0x3377d1cf, v16
	v_fmac_f32_e32 v17, 0x3f317217, v16
	v_cmp_lt_f32_e64 s[4:5], |v16|, s49
	s_nop 1
	v_cndmask_b32_e64 v16, v16, v17, s[4:5]
	v_cndmask_b32_e32 v17, 0, v206, vcc
	v_sub_f32_e32 v16, v16, v17
	v_sub_f32_e32 v14, v14, v16
.LBB0_1403:
	s_andn2_saveexec_b64 s[42:43], s[42:43]
	s_cbranch_execz .LBB0_1406
	v_mad_i64_i32 v[16:17], s[4:5], s34, v60, 0
	v_lshl_add_u64 v[16:17], v[16:17], 2, s[30:31]
	v_mov_b32_e32 v14, v236
	s_andn2_b64 vcc, exec, s[38:39]
	s_cbranch_vccnz .LBB0_1406
	s_waitcnt vmcnt(0)
	v_mul_f32_e64 v16, |v14|, s46
	v_exp_f32_e32 v16, v16
	v_max_f32_e32 v14, v14, v14
	v_min_f32_e32 v14, 0, v14
	v_add_f32_e32 v16, 1.0, v16
	v_cmp_gt_f32_e32 vcc, s47, v16
	s_nop 1
	v_cndmask_b32_e64 v17, 0, 32, vcc
	v_ldexp_f32 v16, v16, v17
	v_log_f32_e32 v16, v16
	s_nop 0
	v_mul_f32_e32 v17, 0x3f317217, v16
	v_fma_f32 v17, v16, s48, -v17
	v_fmac_f32_e32 v17, 0x3377d1cf, v16
	v_fmac_f32_e32 v17, 0x3f317217, v16
	v_cmp_lt_f32_e64 s[4:5], |v16|, s49
	s_nop 1
	v_cndmask_b32_e64 v16, v16, v17, s[4:5]
	v_cndmask_b32_e32 v17, 0, v206, vcc
	v_sub_f32_e32 v16, v16, v17
	v_sub_f32_e32 v14, v14, v16

.LBB0_1407:
	s_or_b64 exec, exec, s[40:41]
	v_or_b32_e32 v62, 13, v51
	s_and_saveexec_b64 s[40:41], s[2:3]
	s_cbranch_execz .LBB0_1414
	v_cmp_le_i32_e32 vcc, s53, v62
	s_and_saveexec_b64 s[4:5], vcc
	s_xor_b64 s[42:43], exec, s[4:5]
	s_cbranch_execz .LBB0_1410
	v_subrev_u32_e32 v196, s53, v62
	v_lshl_add_u64 v[16:17], v[196:197], 2, s[36:37]
	v_mov_b32_e32 v15, v237
	s_waitcnt vmcnt(0)
	v_mul_f32_e64 v16, |v15|, s46
	v_exp_f32_e32 v16, v16
	v_max_f32_e32 v15, v15, v15
	v_min_f32_e32 v15, 0, v15
	v_add_f32_e32 v16, 1.0, v16
	v_cmp_gt_f32_e32 vcc, s47, v16
	s_nop 1
	v_cndmask_b32_e64 v17, 0, 32, vcc
	v_ldexp_f32 v16, v16, v17
	v_log_f32_e32 v16, v16
	s_nop 0
	v_mul_f32_e32 v17, 0x3f317217, v16
	v_fma_f32 v17, v16, s48, -v17
	v_fmac_f32_e32 v17, 0x3377d1cf, v16
	v_fmac_f32_e32 v17, 0x3f317217, v16
	v_cmp_lt_f32_e64 s[4:5], |v16|, s49
	s_nop 1
	v_cndmask_b32_e64 v16, v16, v17, s[4:5]
	v_cndmask_b32_e32 v17, 0, v206, vcc
	v_sub_f32_e32 v16, v16, v17
	v_sub_f32_e32 v15, v15, v16
.LBB0_1410:
	s_andn2_saveexec_b64 s[42:43], s[42:43]
	s_cbranch_execz .LBB0_1413
	v_mad_i64_i32 v[16:17], s[4:5], s34, v62, 0
	v_lshl_add_u64 v[16:17], v[16:17], 2, s[30:31]
	v_mov_b32_e32 v15, v237
	s_andn2_b64 vcc, exec, s[38:39]
	s_cbranch_vccnz .LBB0_1413
	s_waitcnt vmcnt(0)
	v_mul_f32_e64 v16, |v15|, s46
	v_exp_f32_e32 v16, v16
	v_max_f32_e32 v15, v15, v15
	v_min_f32_e32 v15, 0, v15
	v_add_f32_e32 v16, 1.0, v16
	v_cmp_gt_f32_e32 vcc, s47, v16
	s_nop 1
	v_cndmask_b32_e64 v17, 0, 32, vcc
	v_ldexp_f32 v16, v16, v17
	v_log_f32_e32 v16, v16
	s_nop 0
	v_mul_f32_e32 v17, 0x3f317217, v16
	v_fma_f32 v17, v16, s48, -v17
	v_fmac_f32_e32 v17, 0x3377d1cf, v16
	v_fmac_f32_e32 v17, 0x3f317217, v16
	v_cmp_lt_f32_e64 s[4:5], |v16|, s49
	s_nop 1
	v_cndmask_b32_e64 v16, v16, v17, s[4:5]
	v_cndmask_b32_e32 v17, 0, v206, vcc
	v_sub_f32_e32 v16, v16, v17
	v_sub_f32_e32 v15, v15, v16

.LBB0_1414:
	s_or_b64 exec, exec, s[40:41]
	v_or_b32_e32 v65, 14, v51
	v_mov_b32_e32 v17, 0
	v_mov_b32_e32 v16, 0
	s_and_saveexec_b64 s[40:41], s[2:3]
	s_cbranch_execz .LBB0_1421
	v_cmp_le_i32_e32 vcc, s53, v65
	s_and_saveexec_b64 s[4:5], vcc
	s_xor_b64 s[42:43], exec, s[4:5]
	s_cbranch_execz .LBB0_1417
	v_subrev_u32_e32 v196, s53, v65
	v_lshl_add_u64 v[18:19], v[196:197], 2, s[36:37]
	v_mov_b32_e32 v16, v238
	s_waitcnt vmcnt(0)
	v_mul_f32_e64 v18, |v16|, s46
	v_exp_f32_e32 v18, v18
	v_max_f32_e32 v16, v16, v16
	v_min_f32_e32 v16, 0, v16
	v_add_f32_e32 v18, 1.0, v18
	v_cmp_gt_f32_e32 vcc, s47, v18
	s_nop 1
	v_cndmask_b32_e64 v19, 0, 32, vcc
	v_ldexp_f32 v18, v18, v19
	v_log_f32_e32 v18, v18
	s_nop 0
	v_mul_f32_e32 v19, 0x3f317217, v18
	v_fma_f32 v19, v18, s48, -v19
	v_fmac_f32_e32 v19, 0x3377d1cf, v18
	v_fmac_f32_e32 v19, 0x3f317217, v18
	v_cmp_lt_f32_e64 s[4:5], |v18|, s49
	s_nop 1
	v_cndmask_b32_e64 v18, v18, v19, s[4:5]
	v_cndmask_b32_e32 v19, 0, v206, vcc
	v_sub_f32_e32 v18, v18, v19
	v_sub_f32_e32 v16, v16, v18
.LBB0_1417:
	s_andn2_saveexec_b64 s[42:43], s[42:43]
	s_cbranch_execz .LBB0_1420
	v_mad_i64_i32 v[18:19], s[4:5], s34, v65, 0
	v_lshl_add_u64 v[18:19], v[18:19], 2, s[30:31]
	v_mov_b32_e32 v16, v238
	s_andn2_b64 vcc, exec, s[38:39]
	s_cbranch_vccnz .LBB0_1420
	s_waitcnt vmcnt(0)
	v_mul_f32_e64 v18, |v16|, s46
	v_exp_f32_e32 v18, v18
	v_max_f32_e32 v16, v16, v16
	v_min_f32_e32 v16, 0, v16
	v_add_f32_e32 v18, 1.0, v18
	v_cmp_gt_f32_e32 vcc, s47, v18
	s_nop 1
	v_cndmask_b32_e64 v19, 0, 32, vcc
	v_ldexp_f32 v18, v18, v19
	v_log_f32_e32 v18, v18
	s_nop 0
	v_mul_f32_e32 v19, 0x3f317217, v18
	v_fma_f32 v19, v18, s48, -v19
	v_fmac_f32_e32 v19, 0x3377d1cf, v18
	v_fmac_f32_e32 v19, 0x3f317217, v18
	v_cmp_lt_f32_e64 s[4:5], |v18|, s49
	s_nop 1
	v_cndmask_b32_e64 v18, v18, v19, s[4:5]
	v_cndmask_b32_e32 v19, 0, v206, vcc
	v_sub_f32_e32 v18, v18, v19
	v_sub_f32_e32 v16, v16, v18

.LBB0_1421:
	s_or_b64 exec, exec, s[40:41]
	v_or_b32_e32 v66, 15, v51
	s_and_saveexec_b64 s[40:41], s[2:3]
	s_cbranch_execz .LBB0_1428
	v_cmp_le_i32_e32 vcc, s53, v66
	s_and_saveexec_b64 s[4:5], vcc
	s_xor_b64 s[42:43], exec, s[4:5]
	s_cbranch_execz .LBB0_1424
	v_subrev_u32_e32 v196, s53, v66
	v_lshl_add_u64 v[18:19], v[196:197], 2, s[36:37]
	v_mov_b32_e32 v17, v239
	s_waitcnt vmcnt(0)
	v_mul_f32_e64 v18, |v17|, s46
	v_exp_f32_e32 v18, v18
	v_max_f32_e32 v17, v17, v17
	v_min_f32_e32 v17, 0, v17
	v_add_f32_e32 v18, 1.0, v18
	v_cmp_gt_f32_e32 vcc, s47, v18
	s_nop 1
	v_cndmask_b32_e64 v19, 0, 32, vcc
	v_ldexp_f32 v18, v18, v19
	v_log_f32_e32 v18, v18
	s_nop 0
	v_mul_f32_e32 v19, 0x3f317217, v18
	v_fma_f32 v19, v18, s48, -v19
	v_fmac_f32_e32 v19, 0x3377d1cf, v18
	v_fmac_f32_e32 v19, 0x3f317217, v18
	v_cmp_lt_f32_e64 s[4:5], |v18|, s49
	s_nop 1
	v_cndmask_b32_e64 v18, v18, v19, s[4:5]
	v_cndmask_b32_e32 v19, 0, v206, vcc
	v_sub_f32_e32 v18, v18, v19
	v_sub_f32_e32 v17, v17, v18
.LBB0_1424:
	s_andn2_saveexec_b64 s[36:37], s[42:43]
	s_cbranch_execz .LBB0_1427
	v_mad_i64_i32 v[18:19], s[4:5], s34, v66, 0
	v_lshl_add_u64 v[18:19], v[18:19], 2, s[30:31]
	v_mov_b32_e32 v17, v239
	s_andn2_b64 vcc, exec, s[38:39]
	s_cbranch_vccnz .LBB0_1427
	s_waitcnt vmcnt(0)
	v_mul_f32_e64 v18, |v17|, s46
	v_exp_f32_e32 v18, v18
	v_max_f32_e32 v17, v17, v17
	v_min_f32_e32 v17, 0, v17
	v_add_f32_e32 v18, 1.0, v18
	v_cmp_gt_f32_e32 vcc, s47, v18
	s_nop 1
	v_cndmask_b32_e64 v19, 0, 32, vcc
	v_ldexp_f32 v18, v18, v19
	v_log_f32_e32 v18, v18
	s_nop 0
	v_mul_f32_e32 v19, 0x3f317217, v18
	v_fma_f32 v19, v18, s48, -v19
	v_fmac_f32_e32 v19, 0x3377d1cf, v18
	v_fmac_f32_e32 v19, 0x3f317217, v18
	v_cmp_lt_f32_e64 s[4:5], |v18|, s49
	s_nop 1
	v_cndmask_b32_e64 v18, v18, v19, s[4:5]
	v_cndmask_b32_e32 v19, 0, v206, vcc
	v_sub_f32_e32 v18, v18, v19
	v_sub_f32_e32 v17, v17, v18

.LBB0_6573:
	s_ashr_i32 s40, s11, 31
	s_or_b32 s23, s11, 0xff
	s_lshr_b32 s40, s40, 26
	s_add_i32 s40, s23, s40
	s_ashr_i32 s40, s40, 6
	s_add_i32 s40, s40, 1
	s_min_i32 s40, s40, s12
	s_andn2_b64 vcc, exec, s[34:35]
	v_readlane_b32 s34, v253, 7
	s_mov_b64 s[70:71], -1
	s_lshl_b32 s12, s40, 6
	v_mbcnt_lo_u32_b32 v2, -1, 0
	v_mbcnt_hi_u32_b32 v2, -1, v2
	s_nop 0
	v_add_u32_e32 v50, s34, v2
	s_cbranch_vccz .LBB0_6720
	v_lshlrev_b32_e32 v51, 4, v50
	s_xor_b64 s[70:71], s[36:37], -1
	v_cmp_gt_i32_e64 s[34:35], s12, v51
	v_mov_b32_e32 v3, 0
	v_mov_b32_e32 v6, 0
	s_and_saveexec_b64 s[98:99], s[34:35]
	v_mov_b32_e32 v247, 0
	v_subrev_u32_e32 v246, s28, v51
	v_mad_i64_i32 v[244:245], s[100:101], s22, v51, 0
	v_lshl_add_u64 v[242:243], v[246:247], 2, s[26:27]
	v_cmp_le_i32_e64 s[100:101], s28, v51
	v_lshl_add_u64 v[244:245], v[244:245], 2, s[0:1]
	s_nop 1
	v_cndmask_b32_e64 v242, v244, v242, s[100:101]
	v_cndmask_b32_e64 v243, v245, v243, s[100:101]
	global_load_dword v224, v[242:243], off
	v_or_b32_e32 v240, 1, v51
	v_subrev_u32_e32 v246, s28, v240
	v_mad_i64_i32 v[244:245], s[100:101], s22, v240, 0
	v_lshl_add_u64 v[242:243], v[246:247], 2, s[26:27]
	v_cmp_le_i32_e64 s[100:101], s28, v240
	v_lshl_add_u64 v[244:245], v[244:245], 2, s[0:1]
	s_nop 1
	v_cndmask_b32_e64 v242, v244, v242, s[100:101]
	v_cndmask_b32_e64 v243, v245, v243, s[100:101]
	global_load_dword v225, v[242:243], off
	v_or_b32_e32 v240, 2, v51
	v_subrev_u32_e32 v246, s28, v240
	v_mad_i64_i32 v[244:245], s[100:101], s22, v240, 0
	v_lshl_add_u64 v[242:243], v[246:247], 2, s[26:27]
	v_cmp_le_i32_e64 s[100:101], s28, v240
	v_lshl_add_u64 v[244:245], v[244:245], 2, s[0:1]
	s_nop 1
	v_cndmask_b32_e64 v242, v244, v242, s[100:101]
	v_cndmask_b32_e64 v243, v245, v243, s[100:101]
	global_load_dword v226, v[242:243], off
	v_or_b32_e32 v240, 3, v51
	v_subrev_u32_e32 v246, s28, v240
	v_mad_i64_i32 v[244:245], s[100:101], s22, v240, 0
	v_lshl_add_u64 v[242:243], v[246:247], 2, s[26:27]
	v_cmp_le_i32_e64 s[100:101], s28, v240
	v_lshl_add_u64 v[244:245], v[244:245], 2, s[0:1]
	s_nop 1
	v_cndmask_b32_e64 v242, v244, v242, s[100:101]
	v_cndmask_b32_e64 v243, v245, v243, s[100:101]
	global_load_dword v227, v[242:243], off
	v_or_b32_e32 v240, 4, v51
	v_subrev_u32_e32 v246, s28, v240
	v_mad_i64_i32 v[244:245], s[100:101], s22, v240, 0
	v_lshl_add_u64 v[242:243], v[246:247], 2, s[26:27]
	v_cmp_le_i32_e64 s[100:101], s28, v240
	v_lshl_add_u64 v[244:245], v[244:245], 2, s[0:1]
	s_nop 1
	v_cndmask_b32_e64 v242, v244, v242, s[100:101]
	v_cndmask_b32_e64 v243, v245, v243, s[100:101]
	global_load_dword v228, v[242:243], off
	v_or_b32_e32 v240, 5, v51
	v_subrev_u32_e32 v246, s28, v240
	v_mad_i64_i32 v[244:245], s[100:101], s22, v240, 0
	v_lshl_add_u64 v[242:243], v[246:247], 2, s[26:27]
	v_cmp_le_i32_e64 s[100:101], s28, v240
	v_lshl_add_u64 v[244:245], v[244:245], 2, s[0:1]
	s_nop 1
	v_cndmask_b32_e64 v242, v244, v242, s[100:101]
	v_cndmask_b32_e64 v243, v245, v243, s[100:101]
	global_load_dword v229, v[242:243], off
	v_or_b32_e32 v240, 6, v51
	v_subrev_u32_e32 v246, s28, v240
	v_mad_i64_i32 v[244:245], s[100:101], s22, v240, 0
	v_lshl_add_u64 v[242:243], v[246:247], 2, s[26:27]
	v_cmp_le_i32_e64 s[100:101], s28, v240
	v_lshl_add_u64 v[244:245], v[244:245], 2, s[0:1]
	s_nop 1
	v_cndmask_b32_e64 v242, v244, v242, s[100:101]
	v_cndmask_b32_e64 v243, v245, v243, s[100:101]
	global_load_dword v230, v[242:243], off
	v_or_b32_e32 v240, 7, v51
	v_subrev_u32_e32 v246, s28, v240
	v_mad_i64_i32 v[244:245], s[100:101], s22, v240, 0
	v_lshl_add_u64 v[242:243], v[246:247], 2, s[26:27]
	v_cmp_le_i32_e64 s[100:101], s28, v240
	v_lshl_add_u64 v[244:245], v[244:245], 2, s[0:1]
	s_nop 1
	v_cndmask_b32_e64 v242, v244, v242, s[100:101]
	v_cndmask_b32_e64 v243, v245, v243, s[100:101]
	global_load_dword v231, v[242:243], off
	v_or_b32_e32 v240, 8, v51
	v_subrev_u32_e32 v246, s28, v240
	v_mad_i64_i32 v[244:245], s[100:101], s22, v240, 0
	v_lshl_add_u64 v[242:243], v[246:247], 2, s[26:27]
	v_cmp_le_i32_e64 s[100:101], s28, v240
	v_lshl_add_u64 v[244:245], v[244:245], 2, s[0:1]
	s_nop 1
	v_cndmask_b32_e64 v242, v244, v242, s[100:101]
	v_cndmask_b32_e64 v243, v245, v243, s[100:101]
	global_load_dword v232, v[242:243], off
	v_or_b32_e32 v240, 9, v51
	v_subrev_u32_e32 v246, s28, v240
	v_mad_i64_i32 v[244:245], s[100:101], s22, v240, 0
	v_lshl_add_u64 v[242:243], v[246:247], 2, s[26:27]
	v_cmp_le_i32_e64 s[100:101], s28, v240
	v_lshl_add_u64 v[244:245], v[244:245], 2, s[0:1]
	s_nop 1
	v_cndmask_b32_e64 v242, v244, v242, s[100:101]
	v_cndmask_b32_e64 v243, v245, v243, s[100:101]
	global_load_dword v233, v[242:243], off
	v_or_b32_e32 v240, 10, v51
	v_subrev_u32_e32 v246, s28, v240
	v_mad_i64_i32 v[244:245], s[100:101], s22, v240, 0
	v_lshl_add_u64 v[242:243], v[246:247], 2, s[26:27]
	v_cmp_le_i32_e64 s[100:101], s28, v240
	v_lshl_add_u64 v[244:245], v[244:245], 2, s[0:1]
	s_nop 1
	v_cndmask_b32_e64 v242, v244, v242, s[100:101]
	v_cndmask_b32_e64 v243, v245, v243, s[100:101]
	global_load_dword v234, v[242:243], off
	v_or_b32_e32 v240, 11, v51
	v_subrev_u32_e32 v246, s28, v240
	v_mad_i64_i32 v[244:245], s[100:101], s22, v240, 0
	v_lshl_add_u64 v[242:243], v[246:247], 2, s[26:27]
	v_cmp_le_i32_e64 s[100:101], s28, v240
	v_lshl_add_u64 v[244:245], v[244:245], 2, s[0:1]
	s_nop 1
	v_cndmask_b32_e64 v242, v244, v242, s[100:101]
	v_cndmask_b32_e64 v243, v245, v243, s[100:101]
	global_load_dword v235, v[242:243], off
	v_or_b32_e32 v240, 12, v51
	v_subrev_u32_e32 v246, s28, v240
	v_mad_i64_i32 v[244:245], s[100:101], s22, v240, 0
	v_lshl_add_u64 v[242:243], v[246:247], 2, s[26:27]
	v_cmp_le_i32_e64 s[100:101], s28, v240
	v_lshl_add_u64 v[244:245], v[244:245], 2, s[0:1]
	s_nop 1
	v_cndmask_b32_e64 v242, v244, v242, s[100:101]
	v_cndmask_b32_e64 v243, v245, v243, s[100:101]
	global_load_dword v236, v[242:243], off
	v_or_b32_e32 v240, 13, v51
	v_subrev_u32_e32 v246, s28, v240
	v_mad_i64_i32 v[244:245], s[100:101], s22, v240, 0
	v_lshl_add_u64 v[242:243], v[246:247], 2, s[26:27]
	v_cmp_le_i32_e64 s[100:101], s28, v240
	v_lshl_add_u64 v[244:245], v[244:245], 2, s[0:1]
	s_nop 1
	v_cndmask_b32_e64 v242, v244, v242, s[100:101]
	v_cndmask_b32_e64 v243, v245, v243, s[100:101]
	global_load_dword v237, v[242:243], off
	v_or_b32_e32 v240, 14, v51
	v_subrev_u32_e32 v246, s28, v240
	v_mad_i64_i32 v[244:245], s[100:101], s22, v240, 0
	v_lshl_add_u64 v[242:243], v[246:247], 2, s[26:27]
	v_cmp_le_i32_e64 s[100:101], s28, v240
	v_lshl_add_u64 v[244:245], v[244:245], 2, s[0:1]
	s_nop 1
	v_cndmask_b32_e64 v242, v244, v242, s[100:101]
	v_cndmask_b32_e64 v243, v245, v243, s[100:101]
	global_load_dword v238, v[242:243], off
	v_or_b32_e32 v240, 15, v51
	v_subrev_u32_e32 v246, s28, v240
	v_mad_i64_i32 v[244:245], s[100:101], s22, v240, 0
	v_lshl_add_u64 v[242:243], v[246:247], 2, s[26:27]
	v_cmp_le_i32_e64 s[100:101], s28, v240
	v_lshl_add_u64 v[244:245], v[244:245], 2, s[0:1]
	s_nop 1
	v_cndmask_b32_e64 v242, v244, v242, s[100:101]
	v_cndmask_b32_e64 v243, v245, v243, s[100:101]
	global_load_dword v239, v[242:243], off
	s_mov_b64 exec, s[98:99]
	s_waitcnt vmcnt(0)
	s_and_saveexec_b64 s[72:73], s[34:35]
	s_cbranch_execz .LBB0_6581
	v_cmp_le_i32_e32 vcc, s28, v51
	s_and_saveexec_b64 s[36:37], vcc
	s_xor_b64 s[74:75], exec, s[36:37]
	s_cbranch_execz .LBB0_6577
	v_subrev_u32_e32 v0, s28, v51
	v_lshl_add_u64 v[4:5], v[0:1], 2, s[26:27]
	v_mov_b32_e32 v0, v224
	s_waitcnt vmcnt(0)
	v_mul_f32_e64 v4, |v0|, s89
	v_exp_f32_e32 v4, v4
	v_max_f32_e32 v0, v0, v0
	v_min_f32_e32 v0, 0, v0
	v_add_f32_e32 v4, 1.0, v4
	v_cmp_gt_f32_e32 vcc, s90, v4
	s_nop 1
	v_cndmask_b32_e64 v5, 0, 32, vcc
	v_ldexp_f32 v4, v4, v5
	v_log_f32_e32 v4, v4
	s_nop 0
	v_mul_f32_e32 v5, 0x3f317217, v4
	v_fma_f32 v5, v4, s91, -v5
	v_fmac_f32_e32 v5, 0x3377d1cf, v4
	v_fmac_f32_e32 v5, 0x3f317217, v4
	v_cmp_lt_f32_e64 s[36:37], |v4|, s92
	s_nop 1
	v_cndmask_b32_e64 v4, v4, v5, s[36:37]
	v_cndmask_b32_e32 v5, 0, v203, vcc
	v_sub_f32_e32 v4, v4, v5
	v_sub_f32_e32 v6, v0, v4
.LBB0_6577:
	s_andn2_saveexec_b64 s[74:75], s[74:75]
	s_cbranch_execz .LBB0_6580
	v_mad_i64_i32 v[4:5], s[36:37], s22, v51, 0
	v_lshl_add_u64 v[4:5], v[4:5], 2, s[0:1]
	v_mov_b32_e32 v6, v224
	s_andn2_b64 vcc, exec, s[70:71]
	s_cbranch_vccnz .LBB0_6580
	s_waitcnt vmcnt(0)
	v_mul_f32_e64 v0, |v6|, s89
	v_exp_f32_e32 v0, v0
	s_nop 0
	v_add_f32_e32 v0, 1.0, v0
	v_cmp_gt_f32_e32 vcc, s90, v0
	s_nop 1
	v_cndmask_b32_e64 v4, 0, 32, vcc
	v_ldexp_f32 v0, v0, v4
	v_log_f32_e32 v0, v0
	v_max_f32_e32 v4, v6, v6
	v_min_f32_e32 v4, 0, v4
	v_mul_f32_e32 v5, 0x3f317217, v0
	v_fma_f32 v5, v0, s91, -v5
	v_fmac_f32_e32 v5, 0x3377d1cf, v0
	v_fmac_f32_e32 v5, 0x3f317217, v0
	v_cmp_lt_f32_e64 s[36:37], |v0|, s92
	s_nop 1
	v_cndmask_b32_e64 v0, v0, v5, s[36:37]
	v_cndmask_b32_e32 v5, 0, v203, vcc
	v_sub_f32_e32 v0, v0, v5
	v_sub_f32_e32 v6, v4, v0

.LBB0_6581:
	s_or_b64 exec, exec, s[72:73]
	v_or_b32_e32 v52, 1, v51
	s_and_saveexec_b64 s[72:73], s[34:35]
	s_cbranch_execz .LBB0_6588
	v_cmp_le_i32_e32 vcc, s28, v52
	s_and_saveexec_b64 s[36:37], vcc
	s_xor_b64 s[74:75], exec, s[36:37]
	s_cbranch_execz .LBB0_6584
	v_subrev_u32_e32 v0, s28, v52
	v_lshl_add_u64 v[4:5], v[0:1], 2, s[26:27]
	v_mov_b32_e32 v0, v225
	s_waitcnt vmcnt(0)
	v_mul_f32_e64 v3, |v0|, s89
	v_exp_f32_e32 v3, v3
	v_max_f32_e32 v0, v0, v0
	v_min_f32_e32 v0, 0, v0
	v_add_f32_e32 v3, 1.0, v3
	v_cmp_gt_f32_e32 vcc, s90, v3
	s_nop 1
	v_cndmask_b32_e64 v4, 0, 32, vcc
	v_ldexp_f32 v3, v3, v4
	v_log_f32_e32 v3, v3
	s_nop 0
	v_mul_f32_e32 v4, 0x3f317217, v3
	v_fma_f32 v4, v3, s91, -v4
	v_fmac_f32_e32 v4, 0x3377d1cf, v3
	v_fmac_f32_e32 v4, 0x3f317217, v3
	v_cmp_lt_f32_e64 s[36:37], |v3|, s92
	s_nop 1
	v_cndmask_b32_e64 v3, v3, v4, s[36:37]
	v_cndmask_b32_e32 v4, 0, v203, vcc
	v_sub_f32_e32 v3, v3, v4
	v_sub_f32_e32 v3, v0, v3
.LBB0_6584:
	s_andn2_saveexec_b64 s[74:75], s[74:75]
	s_cbranch_execz .LBB0_6587
	v_mad_i64_i32 v[4:5], s[36:37], s22, v52, 0
	v_lshl_add_u64 v[4:5], v[4:5], 2, s[0:1]
	v_mov_b32_e32 v3, v225
	s_andn2_b64 vcc, exec, s[70:71]
	s_cbranch_vccnz .LBB0_6587
	s_waitcnt vmcnt(0)
	v_mul_f32_e64 v0, |v3|, s89
	v_exp_f32_e32 v0, v0
	v_max_f32_e32 v3, v3, v3
	v_min_f32_e32 v3, 0, v3
	v_add_f32_e32 v0, 1.0, v0
	v_cmp_gt_f32_e32 vcc, s90, v0
	s_nop 1
	v_cndmask_b32_e64 v4, 0, 32, vcc
	v_ldexp_f32 v0, v0, v4
	v_log_f32_e32 v0, v0
	s_nop 0
	v_mul_f32_e32 v4, 0x3f317217, v0
	v_fma_f32 v4, v0, s91, -v4
	v_fmac_f32_e32 v4, 0x3377d1cf, v0
	v_fmac_f32_e32 v4, 0x3f317217, v0
	v_cmp_lt_f32_e64 s[36:37], |v0|, s92
	s_nop 1
	v_cndmask_b32_e64 v0, v0, v4, s[36:37]
	v_cndmask_b32_e32 v4, 0, v203, vcc
	v_sub_f32_e32 v0, v0, v4
	v_sub_f32_e32 v3, v3, v0

.LBB0_6588:
	s_or_b64 exec, exec, s[72:73]
	v_or_b32_e32 v53, 2, v51
	v_mov_b32_e32 v5, 0
	v_mov_b32_e32 v4, 0
	s_and_saveexec_b64 s[72:73], s[34:35]
	s_cbranch_execz .LBB0_6595
	v_cmp_le_i32_e32 vcc, s28, v53
	s_and_saveexec_b64 s[36:37], vcc
	s_xor_b64 s[74:75], exec, s[36:37]
	s_cbranch_execz .LBB0_6591
	v_subrev_u32_e32 v0, s28, v53
	v_lshl_add_u64 v[8:9], v[0:1], 2, s[26:27]
	v_mov_b32_e32 v0, v226
	s_waitcnt vmcnt(0)
	v_mul_f32_e64 v4, |v0|, s89
	v_exp_f32_e32 v4, v4
	v_max_f32_e32 v0, v0, v0
	v_min_f32_e32 v0, 0, v0
	v_add_f32_e32 v4, 1.0, v4
	v_cmp_gt_f32_e32 vcc, s90, v4
	s_nop 1
	v_cndmask_b32_e64 v7, 0, 32, vcc
	v_ldexp_f32 v4, v4, v7
	v_log_f32_e32 v4, v4
	s_nop 0
	v_mul_f32_e32 v7, 0x3f317217, v4
	v_fma_f32 v7, v4, s91, -v7
	v_fmac_f32_e32 v7, 0x3377d1cf, v4
	v_fmac_f32_e32 v7, 0x3f317217, v4
	v_cmp_lt_f32_e64 s[36:37], |v4|, s92
	s_nop 1
	v_cndmask_b32_e64 v4, v4, v7, s[36:37]
	v_cndmask_b32_e32 v7, 0, v203, vcc
	v_sub_f32_e32 v4, v4, v7
	v_sub_f32_e32 v4, v0, v4
.LBB0_6591:
	s_andn2_saveexec_b64 s[74:75], s[74:75]
	s_cbranch_execz .LBB0_6594
	v_mad_i64_i32 v[8:9], s[36:37], s22, v53, 0
	v_lshl_add_u64 v[8:9], v[8:9], 2, s[0:1]
	v_mov_b32_e32 v4, v226
	s_andn2_b64 vcc, exec, s[70:71]
	s_cbranch_vccnz .LBB0_6594
	s_waitcnt vmcnt(0)
	v_mul_f32_e64 v0, |v4|, s89
	v_exp_f32_e32 v0, v0
	v_max_f32_e32 v4, v4, v4
	v_min_f32_e32 v4, 0, v4
	v_add_f32_e32 v0, 1.0, v0
	v_cmp_gt_f32_e32 vcc, s90, v0
	s_nop 1
	v_cndmask_b32_e64 v7, 0, 32, vcc
	v_ldexp_f32 v0, v0, v7
	v_log_f32_e32 v0, v0
	s_nop 0
	v_mul_f32_e32 v7, 0x3f317217, v0
	v_fma_f32 v7, v0, s91, -v7
	v_fmac_f32_e32 v7, 0x3377d1cf, v0
	v_fmac_f32_e32 v7, 0x3f317217, v0
	v_cmp_lt_f32_e64 s[36:37], |v0|, s92
	s_nop 1
	v_cndmask_b32_e64 v0, v0, v7, s[36:37]
	v_cndmask_b32_e32 v7, 0, v203, vcc
	v_sub_f32_e32 v0, v0, v7
	v_sub_f32_e32 v4, v4, v0

.LBB0_6595:
	s_or_b64 exec, exec, s[72:73]
	v_or_b32_e32 v54, 3, v51
	s_and_saveexec_b64 s[72:73], s[34:35]
	s_cbranch_execz .LBB0_6602
	v_cmp_le_i32_e32 vcc, s28, v54
	s_and_saveexec_b64 s[36:37], vcc
	s_xor_b64 s[74:75], exec, s[36:37]
	s_cbranch_execz .LBB0_6598
	v_subrev_u32_e32 v0, s28, v54
	v_lshl_add_u64 v[8:9], v[0:1], 2, s[26:27]
	v_mov_b32_e32 v0, v227
	s_waitcnt vmcnt(0)
	v_mul_f32_e64 v5, |v0|, s89
	v_exp_f32_e32 v5, v5
	v_max_f32_e32 v0, v0, v0
	v_min_f32_e32 v0, 0, v0
	v_add_f32_e32 v5, 1.0, v5
	v_cmp_gt_f32_e32 vcc, s90, v5
	s_nop 1
	v_cndmask_b32_e64 v7, 0, 32, vcc
	v_ldexp_f32 v5, v5, v7
	v_log_f32_e32 v5, v5
	s_nop 0
	v_mul_f32_e32 v7, 0x3f317217, v5
	v_fma_f32 v7, v5, s91, -v7
	v_fmac_f32_e32 v7, 0x3377d1cf, v5
	v_fmac_f32_e32 v7, 0x3f317217, v5
	v_cmp_lt_f32_e64 s[36:37], |v5|, s92
	s_nop 1
	v_cndmask_b32_e64 v5, v5, v7, s[36:37]
	v_cndmask_b32_e32 v7, 0, v203, vcc
	v_sub_f32_e32 v5, v5, v7
	v_sub_f32_e32 v5, v0, v5
.LBB0_6598:
	s_andn2_saveexec_b64 s[74:75], s[74:75]
	s_cbranch_execz .LBB0_6601
	v_mad_i64_i32 v[8:9], s[36:37], s22, v54, 0
	v_lshl_add_u64 v[8:9], v[8:9], 2, s[0:1]
	v_mov_b32_e32 v5, v227
	s_andn2_b64 vcc, exec, s[70:71]
	s_cbranch_vccnz .LBB0_6601
	s_waitcnt vmcnt(0)
	v_mul_f32_e64 v0, |v5|, s89
	v_exp_f32_e32 v0, v0
	v_max_f32_e32 v5, v5, v5
	v_min_f32_e32 v5, 0, v5
	v_add_f32_e32 v0, 1.0, v0
	v_cmp_gt_f32_e32 vcc, s90, v0
	s_nop 1
	v_cndmask_b32_e64 v7, 0, 32, vcc
	v_ldexp_f32 v0, v0, v7
	v_log_f32_e32 v0, v0
	s_nop 0
	v_mul_f32_e32 v7, 0x3f317217, v0
	v_fma_f32 v7, v0, s91, -v7
	v_fmac_f32_e32 v7, 0x3377d1cf, v0
	v_fmac_f32_e32 v7, 0x3f317217, v0
	v_cmp_lt_f32_e64 s[36:37], |v0|, s92
	s_nop 1
	v_cndmask_b32_e64 v0, v0, v7, s[36:37]
	v_cndmask_b32_e32 v7, 0, v203, vcc
	v_sub_f32_e32 v0, v0, v7
	v_sub_f32_e32 v5, v5, v0

.LBB0_6602:
	s_or_b64 exec, exec, s[72:73]
	v_or_b32_e32 v55, 4, v51
	v_mov_b32_e32 v8, 0
	v_mov_b32_e32 v7, 0
	s_and_saveexec_b64 s[72:73], s[34:35]
	s_cbranch_execz .LBB0_6609
	v_cmp_le_i32_e32 vcc, s28, v55
	s_and_saveexec_b64 s[36:37], vcc
	s_xor_b64 s[74:75], exec, s[36:37]
	s_cbranch_execz .LBB0_6605
	v_subrev_u32_e32 v0, s28, v55
	v_lshl_add_u64 v[10:11], v[0:1], 2, s[26:27]
	v_mov_b32_e32 v0, v228
	s_waitcnt vmcnt(0)
	v_mul_f32_e64 v7, |v0|, s89
	v_exp_f32_e32 v7, v7
	v_max_f32_e32 v0, v0, v0
	v_min_f32_e32 v0, 0, v0
	v_add_f32_e32 v7, 1.0, v7
	v_cmp_gt_f32_e32 vcc, s90, v7
	s_nop 1
	v_cndmask_b32_e64 v9, 0, 32, vcc
	v_ldexp_f32 v7, v7, v9
	v_log_f32_e32 v7, v7
	s_nop 0
	v_mul_f32_e32 v9, 0x3f317217, v7
	v_fma_f32 v9, v7, s91, -v9
	v_fmac_f32_e32 v9, 0x3377d1cf, v7
	v_fmac_f32_e32 v9, 0x3f317217, v7
	v_cmp_lt_f32_e64 s[36:37], |v7|, s92
	s_nop 1
	v_cndmask_b32_e64 v7, v7, v9, s[36:37]
	v_cndmask_b32_e32 v9, 0, v203, vcc
	v_sub_f32_e32 v7, v7, v9
	v_sub_f32_e32 v7, v0, v7
.LBB0_6605:
	s_andn2_saveexec_b64 s[74:75], s[74:75]
	s_cbranch_execz .LBB0_6608
	v_mad_i64_i32 v[10:11], s[36:37], s22, v55, 0
	v_lshl_add_u64 v[10:11], v[10:11], 2, s[0:1]
	v_mov_b32_e32 v7, v228
	s_andn2_b64 vcc, exec, s[70:71]
	s_cbranch_vccnz .LBB0_6608
	s_waitcnt vmcnt(0)
	v_mul_f32_e64 v0, |v7|, s89
	v_exp_f32_e32 v0, v0
	v_max_f32_e32 v7, v7, v7
	v_min_f32_e32 v7, 0, v7
	v_add_f32_e32 v0, 1.0, v0
	v_cmp_gt_f32_e32 vcc, s90, v0
	s_nop 1
	v_cndmask_b32_e64 v9, 0, 32, vcc
	v_ldexp_f32 v0, v0, v9
	v_log_f32_e32 v0, v0
	s_nop 0
	v_mul_f32_e32 v9, 0x3f317217, v0
	v_fma_f32 v9, v0, s91, -v9
	v_fmac_f32_e32 v9, 0x3377d1cf, v0
	v_fmac_f32_e32 v9, 0x3f317217, v0
	v_cmp_lt_f32_e64 s[36:37], |v0|, s92
	s_nop 1
	v_cndmask_b32_e64 v0, v0, v9, s[36:37]
	v_cndmask_b32_e32 v9, 0, v203, vcc
	v_sub_f32_e32 v0, v0, v9
	v_sub_f32_e32 v7, v7, v0

.LBB0_6609:
	s_or_b64 exec, exec, s[72:73]
	v_or_b32_e32 v56, 5, v51
	s_and_saveexec_b64 s[72:73], s[34:35]
	s_cbranch_execz .LBB0_6616
	v_cmp_le_i32_e32 vcc, s28, v56
	s_and_saveexec_b64 s[36:37], vcc
	s_xor_b64 s[74:75], exec, s[36:37]
	s_cbranch_execz .LBB0_6612
	v_subrev_u32_e32 v0, s28, v56
	v_lshl_add_u64 v[8:9], v[0:1], 2, s[26:27]
	v_mov_b32_e32 v0, v229
	s_waitcnt vmcnt(0)
	v_mul_f32_e64 v8, |v0|, s89
	v_exp_f32_e32 v8, v8
	v_max_f32_e32 v0, v0, v0
	v_min_f32_e32 v0, 0, v0
	v_add_f32_e32 v8, 1.0, v8
	v_cmp_gt_f32_e32 vcc, s90, v8
	s_nop 1
	v_cndmask_b32_e64 v9, 0, 32, vcc
	v_ldexp_f32 v8, v8, v9
	v_log_f32_e32 v8, v8
	s_nop 0
	v_mul_f32_e32 v9, 0x3f317217, v8
	v_fma_f32 v9, v8, s91, -v9
	v_fmac_f32_e32 v9, 0x3377d1cf, v8
	v_fmac_f32_e32 v9, 0x3f317217, v8
	v_cmp_lt_f32_e64 s[36:37], |v8|, s92
	s_nop 1
	v_cndmask_b32_e64 v8, v8, v9, s[36:37]
	v_cndmask_b32_e32 v9, 0, v203, vcc
	v_sub_f32_e32 v8, v8, v9
	v_sub_f32_e32 v8, v0, v8
.LBB0_6612:
	s_andn2_saveexec_b64 s[74:75], s[74:75]
	s_cbranch_execz .LBB0_6615
	v_mad_i64_i32 v[8:9], s[36:37], s22, v56, 0
	v_lshl_add_u64 v[8:9], v[8:9], 2, s[0:1]
	v_mov_b32_e32 v8, v229
	s_andn2_b64 vcc, exec, s[70:71]
	s_cbranch_vccnz .LBB0_6615
	s_waitcnt vmcnt(0)
	v_mul_f32_e64 v0, |v8|, s89
	v_exp_f32_e32 v0, v0
	v_max_f32_e32 v8, v8, v8
	v_min_f32_e32 v8, 0, v8
	v_add_f32_e32 v0, 1.0, v0
	v_cmp_gt_f32_e32 vcc, s90, v0
	s_nop 1
	v_cndmask_b32_e64 v9, 0, 32, vcc
	v_ldexp_f32 v0, v0, v9
	v_log_f32_e32 v0, v0
	s_nop 0
	v_mul_f32_e32 v9, 0x3f317217, v0
	v_fma_f32 v9, v0, s91, -v9
	v_fmac_f32_e32 v9, 0x3377d1cf, v0
	v_fmac_f32_e32 v9, 0x3f317217, v0
	v_cmp_lt_f32_e64 s[36:37], |v0|, s92
	s_nop 1
	v_cndmask_b32_e64 v0, v0, v9, s[36:37]
	v_cndmask_b32_e32 v9, 0, v203, vcc
	v_sub_f32_e32 v0, v0, v9
	v_sub_f32_e32 v8, v8, v0

.LBB0_6616:
	s_or_b64 exec, exec, s[72:73]
	v_or_b32_e32 v57, 6, v51
	v_mov_b32_e32 v10, 0
	v_mov_b32_e32 v9, 0
	s_and_saveexec_b64 s[72:73], s[34:35]
	s_cbranch_execz .LBB0_6623
	v_cmp_le_i32_e32 vcc, s28, v57
	s_and_saveexec_b64 s[36:37], vcc
	s_xor_b64 s[74:75], exec, s[36:37]
	s_cbranch_execz .LBB0_6619
	v_subrev_u32_e32 v0, s28, v57
	v_lshl_add_u64 v[12:13], v[0:1], 2, s[26:27]
	v_mov_b32_e32 v0, v230
	s_waitcnt vmcnt(0)
	v_mul_f32_e64 v9, |v0|, s89
	v_exp_f32_e32 v9, v9
	v_max_f32_e32 v0, v0, v0
	v_min_f32_e32 v0, 0, v0
	v_add_f32_e32 v9, 1.0, v9
	v_cmp_gt_f32_e32 vcc, s90, v9
	s_nop 1
	v_cndmask_b32_e64 v11, 0, 32, vcc
	v_ldexp_f32 v9, v9, v11
	v_log_f32_e32 v9, v9
	s_nop 0
	v_mul_f32_e32 v11, 0x3f317217, v9
	v_fma_f32 v11, v9, s91, -v11
	v_fmac_f32_e32 v11, 0x3377d1cf, v9
	v_fmac_f32_e32 v11, 0x3f317217, v9
	v_cmp_lt_f32_e64 s[36:37], |v9|, s92
	s_nop 1
	v_cndmask_b32_e64 v9, v9, v11, s[36:37]
	v_cndmask_b32_e32 v11, 0, v203, vcc
	v_sub_f32_e32 v9, v9, v11
	v_sub_f32_e32 v9, v0, v9
.LBB0_6619:
	s_andn2_saveexec_b64 s[74:75], s[74:75]
	s_cbranch_execz .LBB0_6622
	v_mad_i64_i32 v[12:13], s[36:37], s22, v57, 0
	v_lshl_add_u64 v[12:13], v[12:13], 2, s[0:1]
	v_mov_b32_e32 v9, v230
	s_andn2_b64 vcc, exec, s[70:71]
	s_cbranch_vccnz .LBB0_6622
	s_waitcnt vmcnt(0)
	v_mul_f32_e64 v0, |v9|, s89
	v_exp_f32_e32 v0, v0
	v_max_f32_e32 v9, v9, v9
	v_min_f32_e32 v9, 0, v9
	v_add_f32_e32 v0, 1.0, v0
	v_cmp_gt_f32_e32 vcc, s90, v0
	s_nop 1
	v_cndmask_b32_e64 v11, 0, 32, vcc
	v_ldexp_f32 v0, v0, v11
	v_log_f32_e32 v0, v0
	s_nop 0
	v_mul_f32_e32 v11, 0x3f317217, v0
	v_fma_f32 v11, v0, s91, -v11
	v_fmac_f32_e32 v11, 0x3377d1cf, v0
	v_fmac_f32_e32 v11, 0x3f317217, v0
	v_cmp_lt_f32_e64 s[36:37], |v0|, s92
	s_nop 1
	v_cndmask_b32_e64 v0, v0, v11, s[36:37]
	v_cndmask_b32_e32 v11, 0, v203, vcc
	v_sub_f32_e32 v0, v0, v11
	v_sub_f32_e32 v9, v9, v0

.LBB0_6623:
	s_or_b64 exec, exec, s[72:73]
	v_or_b32_e32 v58, 7, v51
	s_and_saveexec_b64 s[72:73], s[34:35]
	s_cbranch_execz .LBB0_6630
	v_cmp_le_i32_e32 vcc, s28, v58
	s_and_saveexec_b64 s[36:37], vcc
	s_xor_b64 s[74:75], exec, s[36:37]
	s_cbranch_execz .LBB0_6626
	v_subrev_u32_e32 v0, s28, v58
	v_lshl_add_u64 v[10:11], v[0:1], 2, s[26:27]
	v_mov_b32_e32 v0, v231
	s_waitcnt vmcnt(0)
	v_mul_f32_e64 v10, |v0|, s89
	v_exp_f32_e32 v10, v10
	v_max_f32_e32 v0, v0, v0
	v_min_f32_e32 v0, 0, v0
	v_add_f32_e32 v10, 1.0, v10
	v_cmp_gt_f32_e32 vcc, s90, v10
	s_nop 1
	v_cndmask_b32_e64 v11, 0, 32, vcc
	v_ldexp_f32 v10, v10, v11
	v_log_f32_e32 v10, v10
	s_nop 0
	v_mul_f32_e32 v11, 0x3f317217, v10
	v_fma_f32 v11, v10, s91, -v11
	v_fmac_f32_e32 v11, 0x3377d1cf, v10
	v_fmac_f32_e32 v11, 0x3f317217, v10
	v_cmp_lt_f32_e64 s[36:37], |v10|, s92
	s_nop 1
	v_cndmask_b32_e64 v10, v10, v11, s[36:37]
	v_cndmask_b32_e32 v11, 0, v203, vcc
	v_sub_f32_e32 v10, v10, v11
	v_sub_f32_e32 v10, v0, v10
.LBB0_6626:
	s_andn2_saveexec_b64 s[74:75], s[74:75]
	s_cbranch_execz .LBB0_6629
	v_mad_i64_i32 v[10:11], s[36:37], s22, v58, 0
	v_lshl_add_u64 v[10:11], v[10:11], 2, s[0:1]
	v_mov_b32_e32 v10, v231
	s_andn2_b64 vcc, exec, s[70:71]
	s_cbranch_vccnz .LBB0_6629
	s_waitcnt vmcnt(0)
	v_mul_f32_e64 v0, |v10|, s89
	v_exp_f32_e32 v0, v0
	v_max_f32_e32 v10, v10, v10
	v_min_f32_e32 v10, 0, v10
	v_add_f32_e32 v0, 1.0, v0
	v_cmp_gt_f32_e32 vcc, s90, v0
	s_nop 1
	v_cndmask_b32_e64 v11, 0, 32, vcc
	v_ldexp_f32 v0, v0, v11
	v_log_f32_e32 v0, v0
	s_nop 0
	v_mul_f32_e32 v11, 0x3f317217, v0
	v_fma_f32 v11, v0, s91, -v11
	v_fmac_f32_e32 v11, 0x3377d1cf, v0
	v_fmac_f32_e32 v11, 0x3f317217, v0
	v_cmp_lt_f32_e64 s[36:37], |v0|, s92
	s_nop 1
	v_cndmask_b32_e64 v0, v0, v11, s[36:37]
	v_cndmask_b32_e32 v11, 0, v203, vcc
	v_sub_f32_e32 v0, v0, v11
	v_sub_f32_e32 v10, v10, v0

.LBB0_6630:
	s_or_b64 exec, exec, s[72:73]
	v_or_b32_e32 v59, 8, v51
	v_mov_b32_e32 v12, 0
	v_mov_b32_e32 v11, 0
	s_and_saveexec_b64 s[72:73], s[34:35]
	s_cbranch_execz .LBB0_6637
	v_cmp_le_i32_e32 vcc, s28, v59
	s_and_saveexec_b64 s[36:37], vcc
	s_xor_b64 s[74:75], exec, s[36:37]
	s_cbranch_execz .LBB0_6633
	v_subrev_u32_e32 v0, s28, v59
	v_lshl_add_u64 v[14:15], v[0:1], 2, s[26:27]
	v_mov_b32_e32 v0, v232
	s_waitcnt vmcnt(0)
	v_mul_f32_e64 v11, |v0|, s89
	v_exp_f32_e32 v11, v11
	v_max_f32_e32 v0, v0, v0
	v_min_f32_e32 v0, 0, v0
	v_add_f32_e32 v11, 1.0, v11
	v_cmp_gt_f32_e32 vcc, s90, v11
	s_nop 1
	v_cndmask_b32_e64 v13, 0, 32, vcc
	v_ldexp_f32 v11, v11, v13
	v_log_f32_e32 v11, v11
	s_nop 0
	v_mul_f32_e32 v13, 0x3f317217, v11
	v_fma_f32 v13, v11, s91, -v13
	v_fmac_f32_e32 v13, 0x3377d1cf, v11
	v_fmac_f32_e32 v13, 0x3f317217, v11
	v_cmp_lt_f32_e64 s[36:37], |v11|, s92
	s_nop 1
	v_cndmask_b32_e64 v11, v11, v13, s[36:37]
	v_cndmask_b32_e32 v13, 0, v203, vcc
	v_sub_f32_e32 v11, v11, v13
	v_sub_f32_e32 v11, v0, v11
.LBB0_6633:
	s_andn2_saveexec_b64 s[74:75], s[74:75]
	s_cbranch_execz .LBB0_6636
	v_mad_i64_i32 v[14:15], s[36:37], s22, v59, 0
	v_lshl_add_u64 v[14:15], v[14:15], 2, s[0:1]
	v_mov_b32_e32 v11, v232
	s_andn2_b64 vcc, exec, s[70:71]
	s_cbranch_vccnz .LBB0_6636
	s_waitcnt vmcnt(0)
	v_mul_f32_e64 v0, |v11|, s89
	v_exp_f32_e32 v0, v0
	v_max_f32_e32 v11, v11, v11
	v_min_f32_e32 v11, 0, v11
	v_add_f32_e32 v0, 1.0, v0
	v_cmp_gt_f32_e32 vcc, s90, v0
	s_nop 1
	v_cndmask_b32_e64 v13, 0, 32, vcc
	v_ldexp_f32 v0, v0, v13
	v_log_f32_e32 v0, v0
	s_nop 0
	v_mul_f32_e32 v13, 0x3f317217, v0
	v_fma_f32 v13, v0, s91, -v13
	v_fmac_f32_e32 v13, 0x3377d1cf, v0
	v_fmac_f32_e32 v13, 0x3f317217, v0
	v_cmp_lt_f32_e64 s[36:37], |v0|, s92
	s_nop 1
	v_cndmask_b32_e64 v0, v0, v13, s[36:37]
	v_cndmask_b32_e32 v13, 0, v203, vcc
	v_sub_f32_e32 v0, v0, v13
	v_sub_f32_e32 v11, v11, v0

.LBB0_6637:
	s_or_b64 exec, exec, s[72:73]
	v_or_b32_e32 v61, 9, v51
	s_and_saveexec_b64 s[72:73], s[34:35]
	s_cbranch_execz .LBB0_6644
	v_cmp_le_i32_e32 vcc, s28, v61
	s_and_saveexec_b64 s[36:37], vcc
	s_xor_b64 s[74:75], exec, s[36:37]
	s_cbranch_execz .LBB0_6640
	v_subrev_u32_e32 v0, s28, v61
	v_lshl_add_u64 v[12:13], v[0:1], 2, s[26:27]
	v_mov_b32_e32 v0, v233
	s_waitcnt vmcnt(0)
	v_mul_f32_e64 v12, |v0|, s89
	v_exp_f32_e32 v12, v12
	v_max_f32_e32 v0, v0, v0
	v_min_f32_e32 v0, 0, v0
	v_add_f32_e32 v12, 1.0, v12
	v_cmp_gt_f32_e32 vcc, s90, v12
	s_nop 1
	v_cndmask_b32_e64 v13, 0, 32, vcc
	v_ldexp_f32 v12, v12, v13
	v_log_f32_e32 v12, v12
	s_nop 0
	v_mul_f32_e32 v13, 0x3f317217, v12
	v_fma_f32 v13, v12, s91, -v13
	v_fmac_f32_e32 v13, 0x3377d1cf, v12
	v_fmac_f32_e32 v13, 0x3f317217, v12
	v_cmp_lt_f32_e64 s[36:37], |v12|, s92
	s_nop 1
	v_cndmask_b32_e64 v12, v12, v13, s[36:37]
	v_cndmask_b32_e32 v13, 0, v203, vcc
	v_sub_f32_e32 v12, v12, v13
	v_sub_f32_e32 v12, v0, v12
.LBB0_6640:
	s_andn2_saveexec_b64 s[74:75], s[74:75]
	s_cbranch_execz .LBB0_6643
	v_mad_i64_i32 v[12:13], s[36:37], s22, v61, 0
	v_lshl_add_u64 v[12:13], v[12:13], 2, s[0:1]
	v_mov_b32_e32 v12, v233
	s_andn2_b64 vcc, exec, s[70:71]
	s_cbranch_vccnz .LBB0_6643
	s_waitcnt vmcnt(0)
	v_mul_f32_e64 v0, |v12|, s89
	v_exp_f32_e32 v0, v0
	v_max_f32_e32 v12, v12, v12
	v_min_f32_e32 v12, 0, v12
	v_add_f32_e32 v0, 1.0, v0
	v_cmp_gt_f32_e32 vcc, s90, v0
	s_nop 1
	v_cndmask_b32_e64 v13, 0, 32, vcc
	v_ldexp_f32 v0, v0, v13
	v_log_f32_e32 v0, v0
	s_nop 0
	v_mul_f32_e32 v13, 0x3f317217, v0
	v_fma_f32 v13, v0, s91, -v13
	v_fmac_f32_e32 v13, 0x3377d1cf, v0
	v_fmac_f32_e32 v13, 0x3f317217, v0
	v_cmp_lt_f32_e64 s[36:37], |v0|, s92
	s_nop 1
	v_cndmask_b32_e64 v0, v0, v13, s[36:37]
	v_cndmask_b32_e32 v13, 0, v203, vcc
	v_sub_f32_e32 v0, v0, v13
	v_sub_f32_e32 v12, v12, v0

.LBB0_6644:
	s_or_b64 exec, exec, s[72:73]
	v_or_b32_e32 v63, 10, v51
	v_mov_b32_e32 v14, 0
	v_mov_b32_e32 v13, 0
	s_and_saveexec_b64 s[72:73], s[34:35]
	s_cbranch_execz .LBB0_6651
	v_cmp_le_i32_e32 vcc, s28, v63
	s_and_saveexec_b64 s[36:37], vcc
	s_xor_b64 s[74:75], exec, s[36:37]
	s_cbranch_execz .LBB0_6647
	v_subrev_u32_e32 v0, s28, v63
	v_lshl_add_u64 v[16:17], v[0:1], 2, s[26:27]
	v_mov_b32_e32 v0, v234
	s_waitcnt vmcnt(0)
	v_mul_f32_e64 v13, |v0|, s89
	v_exp_f32_e32 v13, v13
	v_max_f32_e32 v0, v0, v0
	v_min_f32_e32 v0, 0, v0
	v_add_f32_e32 v13, 1.0, v13
	v_cmp_gt_f32_e32 vcc, s90, v13
	s_nop 1
	v_cndmask_b32_e64 v15, 0, 32, vcc
	v_ldexp_f32 v13, v13, v15
	v_log_f32_e32 v13, v13
	s_nop 0
	v_mul_f32_e32 v15, 0x3f317217, v13
	v_fma_f32 v15, v13, s91, -v15
	v_fmac_f32_e32 v15, 0x3377d1cf, v13
	v_fmac_f32_e32 v15, 0x3f317217, v13
	v_cmp_lt_f32_e64 s[36:37], |v13|, s92
	s_nop 1
	v_cndmask_b32_e64 v13, v13, v15, s[36:37]
	v_cndmask_b32_e32 v15, 0, v203, vcc
	v_sub_f32_e32 v13, v13, v15
	v_sub_f32_e32 v13, v0, v13
.LBB0_6647:
	s_andn2_saveexec_b64 s[74:75], s[74:75]
	s_cbranch_execz .LBB0_6650
	v_mad_i64_i32 v[16:17], s[36:37], s22, v63, 0
	v_lshl_add_u64 v[16:17], v[16:17], 2, s[0:1]
	v_mov_b32_e32 v13, v234
	s_andn2_b64 vcc, exec, s[70:71]
	s_cbranch_vccnz .LBB0_6650
	s_waitcnt vmcnt(0)
	v_mul_f32_e64 v0, |v13|, s89
	v_exp_f32_e32 v0, v0
	v_max_f32_e32 v13, v13, v13
	v_min_f32_e32 v13, 0, v13
	v_add_f32_e32 v0, 1.0, v0
	v_cmp_gt_f32_e32 vcc, s90, v0
	s_nop 1
	v_cndmask_b32_e64 v15, 0, 32, vcc
	v_ldexp_f32 v0, v0, v15
	v_log_f32_e32 v0, v0
	s_nop 0
	v_mul_f32_e32 v15, 0x3f317217, v0
	v_fma_f32 v15, v0, s91, -v15
	v_fmac_f32_e32 v15, 0x3377d1cf, v0
	v_fmac_f32_e32 v15, 0x3f317217, v0
	v_cmp_lt_f32_e64 s[36:37], |v0|, s92
	s_nop 1
	v_cndmask_b32_e64 v0, v0, v15, s[36:37]
	v_cndmask_b32_e32 v15, 0, v203, vcc
	v_sub_f32_e32 v0, v0, v15
	v_sub_f32_e32 v13, v13, v0

.LBB0_6651:
	s_or_b64 exec, exec, s[72:73]
	v_or_b32_e32 v64, 11, v51
	s_and_saveexec_b64 s[72:73], s[34:35]
	s_cbranch_execz .LBB0_6658
	v_cmp_le_i32_e32 vcc, s28, v64
	s_and_saveexec_b64 s[36:37], vcc
	s_xor_b64 s[74:75], exec, s[36:37]
	s_cbranch_execz .LBB0_6654
	v_subrev_u32_e32 v0, s28, v64
	v_lshl_add_u64 v[14:15], v[0:1], 2, s[26:27]
	v_mov_b32_e32 v0, v235
	s_waitcnt vmcnt(0)
	v_mul_f32_e64 v14, |v0|, s89
	v_exp_f32_e32 v14, v14
	v_max_f32_e32 v0, v0, v0
	v_min_f32_e32 v0, 0, v0
	v_add_f32_e32 v14, 1.0, v14
	v_cmp_gt_f32_e32 vcc, s90, v14
	s_nop 1
	v_cndmask_b32_e64 v15, 0, 32, vcc
	v_ldexp_f32 v14, v14, v15
	v_log_f32_e32 v14, v14
	s_nop 0
	v_mul_f32_e32 v15, 0x3f317217, v14
	v_fma_f32 v15, v14, s91, -v15
	v_fmac_f32_e32 v15, 0x3377d1cf, v14
	v_fmac_f32_e32 v15, 0x3f317217, v14
	v_cmp_lt_f32_e64 s[36:37], |v14|, s92
	s_nop 1
	v_cndmask_b32_e64 v14, v14, v15, s[36:37]
	v_cndmask_b32_e32 v15, 0, v203, vcc
	v_sub_f32_e32 v14, v14, v15
	v_sub_f32_e32 v14, v0, v14
.LBB0_6654:
	s_andn2_saveexec_b64 s[74:75], s[74:75]
	s_cbranch_execz .LBB0_6657
	v_mad_i64_i32 v[14:15], s[36:37], s22, v64, 0
	v_lshl_add_u64 v[14:15], v[14:15], 2, s[0:1]
	v_mov_b32_e32 v14, v235
	s_andn2_b64 vcc, exec, s[70:71]
	s_cbranch_vccnz .LBB0_6657
	s_waitcnt vmcnt(0)
	v_mul_f32_e64 v0, |v14|, s89
	v_exp_f32_e32 v0, v0
	v_max_f32_e32 v14, v14, v14
	v_min_f32_e32 v14, 0, v14
	v_add_f32_e32 v0, 1.0, v0
	v_cmp_gt_f32_e32 vcc, s90, v0
	s_nop 1
	v_cndmask_b32_e64 v15, 0, 32, vcc
	v_ldexp_f32 v0, v0, v15
	v_log_f32_e32 v0, v0
	s_nop 0
	v_mul_f32_e32 v15, 0x3f317217, v0
	v_fma_f32 v15, v0, s91, -v15
	v_fmac_f32_e32 v15, 0x3377d1cf, v0
	v_fmac_f32_e32 v15, 0x3f317217, v0
	v_cmp_lt_f32_e64 s[36:37], |v0|, s92
	s_nop 1
	v_cndmask_b32_e64 v0, v0, v15, s[36:37]
	v_cndmask_b32_e32 v15, 0, v203, vcc
	v_sub_f32_e32 v0, v0, v15
	v_sub_f32_e32 v14, v14, v0

.LBB0_6658:
	s_or_b64 exec, exec, s[72:73]
	v_or_b32_e32 v60, 12, v51
	v_mov_b32_e32 v16, 0
	v_mov_b32_e32 v15, 0
	s_and_saveexec_b64 s[72:73], s[34:35]
	s_cbranch_execz .LBB0_6665
	v_cmp_le_i32_e32 vcc, s28, v60
	s_and_saveexec_b64 s[36:37], vcc
	s_xor_b64 s[74:75], exec, s[36:37]
	s_cbranch_execz .LBB0_6661
	v_subrev_u32_e32 v0, s28, v60
	v_lshl_add_u64 v[18:19], v[0:1], 2, s[26:27]
	v_mov_b32_e32 v0, v236
	s_waitcnt vmcnt(0)
	v_mul_f32_e64 v15, |v0|, s89
	v_exp_f32_e32 v15, v15
	v_max_f32_e32 v0, v0, v0
	v_min_f32_e32 v0, 0, v0
	v_add_f32_e32 v15, 1.0, v15
	v_cmp_gt_f32_e32 vcc, s90, v15
	s_nop 1
	v_cndmask_b32_e64 v17, 0, 32, vcc
	v_ldexp_f32 v15, v15, v17
	v_log_f32_e32 v15, v15
	s_nop 0
	v_mul_f32_e32 v17, 0x3f317217, v15
	v_fma_f32 v17, v15, s91, -v17
	v_fmac_f32_e32 v17, 0x3377d1cf, v15
	v_fmac_f32_e32 v17, 0x3f317217, v15
	v_cmp_lt_f32_e64 s[36:37], |v15|, s92
	s_nop 1
	v_cndmask_b32_e64 v15, v15, v17, s[36:37]
	v_cndmask_b32_e32 v17, 0, v203, vcc
	v_sub_f32_e32 v15, v15, v17
	v_sub_f32_e32 v15, v0, v15
.LBB0_6661:
	s_andn2_saveexec_b64 s[74:75], s[74:75]
	s_cbranch_execz .LBB0_6664
	v_mad_i64_i32 v[18:19], s[36:37], s22, v60, 0
	v_lshl_add_u64 v[18:19], v[18:19], 2, s[0:1]
	v_mov_b32_e32 v15, v236
	s_andn2_b64 vcc, exec, s[70:71]
	s_cbranch_vccnz .LBB0_6664
	s_waitcnt vmcnt(0)
	v_mul_f32_e64 v0, |v15|, s89
	v_exp_f32_e32 v0, v0
	v_max_f32_e32 v15, v15, v15
	v_min_f32_e32 v15, 0, v15
	v_add_f32_e32 v0, 1.0, v0
	v_cmp_gt_f32_e32 vcc, s90, v0
	s_nop 1
	v_cndmask_b32_e64 v17, 0, 32, vcc
	v_ldexp_f32 v0, v0, v17
	v_log_f32_e32 v0, v0
	s_nop 0
	v_mul_f32_e32 v17, 0x3f317217, v0
	v_fma_f32 v17, v0, s91, -v17
	v_fmac_f32_e32 v17, 0x3377d1cf, v0
	v_fmac_f32_e32 v17, 0x3f317217, v0
	v_cmp_lt_f32_e64 s[36:37], |v0|, s92
	s_nop 1
	v_cndmask_b32_e64 v0, v0, v17, s[36:37]
	v_cndmask_b32_e32 v17, 0, v203, vcc
	v_sub_f32_e32 v0, v0, v17
	v_sub_f32_e32 v15, v15, v0

.LBB0_6665:
	s_or_b64 exec, exec, s[72:73]
	v_or_b32_e32 v62, 13, v51
	s_and_saveexec_b64 s[72:73], s[34:35]
	s_cbranch_execz .LBB0_6672
	v_cmp_le_i32_e32 vcc, s28, v62
	s_and_saveexec_b64 s[36:37], vcc
	s_xor_b64 s[74:75], exec, s[36:37]
	s_cbranch_execz .LBB0_6668
	v_subrev_u32_e32 v0, s28, v62
	v_lshl_add_u64 v[16:17], v[0:1], 2, s[26:27]
	v_mov_b32_e32 v0, v237
	s_waitcnt vmcnt(0)
	v_mul_f32_e64 v16, |v0|, s89
	v_exp_f32_e32 v16, v16
	v_max_f32_e32 v0, v0, v0
	v_min_f32_e32 v0, 0, v0
	v_add_f32_e32 v16, 1.0, v16
	v_cmp_gt_f32_e32 vcc, s90, v16
	s_nop 1
	v_cndmask_b32_e64 v17, 0, 32, vcc
	v_ldexp_f32 v16, v16, v17
	v_log_f32_e32 v16, v16
	s_nop 0
	v_mul_f32_e32 v17, 0x3f317217, v16
	v_fma_f32 v17, v16, s91, -v17
	v_fmac_f32_e32 v17, 0x3377d1cf, v16
	v_fmac_f32_e32 v17, 0x3f317217, v16
	v_cmp_lt_f32_e64 s[36:37], |v16|, s92
	s_nop 1
	v_cndmask_b32_e64 v16, v16, v17, s[36:37]
	v_cndmask_b32_e32 v17, 0, v203, vcc
	v_sub_f32_e32 v16, v16, v17
	v_sub_f32_e32 v16, v0, v16
.LBB0_6668:
	s_andn2_saveexec_b64 s[74:75], s[74:75]
	s_cbranch_execz .LBB0_6671
	v_mad_i64_i32 v[16:17], s[36:37], s22, v62, 0
	v_lshl_add_u64 v[16:17], v[16:17], 2, s[0:1]
	v_mov_b32_e32 v16, v237
	s_andn2_b64 vcc, exec, s[70:71]
	s_cbranch_vccnz .LBB0_6671
	s_waitcnt vmcnt(0)
	v_mul_f32_e64 v0, |v16|, s89
	v_exp_f32_e32 v0, v0
	v_max_f32_e32 v16, v16, v16
	v_min_f32_e32 v16, 0, v16
	v_add_f32_e32 v0, 1.0, v0
	v_cmp_gt_f32_e32 vcc, s90, v0
	s_nop 1
	v_cndmask_b32_e64 v17, 0, 32, vcc
	v_ldexp_f32 v0, v0, v17
	v_log_f32_e32 v0, v0
	s_nop 0
	v_mul_f32_e32 v17, 0x3f317217, v0
	v_fma_f32 v17, v0, s91, -v17
	v_fmac_f32_e32 v17, 0x3377d1cf, v0
	v_fmac_f32_e32 v17, 0x3f317217, v0
	v_cmp_lt_f32_e64 s[36:37], |v0|, s92
	s_nop 1
	v_cndmask_b32_e64 v0, v0, v17, s[36:37]
	v_cndmask_b32_e32 v17, 0, v203, vcc
	v_sub_f32_e32 v0, v0, v17
	v_sub_f32_e32 v16, v16, v0

.LBB0_6672:
	s_or_b64 exec, exec, s[72:73]
	v_or_b32_e32 v65, 14, v51
	v_mov_b32_e32 v18, 0
	v_mov_b32_e32 v17, 0
	s_and_saveexec_b64 s[72:73], s[34:35]
	s_cbranch_execz .LBB0_6679
	v_cmp_le_i32_e32 vcc, s28, v65
	s_and_saveexec_b64 s[36:37], vcc
	s_xor_b64 s[74:75], exec, s[36:37]
	s_cbranch_execz .LBB0_6675
	v_subrev_u32_e32 v0, s28, v65
	v_lshl_add_u64 v[20:21], v[0:1], 2, s[26:27]
	v_mov_b32_e32 v0, v238
	s_waitcnt vmcnt(0)
	v_mul_f32_e64 v17, |v0|, s89
	v_exp_f32_e32 v17, v17
	v_max_f32_e32 v0, v0, v0
	v_min_f32_e32 v0, 0, v0
	v_add_f32_e32 v17, 1.0, v17
	v_cmp_gt_f32_e32 vcc, s90, v17
	s_nop 1
	v_cndmask_b32_e64 v19, 0, 32, vcc
	v_ldexp_f32 v17, v17, v19
	v_log_f32_e32 v17, v17
	s_nop 0
	v_mul_f32_e32 v19, 0x3f317217, v17
	v_fma_f32 v19, v17, s91, -v19
	v_fmac_f32_e32 v19, 0x3377d1cf, v17
	v_fmac_f32_e32 v19, 0x3f317217, v17
	v_cmp_lt_f32_e64 s[36:37], |v17|, s92
	s_nop 1
	v_cndmask_b32_e64 v17, v17, v19, s[36:37]
	v_cndmask_b32_e32 v19, 0, v203, vcc
	v_sub_f32_e32 v17, v17, v19
	v_sub_f32_e32 v17, v0, v17
.LBB0_6675:
	s_andn2_saveexec_b64 s[74:75], s[74:75]
	s_cbranch_execz .LBB0_6678
	v_mad_i64_i32 v[20:21], s[36:37], s22, v65, 0
	v_lshl_add_u64 v[20:21], v[20:21], 2, s[0:1]
	v_mov_b32_e32 v17, v238
	s_andn2_b64 vcc, exec, s[70:71]
	s_cbranch_vccnz .LBB0_6678
	s_waitcnt vmcnt(0)
	v_mul_f32_e64 v0, |v17|, s89
	v_exp_f32_e32 v0, v0
	v_max_f32_e32 v17, v17, v17
	v_min_f32_e32 v17, 0, v17
	v_add_f32_e32 v0, 1.0, v0
	v_cmp_gt_f32_e32 vcc, s90, v0
	s_nop 1
	v_cndmask_b32_e64 v19, 0, 32, vcc
	v_ldexp_f32 v0, v0, v19
	v_log_f32_e32 v0, v0
	s_nop 0
	v_mul_f32_e32 v19, 0x3f317217, v0
	v_fma_f32 v19, v0, s91, -v19
	v_fmac_f32_e32 v19, 0x3377d1cf, v0
	v_fmac_f32_e32 v19, 0x3f317217, v0
	v_cmp_lt_f32_e64 s[36:37], |v0|, s92
	s_nop 1
	v_cndmask_b32_e64 v0, v0, v19, s[36:37]
	v_cndmask_b32_e32 v19, 0, v203, vcc
	v_sub_f32_e32 v0, v0, v19
	v_sub_f32_e32 v17, v17, v0

.LBB0_6679:
	s_or_b64 exec, exec, s[72:73]
	v_or_b32_e32 v66, 15, v51
	s_and_saveexec_b64 s[72:73], s[34:35]
	s_cbranch_execz .LBB0_6686
	v_cmp_le_i32_e32 vcc, s28, v66
	s_and_saveexec_b64 s[36:37], vcc
	s_xor_b64 s[74:75], exec, s[36:37]
	s_cbranch_execz .LBB0_6682
	v_subrev_u32_e32 v0, s28, v66
	v_lshl_add_u64 v[18:19], v[0:1], 2, s[26:27]
	v_mov_b32_e32 v0, v239
	s_waitcnt vmcnt(0)
	v_mul_f32_e64 v18, |v0|, s89
	v_exp_f32_e32 v18, v18
	v_max_f32_e32 v0, v0, v0
	v_min_f32_e32 v0, 0, v0
	v_add_f32_e32 v18, 1.0, v18
	v_cmp_gt_f32_e32 vcc, s90, v18
	s_nop 1
	v_cndmask_b32_e64 v19, 0, 32, vcc
	v_ldexp_f32 v18, v18, v19
	v_log_f32_e32 v18, v18
	s_nop 0
	v_mul_f32_e32 v19, 0x3f317217, v18
	v_fma_f32 v19, v18, s91, -v19
	v_fmac_f32_e32 v19, 0x3377d1cf, v18
	v_fmac_f32_e32 v19, 0x3f317217, v18
	v_cmp_lt_f32_e64 s[36:37], |v18|, s92
	s_nop 1
	v_cndmask_b32_e64 v18, v18, v19, s[36:37]
	v_cndmask_b32_e32 v19, 0, v203, vcc
	v_sub_f32_e32 v18, v18, v19
	v_sub_f32_e32 v18, v0, v18
.LBB0_6682:
	s_andn2_saveexec_b64 s[26:27], s[74:75]
	s_cbranch_execz .LBB0_6685
	v_mad_i64_i32 v[18:19], s[36:37], s22, v66, 0
	v_lshl_add_u64 v[18:19], v[18:19], 2, s[0:1]
	v_mov_b32_e32 v18, v239
	s_andn2_b64 vcc, exec, s[70:71]
	s_cbranch_vccnz .LBB0_6685
	s_waitcnt vmcnt(0)
	v_mul_f32_e64 v0, |v18|, s89
	v_exp_f32_e32 v0, v0
	v_max_f32_e32 v18, v18, v18
	v_min_f32_e32 v18, 0, v18
	v_add_f32_e32 v0, 1.0, v0
	v_cmp_gt_f32_e32 vcc, s90, v0
	s_nop 1
	v_cndmask_b32_e64 v19, 0, 32, vcc
	v_ldexp_f32 v0, v0, v19
	v_log_f32_e32 v0, v0
	s_nop 0
	v_mul_f32_e32 v19, 0x3f317217, v0
	v_fma_f32 v19, v0, s91, -v19
	v_fmac_f32_e32 v19, 0x3377d1cf, v0
	v_fmac_f32_e32 v19, 0x3f317217, v0
	v_cmp_lt_f32_e64 s[36:37], |v0|, s92
	s_nop 1
	v_cndmask_b32_e64 v0, v0, v19, s[36:37]
	v_cndmask_b32_e32 v19, 0, v203, vcc
	v_sub_f32_e32 v0, v0, v19
	v_sub_f32_e32 v18, v18, v0

.LBB0_6909:
	s_lshr_b32 s2, s84, 6
	s_add_i32 s2, s2, 4
	s_lshr_b32 s3, s61, 6
	s_min_u32 s2, s2, s3
	s_lshl_b32 s3, s2, 6
	v_readlane_b32 s2, v253, 7
	s_mov_b64 s[0:1], -1
	v_mbcnt_lo_u32_b32 v0, -1, 0
	v_mbcnt_hi_u32_b32 v0, -1, v0
	s_andn2_b64 vcc, exec, s[26:27]
	v_add_u32_e32 v50, s2, v0
	s_cbranch_vccz .LBB0_7057
	v_lshlrev_b32_e32 v51, 4, v50
	s_xor_b64 s[62:63], s[22:23], -1
	v_cmp_gt_i32_e64 s[36:37], s3, v51
	v_mov_b32_e32 v1, 0
	v_mov_b32_e32 v2, 0
	s_and_saveexec_b64 s[98:99], s[36:37]
	v_mov_b32_e32 v247, 0
	v_subrev_u32_e32 v246, s4, v51
	v_mad_i64_i32 v[244:245], s[100:101], s60, v51, 0
	v_lshl_add_u64 v[242:243], v[246:247], 2, s[64:65]
	v_cmp_le_i32_e64 s[100:101], s4, v51
	v_lshl_add_u64 v[244:245], v[244:245], 2, s[20:21]
	s_nop 1
	v_cndmask_b32_e64 v242, v244, v242, s[100:101]
	v_cndmask_b32_e64 v243, v245, v243, s[100:101]
	global_load_dword v224, v[242:243], off
	v_or_b32_e32 v240, 1, v51
	v_subrev_u32_e32 v246, s4, v240
	v_mad_i64_i32 v[244:245], s[100:101], s60, v240, 0
	v_lshl_add_u64 v[242:243], v[246:247], 2, s[64:65]
	v_cmp_le_i32_e64 s[100:101], s4, v240
	v_lshl_add_u64 v[244:245], v[244:245], 2, s[20:21]
	s_nop 1
	v_cndmask_b32_e64 v242, v244, v242, s[100:101]
	v_cndmask_b32_e64 v243, v245, v243, s[100:101]
	global_load_dword v225, v[242:243], off
	v_or_b32_e32 v240, 2, v51
	v_subrev_u32_e32 v246, s4, v240
	v_mad_i64_i32 v[244:245], s[100:101], s60, v240, 0
	v_lshl_add_u64 v[242:243], v[246:247], 2, s[64:65]
	v_cmp_le_i32_e64 s[100:101], s4, v240
	v_lshl_add_u64 v[244:245], v[244:245], 2, s[20:21]
	s_nop 1
	v_cndmask_b32_e64 v242, v244, v242, s[100:101]
	v_cndmask_b32_e64 v243, v245, v243, s[100:101]
	global_load_dword v226, v[242:243], off
	v_or_b32_e32 v240, 3, v51
	v_subrev_u32_e32 v246, s4, v240
	v_mad_i64_i32 v[244:245], s[100:101], s60, v240, 0
	v_lshl_add_u64 v[242:243], v[246:247], 2, s[64:65]
	v_cmp_le_i32_e64 s[100:101], s4, v240
	v_lshl_add_u64 v[244:245], v[244:245], 2, s[20:21]
	s_nop 1
	v_cndmask_b32_e64 v242, v244, v242, s[100:101]
	v_cndmask_b32_e64 v243, v245, v243, s[100:101]
	global_load_dword v227, v[242:243], off
	v_or_b32_e32 v240, 4, v51
	v_subrev_u32_e32 v246, s4, v240
	v_mad_i64_i32 v[244:245], s[100:101], s60, v240, 0
	v_lshl_add_u64 v[242:243], v[246:247], 2, s[64:65]
	v_cmp_le_i32_e64 s[100:101], s4, v240
	v_lshl_add_u64 v[244:245], v[244:245], 2, s[20:21]
	s_nop 1
	v_cndmask_b32_e64 v242, v244, v242, s[100:101]
	v_cndmask_b32_e64 v243, v245, v243, s[100:101]
	global_load_dword v228, v[242:243], off
	v_or_b32_e32 v240, 5, v51
	v_subrev_u32_e32 v246, s4, v240
	v_mad_i64_i32 v[244:245], s[100:101], s60, v240, 0
	v_lshl_add_u64 v[242:243], v[246:247], 2, s[64:65]
	v_cmp_le_i32_e64 s[100:101], s4, v240
	v_lshl_add_u64 v[244:245], v[244:245], 2, s[20:21]
	s_nop 1
	v_cndmask_b32_e64 v242, v244, v242, s[100:101]
	v_cndmask_b32_e64 v243, v245, v243, s[100:101]
	global_load_dword v229, v[242:243], off
	v_or_b32_e32 v240, 6, v51
	v_subrev_u32_e32 v246, s4, v240
	v_mad_i64_i32 v[244:245], s[100:101], s60, v240, 0
	v_lshl_add_u64 v[242:243], v[246:247], 2, s[64:65]
	v_cmp_le_i32_e64 s[100:101], s4, v240
	v_lshl_add_u64 v[244:245], v[244:245], 2, s[20:21]
	s_nop 1
	v_cndmask_b32_e64 v242, v244, v242, s[100:101]
	v_cndmask_b32_e64 v243, v245, v243, s[100:101]
	global_load_dword v230, v[242:243], off
	v_or_b32_e32 v240, 7, v51
	v_subrev_u32_e32 v246, s4, v240
	v_mad_i64_i32 v[244:245], s[100:101], s60, v240, 0
	v_lshl_add_u64 v[242:243], v[246:247], 2, s[64:65]
	v_cmp_le_i32_e64 s[100:101], s4, v240
	v_lshl_add_u64 v[244:245], v[244:245], 2, s[20:21]
	s_nop 1
	v_cndmask_b32_e64 v242, v244, v242, s[100:101]
	v_cndmask_b32_e64 v243, v245, v243, s[100:101]
	global_load_dword v231, v[242:243], off
	v_or_b32_e32 v240, 8, v51
	v_subrev_u32_e32 v246, s4, v240
	v_mad_i64_i32 v[244:245], s[100:101], s60, v240, 0
	v_lshl_add_u64 v[242:243], v[246:247], 2, s[64:65]
	v_cmp_le_i32_e64 s[100:101], s4, v240
	v_lshl_add_u64 v[244:245], v[244:245], 2, s[20:21]
	s_nop 1
	v_cndmask_b32_e64 v242, v244, v242, s[100:101]
	v_cndmask_b32_e64 v243, v245, v243, s[100:101]
	global_load_dword v232, v[242:243], off
	v_or_b32_e32 v240, 9, v51
	v_subrev_u32_e32 v246, s4, v240
	v_mad_i64_i32 v[244:245], s[100:101], s60, v240, 0
	v_lshl_add_u64 v[242:243], v[246:247], 2, s[64:65]
	v_cmp_le_i32_e64 s[100:101], s4, v240
	v_lshl_add_u64 v[244:245], v[244:245], 2, s[20:21]
	s_nop 1
	v_cndmask_b32_e64 v242, v244, v242, s[100:101]
	v_cndmask_b32_e64 v243, v245, v243, s[100:101]
	global_load_dword v233, v[242:243], off
	v_or_b32_e32 v240, 10, v51
	v_subrev_u32_e32 v246, s4, v240
	v_mad_i64_i32 v[244:245], s[100:101], s60, v240, 0
	v_lshl_add_u64 v[242:243], v[246:247], 2, s[64:65]
	v_cmp_le_i32_e64 s[100:101], s4, v240
	v_lshl_add_u64 v[244:245], v[244:245], 2, s[20:21]
	s_nop 1
	v_cndmask_b32_e64 v242, v244, v242, s[100:101]
	v_cndmask_b32_e64 v243, v245, v243, s[100:101]
	global_load_dword v234, v[242:243], off
	v_or_b32_e32 v240, 11, v51
	v_subrev_u32_e32 v246, s4, v240
	v_mad_i64_i32 v[244:245], s[100:101], s60, v240, 0
	v_lshl_add_u64 v[242:243], v[246:247], 2, s[64:65]
	v_cmp_le_i32_e64 s[100:101], s4, v240
	v_lshl_add_u64 v[244:245], v[244:245], 2, s[20:21]
	s_nop 1
	v_cndmask_b32_e64 v242, v244, v242, s[100:101]
	v_cndmask_b32_e64 v243, v245, v243, s[100:101]
	global_load_dword v235, v[242:243], off
	v_or_b32_e32 v240, 12, v51
	v_subrev_u32_e32 v246, s4, v240
	v_mad_i64_i32 v[244:245], s[100:101], s60, v240, 0
	v_lshl_add_u64 v[242:243], v[246:247], 2, s[64:65]
	v_cmp_le_i32_e64 s[100:101], s4, v240
	v_lshl_add_u64 v[244:245], v[244:245], 2, s[20:21]
	s_nop 1
	v_cndmask_b32_e64 v242, v244, v242, s[100:101]
	v_cndmask_b32_e64 v243, v245, v243, s[100:101]
	global_load_dword v236, v[242:243], off
	v_or_b32_e32 v240, 13, v51
	v_subrev_u32_e32 v246, s4, v240
	v_mad_i64_i32 v[244:245], s[100:101], s60, v240, 0
	v_lshl_add_u64 v[242:243], v[246:247], 2, s[64:65]
	v_cmp_le_i32_e64 s[100:101], s4, v240
	v_lshl_add_u64 v[244:245], v[244:245], 2, s[20:21]
	s_nop 1
	v_cndmask_b32_e64 v242, v244, v242, s[100:101]
	v_cndmask_b32_e64 v243, v245, v243, s[100:101]
	global_load_dword v237, v[242:243], off
	v_or_b32_e32 v240, 14, v51
	v_subrev_u32_e32 v246, s4, v240
	v_mad_i64_i32 v[244:245], s[100:101], s60, v240, 0
	v_lshl_add_u64 v[242:243], v[246:247], 2, s[64:65]
	v_cmp_le_i32_e64 s[100:101], s4, v240
	v_lshl_add_u64 v[244:245], v[244:245], 2, s[20:21]
	s_nop 1
	v_cndmask_b32_e64 v242, v244, v242, s[100:101]
	v_cndmask_b32_e64 v243, v245, v243, s[100:101]
	global_load_dword v238, v[242:243], off
	v_or_b32_e32 v240, 15, v51
	v_subrev_u32_e32 v246, s4, v240
	v_mad_i64_i32 v[244:245], s[100:101], s60, v240, 0
	v_lshl_add_u64 v[242:243], v[246:247], 2, s[64:65]
	v_cmp_le_i32_e64 s[100:101], s4, v240
	v_lshl_add_u64 v[244:245], v[244:245], 2, s[20:21]
	s_nop 1
	v_cndmask_b32_e64 v242, v244, v242, s[100:101]
	v_cndmask_b32_e64 v243, v245, v243, s[100:101]
	global_load_dword v239, v[242:243], off
	s_mov_b64 exec, s[98:99]
	s_waitcnt vmcnt(0)
	s_and_saveexec_b64 s[0:1], s[36:37]
	s_cbranch_execz .LBB0_6917
	v_cmp_le_i32_e32 vcc, s4, v51
	s_and_saveexec_b64 s[6:7], vcc
	s_xor_b64 s[22:23], exec, s[6:7]
	s_cbranch_execz .LBB0_6913
	v_subrev_u32_e32 v2, s4, v51
	v_mov_b32_e32 v3, 0
	v_lshl_add_u64 v[2:3], v[2:3], 2, s[64:65]
	v_mov_b32_e32 v2, v224
	s_mov_b32 s2, 0xbfb8aa3b
	s_waitcnt vmcnt(0)
	v_max_f32_e32 v3, v2, v2
	v_mul_f32_e64 v2, |v2|, s2
	v_exp_f32_e32 v2, v2
	s_mov_b32 s2, 0x800000
	v_min_f32_e32 v3, 0, v3
	v_add_f32_e32 v2, 1.0, v2
	v_cmp_gt_f32_e32 vcc, s2, v2
	s_mov_b32 s2, 0x3f317217
	s_nop 0
	v_cndmask_b32_e64 v4, 0, 32, vcc
	v_ldexp_f32 v2, v2, v4
	v_log_f32_e32 v2, v2
	s_nop 0
	v_mul_f32_e32 v4, 0x3f317217, v2
	v_fma_f32 v4, v2, s2, -v4
	v_fmamk_f32 v4, v2, 0x3377d1cf, v4
	s_mov_b32 s2, 0x7f800000
	v_fmac_f32_e32 v4, 0x3f317217, v2
	v_cmp_lt_f32_e64 s[38:39], |v2|, s2
	s_nop 1
	v_cndmask_b32_e64 v2, v2, v4, s[38:39]
	v_mov_b32_e32 v4, 0x41b17218
	v_cndmask_b32_e32 v4, 0, v4, vcc
	v_sub_f32_e32 v2, v2, v4
	v_sub_f32_e32 v2, v3, v2
.LBB0_6913:
	s_andn2_saveexec_b64 s[22:23], s[22:23]
	s_cbranch_execz .LBB0_6916
	v_mad_i64_i32 v[2:3], s[6:7], s60, v51, 0
	v_lshl_add_u64 v[2:3], v[2:3], 2, s[20:21]
	v_mov_b32_e32 v2, v224
	s_andn2_b64 vcc, exec, s[62:63]
	s_cbranch_vccnz .LBB0_6916
	s_mov_b32 s2, 0xbfb8aa3b
	s_waitcnt vmcnt(0)
	v_mul_f32_e64 v3, |v2|, s2
	v_exp_f32_e32 v3, v3
	s_mov_b32 s2, 0x800000
	s_mov_b32 s5, 0x7f800000
	v_max_f32_e32 v2, v2, v2
	v_add_f32_e32 v3, 1.0, v3
	v_cmp_gt_f32_e32 vcc, s2, v3
	s_mov_b32 s2, 0x3f317217
	v_min_f32_e32 v2, 0, v2
	v_cndmask_b32_e64 v4, 0, 32, vcc
	v_ldexp_f32 v3, v3, v4
	v_log_f32_e32 v3, v3
	s_nop 0
	v_mul_f32_e32 v4, 0x3f317217, v3
	v_fma_f32 v4, v3, s2, -v4
	v_fmamk_f32 v4, v3, 0x3377d1cf, v4
	v_fmac_f32_e32 v4, 0x3f317217, v3
	v_cmp_lt_f32_e64 s[38:39], |v3|, s5
	s_nop 1
	v_cndmask_b32_e64 v3, v3, v4, s[38:39]
	v_mov_b32_e32 v4, 0x41b17218
	v_cndmask_b32_e32 v4, 0, v4, vcc
	v_sub_f32_e32 v3, v3, v4
	v_sub_f32_e32 v2, v2, v3

.LBB0_6917:
	s_or_b64 exec, exec, s[0:1]
	v_or_b32_e32 v52, 1, v51
	s_and_saveexec_b64 s[0:1], s[36:37]
	s_cbranch_execz .LBB0_6924
	v_cmp_le_i32_e32 vcc, s4, v52
	s_and_saveexec_b64 s[6:7], vcc
	s_xor_b64 s[22:23], exec, s[6:7]
	s_cbranch_execz .LBB0_6920
	v_subrev_u32_e32 v4, s4, v52
	v_mov_b32_e32 v5, 0
	v_lshl_add_u64 v[4:5], v[4:5], 2, s[64:65]
	v_mov_b32_e32 v1, v225
	s_mov_b32 s2, 0xbfb8aa3b
	s_waitcnt vmcnt(0)
	v_max_f32_e32 v3, v1, v1
	v_mul_f32_e64 v1, |v1|, s2
	v_exp_f32_e32 v1, v1
	s_mov_b32 s2, 0x800000
	v_min_f32_e32 v3, 0, v3
	v_add_f32_e32 v1, 1.0, v1
	v_cmp_gt_f32_e32 vcc, s2, v1
	s_mov_b32 s2, 0x3f317217
	s_nop 0
	v_cndmask_b32_e64 v4, 0, 32, vcc
	v_ldexp_f32 v1, v1, v4
	v_log_f32_e32 v1, v1
	s_nop 0
	v_mul_f32_e32 v4, 0x3f317217, v1
	v_fma_f32 v4, v1, s2, -v4
	v_fmamk_f32 v4, v1, 0x3377d1cf, v4
	s_mov_b32 s2, 0x7f800000
	v_fmac_f32_e32 v4, 0x3f317217, v1
	v_cmp_lt_f32_e64 s[38:39], |v1|, s2
	s_nop 1
	v_cndmask_b32_e64 v1, v1, v4, s[38:39]
	v_mov_b32_e32 v4, 0x41b17218
	v_cndmask_b32_e32 v4, 0, v4, vcc
	v_sub_f32_e32 v1, v1, v4
	v_sub_f32_e32 v1, v3, v1
.LBB0_6920:
	s_andn2_saveexec_b64 s[22:23], s[22:23]
	s_cbranch_execz .LBB0_6923
	v_mad_i64_i32 v[4:5], s[6:7], s60, v52, 0
	v_lshl_add_u64 v[4:5], v[4:5], 2, s[20:21]
	v_mov_b32_e32 v1, v225
	s_andn2_b64 vcc, exec, s[62:63]
	s_cbranch_vccnz .LBB0_6923
	s_mov_b32 s2, 0xbfb8aa3b
	s_waitcnt vmcnt(0)
	v_mul_f32_e64 v3, |v1|, s2
	v_exp_f32_e32 v3, v3
	s_mov_b32 s2, 0x800000
	s_mov_b32 s5, 0x7f800000
	v_max_f32_e32 v1, v1, v1
	v_add_f32_e32 v3, 1.0, v3
	v_cmp_gt_f32_e32 vcc, s2, v3
	s_mov_b32 s2, 0x3f317217
	v_min_f32_e32 v1, 0, v1
	v_cndmask_b32_e64 v4, 0, 32, vcc
	v_ldexp_f32 v3, v3, v4
	v_log_f32_e32 v3, v3
	s_nop 0
	v_mul_f32_e32 v4, 0x3f317217, v3
	v_fma_f32 v4, v3, s2, -v4
	v_fmamk_f32 v4, v3, 0x3377d1cf, v4
	v_fmac_f32_e32 v4, 0x3f317217, v3
	v_cmp_lt_f32_e64 s[38:39], |v3|, s5
	s_nop 1
	v_cndmask_b32_e64 v3, v3, v4, s[38:39]
	v_mov_b32_e32 v4, 0x41b17218
	v_cndmask_b32_e32 v4, 0, v4, vcc
	v_sub_f32_e32 v3, v3, v4
	v_sub_f32_e32 v1, v1, v3

.LBB0_6924:
	s_or_b64 exec, exec, s[0:1]
	v_or_b32_e32 v53, 2, v51
	v_mov_b32_e32 v4, 0
	v_mov_b32_e32 v3, 0
	s_and_saveexec_b64 s[0:1], s[36:37]
	s_cbranch_execz .LBB0_6931
	v_cmp_le_i32_e32 vcc, s4, v53
	s_and_saveexec_b64 s[6:7], vcc
	s_xor_b64 s[22:23], exec, s[6:7]
	s_cbranch_execz .LBB0_6927
	v_subrev_u32_e32 v6, s4, v53
	v_mov_b32_e32 v7, 0
	v_lshl_add_u64 v[6:7], v[6:7], 2, s[64:65]
	v_mov_b32_e32 v3, v226
	s_mov_b32 s2, 0xbfb8aa3b
	s_waitcnt vmcnt(0)
	v_max_f32_e32 v5, v3, v3
	v_mul_f32_e64 v3, |v3|, s2
	v_exp_f32_e32 v3, v3
	s_mov_b32 s2, 0x800000
	v_min_f32_e32 v5, 0, v5
	v_add_f32_e32 v3, 1.0, v3
	v_cmp_gt_f32_e32 vcc, s2, v3
	s_mov_b32 s2, 0x3f317217
	s_nop 0
	v_cndmask_b32_e64 v6, 0, 32, vcc
	v_ldexp_f32 v3, v3, v6
	v_log_f32_e32 v3, v3
	s_nop 0
	v_mul_f32_e32 v6, 0x3f317217, v3
	v_fma_f32 v6, v3, s2, -v6
	v_fmamk_f32 v6, v3, 0x3377d1cf, v6
	s_mov_b32 s2, 0x7f800000
	v_fmac_f32_e32 v6, 0x3f317217, v3
	v_cmp_lt_f32_e64 s[38:39], |v3|, s2
	s_nop 1
	v_cndmask_b32_e64 v3, v3, v6, s[38:39]
	v_mov_b32_e32 v6, 0x41b17218
	v_cndmask_b32_e32 v6, 0, v6, vcc
	v_sub_f32_e32 v3, v3, v6
	v_sub_f32_e32 v3, v5, v3
.LBB0_6927:
	s_andn2_saveexec_b64 s[22:23], s[22:23]
	s_cbranch_execz .LBB0_6930
	v_mad_i64_i32 v[6:7], s[6:7], s60, v53, 0
	v_lshl_add_u64 v[6:7], v[6:7], 2, s[20:21]
	v_mov_b32_e32 v3, v226
	s_andn2_b64 vcc, exec, s[62:63]
	s_cbranch_vccnz .LBB0_6930
	s_mov_b32 s2, 0xbfb8aa3b
	s_waitcnt vmcnt(0)
	v_mul_f32_e64 v5, |v3|, s2
	v_exp_f32_e32 v5, v5
	s_mov_b32 s2, 0x800000
	s_mov_b32 s5, 0x7f800000
	v_max_f32_e32 v3, v3, v3
	v_add_f32_e32 v5, 1.0, v5
	v_cmp_gt_f32_e32 vcc, s2, v5
	s_mov_b32 s2, 0x3f317217
	v_min_f32_e32 v3, 0, v3
	v_cndmask_b32_e64 v6, 0, 32, vcc
	v_ldexp_f32 v5, v5, v6
	v_log_f32_e32 v5, v5
	s_nop 0
	v_mul_f32_e32 v6, 0x3f317217, v5
	v_fma_f32 v6, v5, s2, -v6
	v_fmamk_f32 v6, v5, 0x3377d1cf, v6
	v_fmac_f32_e32 v6, 0x3f317217, v5
	v_cmp_lt_f32_e64 s[38:39], |v5|, s5
	s_nop 1
	v_cndmask_b32_e64 v5, v5, v6, s[38:39]
	v_mov_b32_e32 v6, 0x41b17218
	v_cndmask_b32_e32 v6, 0, v6, vcc
	v_sub_f32_e32 v5, v5, v6
	v_sub_f32_e32 v3, v3, v5

.LBB0_6931:
	s_or_b64 exec, exec, s[0:1]
	v_or_b32_e32 v54, 3, v51
	s_and_saveexec_b64 s[0:1], s[36:37]
	s_cbranch_execz .LBB0_6938
	v_cmp_le_i32_e32 vcc, s4, v54
	s_and_saveexec_b64 s[6:7], vcc
	s_xor_b64 s[22:23], exec, s[6:7]
	s_cbranch_execz .LBB0_6934
	v_subrev_u32_e32 v4, s4, v54
	v_mov_b32_e32 v5, 0
	v_lshl_add_u64 v[4:5], v[4:5], 2, s[64:65]
	v_mov_b32_e32 v4, v227
	s_mov_b32 s2, 0xbfb8aa3b
	s_waitcnt vmcnt(0)
	v_max_f32_e32 v5, v4, v4
	v_mul_f32_e64 v4, |v4|, s2
	v_exp_f32_e32 v4, v4
	s_mov_b32 s2, 0x800000
	v_min_f32_e32 v5, 0, v5
	v_add_f32_e32 v4, 1.0, v4
	v_cmp_gt_f32_e32 vcc, s2, v4
	s_mov_b32 s2, 0x3f317217
	s_nop 0
	v_cndmask_b32_e64 v6, 0, 32, vcc
	v_ldexp_f32 v4, v4, v6
	v_log_f32_e32 v4, v4
	s_nop 0
	v_mul_f32_e32 v6, 0x3f317217, v4
	v_fma_f32 v6, v4, s2, -v6
	v_fmamk_f32 v6, v4, 0x3377d1cf, v6
	s_mov_b32 s2, 0x7f800000
	v_fmac_f32_e32 v6, 0x3f317217, v4
	v_cmp_lt_f32_e64 s[38:39], |v4|, s2
	s_nop 1
	v_cndmask_b32_e64 v4, v4, v6, s[38:39]
	v_mov_b32_e32 v6, 0x41b17218
	v_cndmask_b32_e32 v6, 0, v6, vcc
	v_sub_f32_e32 v4, v4, v6
	v_sub_f32_e32 v4, v5, v4
.LBB0_6934:
	s_andn2_saveexec_b64 s[22:23], s[22:23]
	s_cbranch_execz .LBB0_6937
	v_mad_i64_i32 v[4:5], s[6:7], s60, v54, 0
	v_lshl_add_u64 v[4:5], v[4:5], 2, s[20:21]
	v_mov_b32_e32 v4, v227
	s_andn2_b64 vcc, exec, s[62:63]
	s_cbranch_vccnz .LBB0_6937
	s_mov_b32 s2, 0xbfb8aa3b
	s_waitcnt vmcnt(0)
	v_mul_f32_e64 v5, |v4|, s2
	v_exp_f32_e32 v5, v5
	s_mov_b32 s2, 0x800000
	s_mov_b32 s5, 0x7f800000
	v_max_f32_e32 v4, v4, v4
	v_add_f32_e32 v5, 1.0, v5
	v_cmp_gt_f32_e32 vcc, s2, v5
	s_mov_b32 s2, 0x3f317217
	v_min_f32_e32 v4, 0, v4
	v_cndmask_b32_e64 v6, 0, 32, vcc
	v_ldexp_f32 v5, v5, v6
	v_log_f32_e32 v5, v5
	s_nop 0
	v_mul_f32_e32 v6, 0x3f317217, v5
	v_fma_f32 v6, v5, s2, -v6
	v_fmamk_f32 v6, v5, 0x3377d1cf, v6
	v_fmac_f32_e32 v6, 0x3f317217, v5
	v_cmp_lt_f32_e64 s[38:39], |v5|, s5
	s_nop 1
	v_cndmask_b32_e64 v5, v5, v6, s[38:39]
	v_mov_b32_e32 v6, 0x41b17218
	v_cndmask_b32_e32 v6, 0, v6, vcc
	v_sub_f32_e32 v5, v5, v6
	v_sub_f32_e32 v4, v4, v5

.LBB0_6938:
	s_or_b64 exec, exec, s[0:1]
	v_or_b32_e32 v55, 4, v51
	v_mov_b32_e32 v6, 0
	v_mov_b32_e32 v5, 0
	s_and_saveexec_b64 s[0:1], s[36:37]
	s_cbranch_execz .LBB0_6945
	v_cmp_le_i32_e32 vcc, s4, v55
	s_and_saveexec_b64 s[6:7], vcc
	s_xor_b64 s[22:23], exec, s[6:7]
	s_cbranch_execz .LBB0_6941
	v_subrev_u32_e32 v8, s4, v55
	v_mov_b32_e32 v9, 0
	v_lshl_add_u64 v[8:9], v[8:9], 2, s[64:65]
	v_mov_b32_e32 v5, v228
	s_mov_b32 s2, 0xbfb8aa3b
	s_waitcnt vmcnt(0)
	v_max_f32_e32 v7, v5, v5
	v_mul_f32_e64 v5, |v5|, s2
	v_exp_f32_e32 v5, v5
	s_mov_b32 s2, 0x800000
	v_min_f32_e32 v7, 0, v7
	v_add_f32_e32 v5, 1.0, v5
	v_cmp_gt_f32_e32 vcc, s2, v5
	s_mov_b32 s2, 0x3f317217
	s_nop 0
	v_cndmask_b32_e64 v8, 0, 32, vcc
	v_ldexp_f32 v5, v5, v8
	v_log_f32_e32 v5, v5
	s_nop 0
	v_mul_f32_e32 v8, 0x3f317217, v5
	v_fma_f32 v8, v5, s2, -v8
	v_fmamk_f32 v8, v5, 0x3377d1cf, v8
	s_mov_b32 s2, 0x7f800000
	v_fmac_f32_e32 v8, 0x3f317217, v5
	v_cmp_lt_f32_e64 s[38:39], |v5|, s2
	s_nop 1
	v_cndmask_b32_e64 v5, v5, v8, s[38:39]
	v_mov_b32_e32 v8, 0x41b17218
	v_cndmask_b32_e32 v8, 0, v8, vcc
	v_sub_f32_e32 v5, v5, v8
	v_sub_f32_e32 v5, v7, v5
.LBB0_6941:
	s_andn2_saveexec_b64 s[22:23], s[22:23]
	s_cbranch_execz .LBB0_6944
	v_mad_i64_i32 v[8:9], s[6:7], s60, v55, 0
	v_lshl_add_u64 v[8:9], v[8:9], 2, s[20:21]
	v_mov_b32_e32 v5, v228
	s_andn2_b64 vcc, exec, s[62:63]
	s_cbranch_vccnz .LBB0_6944
	s_mov_b32 s2, 0xbfb8aa3b
	s_waitcnt vmcnt(0)
	v_mul_f32_e64 v7, |v5|, s2
	v_exp_f32_e32 v7, v7
	s_mov_b32 s2, 0x800000
	s_mov_b32 s5, 0x7f800000
	v_max_f32_e32 v5, v5, v5
	v_add_f32_e32 v7, 1.0, v7
	v_cmp_gt_f32_e32 vcc, s2, v7
	s_mov_b32 s2, 0x3f317217
	v_min_f32_e32 v5, 0, v5
	v_cndmask_b32_e64 v8, 0, 32, vcc
	v_ldexp_f32 v7, v7, v8
	v_log_f32_e32 v7, v7
	s_nop 0
	v_mul_f32_e32 v8, 0x3f317217, v7
	v_fma_f32 v8, v7, s2, -v8
	v_fmamk_f32 v8, v7, 0x3377d1cf, v8
	v_fmac_f32_e32 v8, 0x3f317217, v7
	v_cmp_lt_f32_e64 s[38:39], |v7|, s5
	s_nop 1
	v_cndmask_b32_e64 v7, v7, v8, s[38:39]
	v_mov_b32_e32 v8, 0x41b17218
	v_cndmask_b32_e32 v8, 0, v8, vcc
	v_sub_f32_e32 v7, v7, v8
	v_sub_f32_e32 v5, v5, v7

.LBB0_6945:
	s_or_b64 exec, exec, s[0:1]
	v_or_b32_e32 v56, 5, v51
	s_and_saveexec_b64 s[0:1], s[36:37]
	s_cbranch_execz .LBB0_6952
	v_cmp_le_i32_e32 vcc, s4, v56
	s_and_saveexec_b64 s[6:7], vcc
	s_xor_b64 s[22:23], exec, s[6:7]
	s_cbranch_execz .LBB0_6948
	v_subrev_u32_e32 v6, s4, v56
	v_mov_b32_e32 v7, 0
	v_lshl_add_u64 v[6:7], v[6:7], 2, s[64:65]
	v_mov_b32_e32 v6, v229
	s_mov_b32 s2, 0xbfb8aa3b
	s_waitcnt vmcnt(0)
	v_max_f32_e32 v7, v6, v6
	v_mul_f32_e64 v6, |v6|, s2
	v_exp_f32_e32 v6, v6
	s_mov_b32 s2, 0x800000
	v_min_f32_e32 v7, 0, v7
	v_add_f32_e32 v6, 1.0, v6
	v_cmp_gt_f32_e32 vcc, s2, v6
	s_mov_b32 s2, 0x3f317217
	s_nop 0
	v_cndmask_b32_e64 v8, 0, 32, vcc
	v_ldexp_f32 v6, v6, v8
	v_log_f32_e32 v6, v6
	s_nop 0
	v_mul_f32_e32 v8, 0x3f317217, v6
	v_fma_f32 v8, v6, s2, -v8
	v_fmamk_f32 v8, v6, 0x3377d1cf, v8
	s_mov_b32 s2, 0x7f800000
	v_fmac_f32_e32 v8, 0x3f317217, v6
	v_cmp_lt_f32_e64 s[38:39], |v6|, s2
	s_nop 1
	v_cndmask_b32_e64 v6, v6, v8, s[38:39]
	v_mov_b32_e32 v8, 0x41b17218
	v_cndmask_b32_e32 v8, 0, v8, vcc
	v_sub_f32_e32 v6, v6, v8
	v_sub_f32_e32 v6, v7, v6
.LBB0_6948:
	s_andn2_saveexec_b64 s[22:23], s[22:23]
	s_cbranch_execz .LBB0_6951
	v_mad_i64_i32 v[6:7], s[6:7], s60, v56, 0
	v_lshl_add_u64 v[6:7], v[6:7], 2, s[20:21]
	v_mov_b32_e32 v6, v229
	s_andn2_b64 vcc, exec, s[62:63]
	s_cbranch_vccnz .LBB0_6951
	s_mov_b32 s2, 0xbfb8aa3b
	s_waitcnt vmcnt(0)
	v_mul_f32_e64 v7, |v6|, s2
	v_exp_f32_e32 v7, v7
	s_mov_b32 s2, 0x800000
	s_mov_b32 s5, 0x7f800000
	v_max_f32_e32 v6, v6, v6
	v_add_f32_e32 v7, 1.0, v7
	v_cmp_gt_f32_e32 vcc, s2, v7
	s_mov_b32 s2, 0x3f317217
	v_min_f32_e32 v6, 0, v6
	v_cndmask_b32_e64 v8, 0, 32, vcc
	v_ldexp_f32 v7, v7, v8
	v_log_f32_e32 v7, v7
	s_nop 0
	v_mul_f32_e32 v8, 0x3f317217, v7
	v_fma_f32 v8, v7, s2, -v8
	v_fmamk_f32 v8, v7, 0x3377d1cf, v8
	v_fmac_f32_e32 v8, 0x3f317217, v7
	v_cmp_lt_f32_e64 s[38:39], |v7|, s5
	s_nop 1
	v_cndmask_b32_e64 v7, v7, v8, s[38:39]
	v_mov_b32_e32 v8, 0x41b17218
	v_cndmask_b32_e32 v8, 0, v8, vcc
	v_sub_f32_e32 v7, v7, v8
	v_sub_f32_e32 v6, v6, v7

.LBB0_6952:
	s_or_b64 exec, exec, s[0:1]
	v_or_b32_e32 v57, 6, v51
	v_mov_b32_e32 v8, 0
	v_mov_b32_e32 v7, 0
	s_and_saveexec_b64 s[0:1], s[36:37]
	s_cbranch_execz .LBB0_6959
	v_cmp_le_i32_e32 vcc, s4, v57
	s_and_saveexec_b64 s[6:7], vcc
	s_xor_b64 s[22:23], exec, s[6:7]
	s_cbranch_execz .LBB0_6955
	v_subrev_u32_e32 v10, s4, v57
	v_mov_b32_e32 v11, 0
	v_lshl_add_u64 v[10:11], v[10:11], 2, s[64:65]
	v_mov_b32_e32 v7, v230
	s_mov_b32 s2, 0xbfb8aa3b
	s_waitcnt vmcnt(0)
	v_max_f32_e32 v9, v7, v7
	v_mul_f32_e64 v7, |v7|, s2
	v_exp_f32_e32 v7, v7
	s_mov_b32 s2, 0x800000
	v_min_f32_e32 v9, 0, v9
	v_add_f32_e32 v7, 1.0, v7
	v_cmp_gt_f32_e32 vcc, s2, v7
	s_mov_b32 s2, 0x3f317217
	s_nop 0
	v_cndmask_b32_e64 v10, 0, 32, vcc
	v_ldexp_f32 v7, v7, v10
	v_log_f32_e32 v7, v7
	s_nop 0
	v_mul_f32_e32 v10, 0x3f317217, v7
	v_fma_f32 v10, v7, s2, -v10
	v_fmamk_f32 v10, v7, 0x3377d1cf, v10
	s_mov_b32 s2, 0x7f800000
	v_fmac_f32_e32 v10, 0x3f317217, v7
	v_cmp_lt_f32_e64 s[38:39], |v7|, s2
	s_nop 1
	v_cndmask_b32_e64 v7, v7, v10, s[38:39]
	v_mov_b32_e32 v10, 0x41b17218
	v_cndmask_b32_e32 v10, 0, v10, vcc
	v_sub_f32_e32 v7, v7, v10
	v_sub_f32_e32 v7, v9, v7
.LBB0_6955:
	s_andn2_saveexec_b64 s[22:23], s[22:23]
	s_cbranch_execz .LBB0_6958
	v_mad_i64_i32 v[10:11], s[6:7], s60, v57, 0
	v_lshl_add_u64 v[10:11], v[10:11], 2, s[20:21]
	v_mov_b32_e32 v7, v230
	s_andn2_b64 vcc, exec, s[62:63]
	s_cbranch_vccnz .LBB0_6958
	s_mov_b32 s2, 0xbfb8aa3b
	s_waitcnt vmcnt(0)
	v_mul_f32_e64 v9, |v7|, s2
	v_exp_f32_e32 v9, v9
	s_mov_b32 s2, 0x800000
	s_mov_b32 s5, 0x7f800000
	v_max_f32_e32 v7, v7, v7
	v_add_f32_e32 v9, 1.0, v9
	v_cmp_gt_f32_e32 vcc, s2, v9
	s_mov_b32 s2, 0x3f317217
	v_min_f32_e32 v7, 0, v7
	v_cndmask_b32_e64 v10, 0, 32, vcc
	v_ldexp_f32 v9, v9, v10
	v_log_f32_e32 v9, v9
	s_nop 0
	v_mul_f32_e32 v10, 0x3f317217, v9
	v_fma_f32 v10, v9, s2, -v10
	v_fmamk_f32 v10, v9, 0x3377d1cf, v10
	v_fmac_f32_e32 v10, 0x3f317217, v9
	v_cmp_lt_f32_e64 s[38:39], |v9|, s5
	s_nop 1
	v_cndmask_b32_e64 v9, v9, v10, s[38:39]
	v_mov_b32_e32 v10, 0x41b17218
	v_cndmask_b32_e32 v10, 0, v10, vcc
	v_sub_f32_e32 v9, v9, v10
	v_sub_f32_e32 v7, v7, v9

.LBB0_6959:
	s_or_b64 exec, exec, s[0:1]
	v_or_b32_e32 v58, 7, v51
	s_and_saveexec_b64 s[0:1], s[36:37]
	s_cbranch_execz .LBB0_6966
	v_cmp_le_i32_e32 vcc, s4, v58
	s_and_saveexec_b64 s[6:7], vcc
	s_xor_b64 s[22:23], exec, s[6:7]
	s_cbranch_execz .LBB0_6962
	v_subrev_u32_e32 v8, s4, v58
	v_mov_b32_e32 v9, 0
	v_lshl_add_u64 v[8:9], v[8:9], 2, s[64:65]
	v_mov_b32_e32 v8, v231
	s_mov_b32 s2, 0xbfb8aa3b
	s_waitcnt vmcnt(0)
	v_max_f32_e32 v9, v8, v8
	v_mul_f32_e64 v8, |v8|, s2
	v_exp_f32_e32 v8, v8
	s_mov_b32 s2, 0x800000
	v_min_f32_e32 v9, 0, v9
	v_add_f32_e32 v8, 1.0, v8
	v_cmp_gt_f32_e32 vcc, s2, v8
	s_mov_b32 s2, 0x3f317217
	s_nop 0
	v_cndmask_b32_e64 v10, 0, 32, vcc
	v_ldexp_f32 v8, v8, v10
	v_log_f32_e32 v8, v8
	s_nop 0
	v_mul_f32_e32 v10, 0x3f317217, v8
	v_fma_f32 v10, v8, s2, -v10
	v_fmamk_f32 v10, v8, 0x3377d1cf, v10
	s_mov_b32 s2, 0x7f800000
	v_fmac_f32_e32 v10, 0x3f317217, v8
	v_cmp_lt_f32_e64 s[38:39], |v8|, s2
	s_nop 1
	v_cndmask_b32_e64 v8, v8, v10, s[38:39]
	v_mov_b32_e32 v10, 0x41b17218
	v_cndmask_b32_e32 v10, 0, v10, vcc
	v_sub_f32_e32 v8, v8, v10
	v_sub_f32_e32 v8, v9, v8
.LBB0_6962:
	s_andn2_saveexec_b64 s[22:23], s[22:23]
	s_cbranch_execz .LBB0_6965
	v_mad_i64_i32 v[8:9], s[6:7], s60, v58, 0
	v_lshl_add_u64 v[8:9], v[8:9], 2, s[20:21]
	v_mov_b32_e32 v8, v231
	s_andn2_b64 vcc, exec, s[62:63]
	s_cbranch_vccnz .LBB0_6965
	s_mov_b32 s2, 0xbfb8aa3b
	s_waitcnt vmcnt(0)
	v_mul_f32_e64 v9, |v8|, s2
	v_exp_f32_e32 v9, v9
	s_mov_b32 s2, 0x800000
	s_mov_b32 s5, 0x7f800000
	v_max_f32_e32 v8, v8, v8
	v_add_f32_e32 v9, 1.0, v9
	v_cmp_gt_f32_e32 vcc, s2, v9
	s_mov_b32 s2, 0x3f317217
	v_min_f32_e32 v8, 0, v8
	v_cndmask_b32_e64 v10, 0, 32, vcc
	v_ldexp_f32 v9, v9, v10
	v_log_f32_e32 v9, v9
	s_nop 0
	v_mul_f32_e32 v10, 0x3f317217, v9
	v_fma_f32 v10, v9, s2, -v10
	v_fmamk_f32 v10, v9, 0x3377d1cf, v10
	v_fmac_f32_e32 v10, 0x3f317217, v9
	v_cmp_lt_f32_e64 s[38:39], |v9|, s5
	s_nop 1
	v_cndmask_b32_e64 v9, v9, v10, s[38:39]
	v_mov_b32_e32 v10, 0x41b17218
	v_cndmask_b32_e32 v10, 0, v10, vcc
	v_sub_f32_e32 v9, v9, v10
	v_sub_f32_e32 v8, v8, v9

.LBB0_6966:
	s_or_b64 exec, exec, s[0:1]
	v_or_b32_e32 v59, 8, v51
	v_mov_b32_e32 v10, 0
	v_mov_b32_e32 v9, 0
	s_and_saveexec_b64 s[0:1], s[36:37]
	s_cbranch_execz .LBB0_6973
	v_cmp_le_i32_e32 vcc, s4, v59
	s_and_saveexec_b64 s[6:7], vcc
	s_xor_b64 s[22:23], exec, s[6:7]
	s_cbranch_execz .LBB0_6969
	v_subrev_u32_e32 v12, s4, v59
	v_mov_b32_e32 v13, 0
	v_lshl_add_u64 v[12:13], v[12:13], 2, s[64:65]
	v_mov_b32_e32 v9, v232
	s_mov_b32 s2, 0xbfb8aa3b
	s_waitcnt vmcnt(0)
	v_max_f32_e32 v11, v9, v9
	v_mul_f32_e64 v9, |v9|, s2
	v_exp_f32_e32 v9, v9
	s_mov_b32 s2, 0x800000
	v_min_f32_e32 v11, 0, v11
	v_add_f32_e32 v9, 1.0, v9
	v_cmp_gt_f32_e32 vcc, s2, v9
	s_mov_b32 s2, 0x3f317217
	s_nop 0
	v_cndmask_b32_e64 v12, 0, 32, vcc
	v_ldexp_f32 v9, v9, v12
	v_log_f32_e32 v9, v9
	s_nop 0
	v_mul_f32_e32 v12, 0x3f317217, v9
	v_fma_f32 v12, v9, s2, -v12
	v_fmamk_f32 v12, v9, 0x3377d1cf, v12
	s_mov_b32 s2, 0x7f800000
	v_fmac_f32_e32 v12, 0x3f317217, v9
	v_cmp_lt_f32_e64 s[38:39], |v9|, s2
	s_nop 1
	v_cndmask_b32_e64 v9, v9, v12, s[38:39]
	v_mov_b32_e32 v12, 0x41b17218
	v_cndmask_b32_e32 v12, 0, v12, vcc
	v_sub_f32_e32 v9, v9, v12
	v_sub_f32_e32 v9, v11, v9
.LBB0_6969:
	s_andn2_saveexec_b64 s[22:23], s[22:23]
	s_cbranch_execz .LBB0_6972
	v_mad_i64_i32 v[12:13], s[6:7], s60, v59, 0
	v_lshl_add_u64 v[12:13], v[12:13], 2, s[20:21]
	v_mov_b32_e32 v9, v232
	s_andn2_b64 vcc, exec, s[62:63]
	s_cbranch_vccnz .LBB0_6972
	s_mov_b32 s2, 0xbfb8aa3b
	s_waitcnt vmcnt(0)
	v_mul_f32_e64 v11, |v9|, s2
	v_exp_f32_e32 v11, v11
	s_mov_b32 s2, 0x800000
	s_mov_b32 s5, 0x7f800000
	v_max_f32_e32 v9, v9, v9
	v_add_f32_e32 v11, 1.0, v11
	v_cmp_gt_f32_e32 vcc, s2, v11
	s_mov_b32 s2, 0x3f317217
	v_min_f32_e32 v9, 0, v9
	v_cndmask_b32_e64 v12, 0, 32, vcc
	v_ldexp_f32 v11, v11, v12
	v_log_f32_e32 v11, v11
	s_nop 0
	v_mul_f32_e32 v12, 0x3f317217, v11
	v_fma_f32 v12, v11, s2, -v12
	v_fmamk_f32 v12, v11, 0x3377d1cf, v12
	v_fmac_f32_e32 v12, 0x3f317217, v11
	v_cmp_lt_f32_e64 s[38:39], |v11|, s5
	s_nop 1
	v_cndmask_b32_e64 v11, v11, v12, s[38:39]
	v_mov_b32_e32 v12, 0x41b17218
	v_cndmask_b32_e32 v12, 0, v12, vcc
	v_sub_f32_e32 v11, v11, v12
	v_sub_f32_e32 v9, v9, v11

.LBB0_6973:
	s_or_b64 exec, exec, s[0:1]
	v_or_b32_e32 v60, 9, v51
	s_and_saveexec_b64 s[0:1], s[36:37]
	s_cbranch_execz .LBB0_6980
	v_cmp_le_i32_e32 vcc, s4, v60
	s_and_saveexec_b64 s[6:7], vcc
	s_xor_b64 s[22:23], exec, s[6:7]
	s_cbranch_execz .LBB0_6976
	v_subrev_u32_e32 v10, s4, v60
	v_mov_b32_e32 v11, 0
	v_lshl_add_u64 v[10:11], v[10:11], 2, s[64:65]
	v_mov_b32_e32 v10, v233
	s_mov_b32 s2, 0xbfb8aa3b
	s_waitcnt vmcnt(0)
	v_max_f32_e32 v11, v10, v10
	v_mul_f32_e64 v10, |v10|, s2
	v_exp_f32_e32 v10, v10
	s_mov_b32 s2, 0x800000
	v_min_f32_e32 v11, 0, v11
	v_add_f32_e32 v10, 1.0, v10
	v_cmp_gt_f32_e32 vcc, s2, v10
	s_mov_b32 s2, 0x3f317217
	s_nop 0
	v_cndmask_b32_e64 v12, 0, 32, vcc
	v_ldexp_f32 v10, v10, v12
	v_log_f32_e32 v10, v10
	s_nop 0
	v_mul_f32_e32 v12, 0x3f317217, v10
	v_fma_f32 v12, v10, s2, -v12
	v_fmamk_f32 v12, v10, 0x3377d1cf, v12
	s_mov_b32 s2, 0x7f800000
	v_fmac_f32_e32 v12, 0x3f317217, v10
	v_cmp_lt_f32_e64 s[38:39], |v10|, s2
	s_nop 1
	v_cndmask_b32_e64 v10, v10, v12, s[38:39]
	v_mov_b32_e32 v12, 0x41b17218
	v_cndmask_b32_e32 v12, 0, v12, vcc
	v_sub_f32_e32 v10, v10, v12
	v_sub_f32_e32 v10, v11, v10
.LBB0_6976:
	s_andn2_saveexec_b64 s[22:23], s[22:23]
	s_cbranch_execz .LBB0_6979
	v_mad_i64_i32 v[10:11], s[6:7], s60, v60, 0
	v_lshl_add_u64 v[10:11], v[10:11], 2, s[20:21]
	v_mov_b32_e32 v10, v233
	s_andn2_b64 vcc, exec, s[62:63]
	s_cbranch_vccnz .LBB0_6979
	s_mov_b32 s2, 0xbfb8aa3b
	s_waitcnt vmcnt(0)
	v_mul_f32_e64 v11, |v10|, s2
	v_exp_f32_e32 v11, v11
	s_mov_b32 s2, 0x800000
	s_mov_b32 s5, 0x7f800000
	v_max_f32_e32 v10, v10, v10
	v_add_f32_e32 v11, 1.0, v11
	v_cmp_gt_f32_e32 vcc, s2, v11
	s_mov_b32 s2, 0x3f317217
	v_min_f32_e32 v10, 0, v10
	v_cndmask_b32_e64 v12, 0, 32, vcc
	v_ldexp_f32 v11, v11, v12
	v_log_f32_e32 v11, v11
	s_nop 0
	v_mul_f32_e32 v12, 0x3f317217, v11
	v_fma_f32 v12, v11, s2, -v12
	v_fmamk_f32 v12, v11, 0x3377d1cf, v12
	v_fmac_f32_e32 v12, 0x3f317217, v11
	v_cmp_lt_f32_e64 s[38:39], |v11|, s5
	s_nop 1
	v_cndmask_b32_e64 v11, v11, v12, s[38:39]
	v_mov_b32_e32 v12, 0x41b17218
	v_cndmask_b32_e32 v12, 0, v12, vcc
	v_sub_f32_e32 v11, v11, v12
	v_sub_f32_e32 v10, v10, v11

.LBB0_6980:
	s_or_b64 exec, exec, s[0:1]
	v_or_b32_e32 v62, 10, v51
	v_mov_b32_e32 v12, 0
	v_mov_b32_e32 v11, 0
	s_and_saveexec_b64 s[0:1], s[36:37]
	s_cbranch_execz .LBB0_6987
	v_cmp_le_i32_e32 vcc, s4, v62
	s_and_saveexec_b64 s[6:7], vcc
	s_xor_b64 s[22:23], exec, s[6:7]
	s_cbranch_execz .LBB0_6983
	v_subrev_u32_e32 v14, s4, v62
	v_mov_b32_e32 v15, 0
	v_lshl_add_u64 v[14:15], v[14:15], 2, s[64:65]
	v_mov_b32_e32 v11, v234
	s_mov_b32 s2, 0xbfb8aa3b
	s_waitcnt vmcnt(0)
	v_max_f32_e32 v13, v11, v11
	v_mul_f32_e64 v11, |v11|, s2
	v_exp_f32_e32 v11, v11
	s_mov_b32 s2, 0x800000
	v_min_f32_e32 v13, 0, v13
	v_add_f32_e32 v11, 1.0, v11
	v_cmp_gt_f32_e32 vcc, s2, v11
	s_mov_b32 s2, 0x3f317217
	s_nop 0
	v_cndmask_b32_e64 v14, 0, 32, vcc
	v_ldexp_f32 v11, v11, v14
	v_log_f32_e32 v11, v11
	s_nop 0
	v_mul_f32_e32 v14, 0x3f317217, v11
	v_fma_f32 v14, v11, s2, -v14
	v_fmamk_f32 v14, v11, 0x3377d1cf, v14
	s_mov_b32 s2, 0x7f800000
	v_fmac_f32_e32 v14, 0x3f317217, v11
	v_cmp_lt_f32_e64 s[38:39], |v11|, s2
	s_nop 1
	v_cndmask_b32_e64 v11, v11, v14, s[38:39]
	v_mov_b32_e32 v14, 0x41b17218
	v_cndmask_b32_e32 v14, 0, v14, vcc
	v_sub_f32_e32 v11, v11, v14
	v_sub_f32_e32 v11, v13, v11
.LBB0_6983:
	s_andn2_saveexec_b64 s[22:23], s[22:23]
	s_cbranch_execz .LBB0_6986
	v_mad_i64_i32 v[14:15], s[6:7], s60, v62, 0
	v_lshl_add_u64 v[14:15], v[14:15], 2, s[20:21]
	v_mov_b32_e32 v11, v234
	s_andn2_b64 vcc, exec, s[62:63]
	s_cbranch_vccnz .LBB0_6986
	s_mov_b32 s2, 0xbfb8aa3b
	s_waitcnt vmcnt(0)
	v_mul_f32_e64 v13, |v11|, s2
	v_exp_f32_e32 v13, v13
	s_mov_b32 s2, 0x800000
	s_mov_b32 s5, 0x7f800000
	v_max_f32_e32 v11, v11, v11
	v_add_f32_e32 v13, 1.0, v13
	v_cmp_gt_f32_e32 vcc, s2, v13
	s_mov_b32 s2, 0x3f317217
	v_min_f32_e32 v11, 0, v11
	v_cndmask_b32_e64 v14, 0, 32, vcc
	v_ldexp_f32 v13, v13, v14
	v_log_f32_e32 v13, v13
	s_nop 0
	v_mul_f32_e32 v14, 0x3f317217, v13
	v_fma_f32 v14, v13, s2, -v14
	v_fmamk_f32 v14, v13, 0x3377d1cf, v14
	v_fmac_f32_e32 v14, 0x3f317217, v13
	v_cmp_lt_f32_e64 s[38:39], |v13|, s5
	s_nop 1
	v_cndmask_b32_e64 v13, v13, v14, s[38:39]
	v_mov_b32_e32 v14, 0x41b17218
	v_cndmask_b32_e32 v14, 0, v14, vcc
	v_sub_f32_e32 v13, v13, v14
	v_sub_f32_e32 v11, v11, v13

.LBB0_6987:
	s_or_b64 exec, exec, s[0:1]
	v_or_b32_e32 v61, 11, v51
	s_and_saveexec_b64 s[0:1], s[36:37]
	s_cbranch_execz .LBB0_6994
	v_cmp_le_i32_e32 vcc, s4, v61
	s_and_saveexec_b64 s[6:7], vcc
	s_xor_b64 s[22:23], exec, s[6:7]
	s_cbranch_execz .LBB0_6990
	v_subrev_u32_e32 v12, s4, v61
	v_mov_b32_e32 v13, 0
	v_lshl_add_u64 v[12:13], v[12:13], 2, s[64:65]
	v_mov_b32_e32 v12, v235
	s_mov_b32 s2, 0xbfb8aa3b
	s_waitcnt vmcnt(0)
	v_max_f32_e32 v13, v12, v12
	v_mul_f32_e64 v12, |v12|, s2
	v_exp_f32_e32 v12, v12
	s_mov_b32 s2, 0x800000
	v_min_f32_e32 v13, 0, v13
	v_add_f32_e32 v12, 1.0, v12
	v_cmp_gt_f32_e32 vcc, s2, v12
	s_mov_b32 s2, 0x3f317217
	s_nop 0
	v_cndmask_b32_e64 v14, 0, 32, vcc
	v_ldexp_f32 v12, v12, v14
	v_log_f32_e32 v12, v12
	s_nop 0
	v_mul_f32_e32 v14, 0x3f317217, v12
	v_fma_f32 v14, v12, s2, -v14
	v_fmamk_f32 v14, v12, 0x3377d1cf, v14
	s_mov_b32 s2, 0x7f800000
	v_fmac_f32_e32 v14, 0x3f317217, v12
	v_cmp_lt_f32_e64 s[38:39], |v12|, s2
	s_nop 1
	v_cndmask_b32_e64 v12, v12, v14, s[38:39]
	v_mov_b32_e32 v14, 0x41b17218
	v_cndmask_b32_e32 v14, 0, v14, vcc
	v_sub_f32_e32 v12, v12, v14
	v_sub_f32_e32 v12, v13, v12
.LBB0_6990:
	s_andn2_saveexec_b64 s[22:23], s[22:23]
	s_cbranch_execz .LBB0_6993
	v_mad_i64_i32 v[12:13], s[6:7], s60, v61, 0
	v_lshl_add_u64 v[12:13], v[12:13], 2, s[20:21]
	v_mov_b32_e32 v12, v235
	s_andn2_b64 vcc, exec, s[62:63]
	s_cbranch_vccnz .LBB0_6993
	s_mov_b32 s2, 0xbfb8aa3b
	s_waitcnt vmcnt(0)
	v_mul_f32_e64 v13, |v12|, s2
	v_exp_f32_e32 v13, v13
	s_mov_b32 s2, 0x800000
	s_mov_b32 s5, 0x7f800000
	v_max_f32_e32 v12, v12, v12
	v_add_f32_e32 v13, 1.0, v13
	v_cmp_gt_f32_e32 vcc, s2, v13
	s_mov_b32 s2, 0x3f317217
	v_min_f32_e32 v12, 0, v12
	v_cndmask_b32_e64 v14, 0, 32, vcc
	v_ldexp_f32 v13, v13, v14
	v_log_f32_e32 v13, v13
	s_nop 0
	v_mul_f32_e32 v14, 0x3f317217, v13
	v_fma_f32 v14, v13, s2, -v14
	v_fmamk_f32 v14, v13, 0x3377d1cf, v14
	v_fmac_f32_e32 v14, 0x3f317217, v13
	v_cmp_lt_f32_e64 s[38:39], |v13|, s5
	s_nop 1
	v_cndmask_b32_e64 v13, v13, v14, s[38:39]
	v_mov_b32_e32 v14, 0x41b17218
	v_cndmask_b32_e32 v14, 0, v14, vcc
	v_sub_f32_e32 v13, v13, v14
	v_sub_f32_e32 v12, v12, v13

.LBB0_6994:
	s_or_b64 exec, exec, s[0:1]
	v_or_b32_e32 v63, 12, v51
	v_mov_b32_e32 v14, 0
	v_mov_b32_e32 v13, 0
	s_and_saveexec_b64 s[0:1], s[36:37]
	s_cbranch_execz .LBB0_7001
	v_cmp_le_i32_e32 vcc, s4, v63
	s_and_saveexec_b64 s[6:7], vcc
	s_xor_b64 s[22:23], exec, s[6:7]
	s_cbranch_execz .LBB0_6997
	v_subrev_u32_e32 v16, s4, v63
	v_mov_b32_e32 v17, 0
	v_lshl_add_u64 v[16:17], v[16:17], 2, s[64:65]
	v_mov_b32_e32 v13, v236
	s_mov_b32 s2, 0xbfb8aa3b
	s_waitcnt vmcnt(0)
	v_max_f32_e32 v15, v13, v13
	v_mul_f32_e64 v13, |v13|, s2
	v_exp_f32_e32 v13, v13
	s_mov_b32 s2, 0x800000
	v_min_f32_e32 v15, 0, v15
	v_add_f32_e32 v13, 1.0, v13
	v_cmp_gt_f32_e32 vcc, s2, v13
	s_mov_b32 s2, 0x3f317217
	s_nop 0
	v_cndmask_b32_e64 v16, 0, 32, vcc
	v_ldexp_f32 v13, v13, v16
	v_log_f32_e32 v13, v13
	s_nop 0
	v_mul_f32_e32 v16, 0x3f317217, v13
	v_fma_f32 v16, v13, s2, -v16
	v_fmamk_f32 v16, v13, 0x3377d1cf, v16
	s_mov_b32 s2, 0x7f800000
	v_fmac_f32_e32 v16, 0x3f317217, v13
	v_cmp_lt_f32_e64 s[38:39], |v13|, s2
	s_nop 1
	v_cndmask_b32_e64 v13, v13, v16, s[38:39]
	v_mov_b32_e32 v16, 0x41b17218
	v_cndmask_b32_e32 v16, 0, v16, vcc
	v_sub_f32_e32 v13, v13, v16
	v_sub_f32_e32 v13, v15, v13
.LBB0_6997:
	s_andn2_saveexec_b64 s[22:23], s[22:23]
	s_cbranch_execz .LBB0_7000
	v_mad_i64_i32 v[16:17], s[6:7], s60, v63, 0
	v_lshl_add_u64 v[16:17], v[16:17], 2, s[20:21]
	v_mov_b32_e32 v13, v236
	s_andn2_b64 vcc, exec, s[62:63]
	s_cbranch_vccnz .LBB0_7000
	s_mov_b32 s2, 0xbfb8aa3b
	s_waitcnt vmcnt(0)
	v_mul_f32_e64 v15, |v13|, s2
	v_exp_f32_e32 v15, v15
	s_mov_b32 s2, 0x800000
	s_mov_b32 s5, 0x7f800000
	v_max_f32_e32 v13, v13, v13
	v_add_f32_e32 v15, 1.0, v15
	v_cmp_gt_f32_e32 vcc, s2, v15
	s_mov_b32 s2, 0x3f317217
	v_min_f32_e32 v13, 0, v13
	v_cndmask_b32_e64 v16, 0, 32, vcc
	v_ldexp_f32 v15, v15, v16
	v_log_f32_e32 v15, v15
	s_nop 0
	v_mul_f32_e32 v16, 0x3f317217, v15
	v_fma_f32 v16, v15, s2, -v16
	v_fmamk_f32 v16, v15, 0x3377d1cf, v16
	v_fmac_f32_e32 v16, 0x3f317217, v15
	v_cmp_lt_f32_e64 s[38:39], |v15|, s5
	s_nop 1
	v_cndmask_b32_e64 v15, v15, v16, s[38:39]
	v_mov_b32_e32 v16, 0x41b17218
	v_cndmask_b32_e32 v16, 0, v16, vcc
	v_sub_f32_e32 v15, v15, v16
	v_sub_f32_e32 v13, v13, v15

.LBB0_7001:
	s_or_b64 exec, exec, s[0:1]
	v_or_b32_e32 v64, 13, v51
	s_and_saveexec_b64 s[0:1], s[36:37]
	s_cbranch_execz .LBB0_7008
	v_cmp_le_i32_e32 vcc, s4, v64
	s_and_saveexec_b64 s[6:7], vcc
	s_xor_b64 s[22:23], exec, s[6:7]
	s_cbranch_execz .LBB0_7004
	v_subrev_u32_e32 v14, s4, v64
	v_mov_b32_e32 v15, 0
	v_lshl_add_u64 v[14:15], v[14:15], 2, s[64:65]
	v_mov_b32_e32 v14, v237
	s_mov_b32 s2, 0xbfb8aa3b
	s_waitcnt vmcnt(0)
	v_max_f32_e32 v15, v14, v14
	v_mul_f32_e64 v14, |v14|, s2
	v_exp_f32_e32 v14, v14
	s_mov_b32 s2, 0x800000
	v_min_f32_e32 v15, 0, v15
	v_add_f32_e32 v14, 1.0, v14
	v_cmp_gt_f32_e32 vcc, s2, v14
	s_mov_b32 s2, 0x3f317217
	s_nop 0
	v_cndmask_b32_e64 v16, 0, 32, vcc
	v_ldexp_f32 v14, v14, v16
	v_log_f32_e32 v14, v14
	s_nop 0
	v_mul_f32_e32 v16, 0x3f317217, v14
	v_fma_f32 v16, v14, s2, -v16
	v_fmamk_f32 v16, v14, 0x3377d1cf, v16
	s_mov_b32 s2, 0x7f800000
	v_fmac_f32_e32 v16, 0x3f317217, v14
	v_cmp_lt_f32_e64 s[38:39], |v14|, s2
	s_nop 1
	v_cndmask_b32_e64 v14, v14, v16, s[38:39]
	v_mov_b32_e32 v16, 0x41b17218
	v_cndmask_b32_e32 v16, 0, v16, vcc
	v_sub_f32_e32 v14, v14, v16
	v_sub_f32_e32 v14, v15, v14
.LBB0_7004:
	s_andn2_saveexec_b64 s[22:23], s[22:23]
	s_cbranch_execz .LBB0_7007
	v_mad_i64_i32 v[14:15], s[6:7], s60, v64, 0
	v_lshl_add_u64 v[14:15], v[14:15], 2, s[20:21]
	v_mov_b32_e32 v14, v237
	s_andn2_b64 vcc, exec, s[62:63]
	s_cbranch_vccnz .LBB0_7007
	s_mov_b32 s2, 0xbfb8aa3b
	s_waitcnt vmcnt(0)
	v_mul_f32_e64 v15, |v14|, s2
	v_exp_f32_e32 v15, v15
	s_mov_b32 s2, 0x800000
	s_mov_b32 s5, 0x7f800000
	v_max_f32_e32 v14, v14, v14
	v_add_f32_e32 v15, 1.0, v15
	v_cmp_gt_f32_e32 vcc, s2, v15
	s_mov_b32 s2, 0x3f317217
	v_min_f32_e32 v14, 0, v14
	v_cndmask_b32_e64 v16, 0, 32, vcc
	v_ldexp_f32 v15, v15, v16
	v_log_f32_e32 v15, v15
	s_nop 0
	v_mul_f32_e32 v16, 0x3f317217, v15
	v_fma_f32 v16, v15, s2, -v16
	v_fmamk_f32 v16, v15, 0x3377d1cf, v16
	v_fmac_f32_e32 v16, 0x3f317217, v15
	v_cmp_lt_f32_e64 s[38:39], |v15|, s5
	s_nop 1
	v_cndmask_b32_e64 v15, v15, v16, s[38:39]
	v_mov_b32_e32 v16, 0x41b17218
	v_cndmask_b32_e32 v16, 0, v16, vcc
	v_sub_f32_e32 v15, v15, v16
	v_sub_f32_e32 v14, v14, v15

.LBB0_7008:
	s_or_b64 exec, exec, s[0:1]
	v_or_b32_e32 v65, 14, v51
	v_mov_b32_e32 v16, 0
	v_mov_b32_e32 v15, 0
	s_and_saveexec_b64 s[0:1], s[36:37]
	s_cbranch_execz .LBB0_7015
	v_cmp_le_i32_e32 vcc, s4, v65
	s_and_saveexec_b64 s[6:7], vcc
	s_xor_b64 s[22:23], exec, s[6:7]
	s_cbranch_execz .LBB0_7011
	v_subrev_u32_e32 v18, s4, v65
	v_mov_b32_e32 v19, 0
	v_lshl_add_u64 v[18:19], v[18:19], 2, s[64:65]
	v_mov_b32_e32 v15, v238
	s_mov_b32 s2, 0xbfb8aa3b
	s_waitcnt vmcnt(0)
	v_max_f32_e32 v17, v15, v15
	v_mul_f32_e64 v15, |v15|, s2
	v_exp_f32_e32 v15, v15
	s_mov_b32 s2, 0x800000
	v_min_f32_e32 v17, 0, v17
	v_add_f32_e32 v15, 1.0, v15
	v_cmp_gt_f32_e32 vcc, s2, v15
	s_mov_b32 s2, 0x3f317217
	s_nop 0
	v_cndmask_b32_e64 v18, 0, 32, vcc
	v_ldexp_f32 v15, v15, v18
	v_log_f32_e32 v15, v15
	s_nop 0
	v_mul_f32_e32 v18, 0x3f317217, v15
	v_fma_f32 v18, v15, s2, -v18
	v_fmamk_f32 v18, v15, 0x3377d1cf, v18
	s_mov_b32 s2, 0x7f800000
	v_fmac_f32_e32 v18, 0x3f317217, v15
	v_cmp_lt_f32_e64 s[38:39], |v15|, s2
	s_nop 1
	v_cndmask_b32_e64 v15, v15, v18, s[38:39]
	v_mov_b32_e32 v18, 0x41b17218
	v_cndmask_b32_e32 v18, 0, v18, vcc
	v_sub_f32_e32 v15, v15, v18
	v_sub_f32_e32 v15, v17, v15
.LBB0_7011:
	s_andn2_saveexec_b64 s[22:23], s[22:23]
	s_cbranch_execz .LBB0_7014
	v_mad_i64_i32 v[18:19], s[6:7], s60, v65, 0
	v_lshl_add_u64 v[18:19], v[18:19], 2, s[20:21]
	v_mov_b32_e32 v15, v238
	s_andn2_b64 vcc, exec, s[62:63]
	s_cbranch_vccnz .LBB0_7014
	s_mov_b32 s2, 0xbfb8aa3b
	s_waitcnt vmcnt(0)
	v_mul_f32_e64 v17, |v15|, s2
	v_exp_f32_e32 v17, v17
	s_mov_b32 s2, 0x800000
	s_mov_b32 s5, 0x7f800000
	v_max_f32_e32 v15, v15, v15
	v_add_f32_e32 v17, 1.0, v17
	v_cmp_gt_f32_e32 vcc, s2, v17
	s_mov_b32 s2, 0x3f317217
	v_min_f32_e32 v15, 0, v15
	v_cndmask_b32_e64 v18, 0, 32, vcc
	v_ldexp_f32 v17, v17, v18
	v_log_f32_e32 v17, v17
	s_nop 0
	v_mul_f32_e32 v18, 0x3f317217, v17
	v_fma_f32 v18, v17, s2, -v18
	v_fmamk_f32 v18, v17, 0x3377d1cf, v18
	v_fmac_f32_e32 v18, 0x3f317217, v17
	v_cmp_lt_f32_e64 s[38:39], |v17|, s5
	s_nop 1
	v_cndmask_b32_e64 v17, v17, v18, s[38:39]
	v_mov_b32_e32 v18, 0x41b17218
	v_cndmask_b32_e32 v18, 0, v18, vcc
	v_sub_f32_e32 v17, v17, v18
	v_sub_f32_e32 v15, v15, v17

.LBB0_7015:
	s_or_b64 exec, exec, s[0:1]
	v_or_b32_e32 v66, 15, v51
	s_and_saveexec_b64 s[0:1], s[36:37]
	s_cbranch_execz .LBB0_7022
	v_cmp_le_i32_e32 vcc, s4, v66
	s_and_saveexec_b64 s[6:7], vcc
	s_xor_b64 s[22:23], exec, s[6:7]
	s_cbranch_execz .LBB0_7018
	v_subrev_u32_e32 v16, s4, v66
	v_mov_b32_e32 v17, 0
	v_lshl_add_u64 v[16:17], v[16:17], 2, s[64:65]
	v_mov_b32_e32 v16, v239
	s_mov_b32 s2, 0xbfb8aa3b
	s_waitcnt vmcnt(0)
	v_max_f32_e32 v17, v16, v16
	v_mul_f32_e64 v16, |v16|, s2
	v_exp_f32_e32 v16, v16
	s_mov_b32 s2, 0x800000
	v_min_f32_e32 v17, 0, v17
	v_add_f32_e32 v16, 1.0, v16
	v_cmp_gt_f32_e32 vcc, s2, v16
	s_mov_b32 s2, 0x3f317217
	s_nop 0
	v_cndmask_b32_e64 v18, 0, 32, vcc
	v_ldexp_f32 v16, v16, v18
	v_log_f32_e32 v16, v16
	s_nop 0
	v_mul_f32_e32 v18, 0x3f317217, v16
	v_fma_f32 v18, v16, s2, -v18
	v_fmamk_f32 v18, v16, 0x3377d1cf, v18
	s_mov_b32 s2, 0x7f800000
	v_fmac_f32_e32 v18, 0x3f317217, v16
	v_cmp_lt_f32_e64 s[38:39], |v16|, s2
	s_nop 1
	v_cndmask_b32_e64 v16, v16, v18, s[38:39]
	v_mov_b32_e32 v18, 0x41b17218
	v_cndmask_b32_e32 v18, 0, v18, vcc
	v_sub_f32_e32 v16, v16, v18
	v_sub_f32_e32 v16, v17, v16
.LBB0_7018:
	s_andn2_saveexec_b64 s[22:23], s[22:23]
	s_cbranch_execz .LBB0_7021
	v_mad_i64_i32 v[16:17], s[4:5], s60, v66, 0
	v_lshl_add_u64 v[16:17], v[16:17], 2, s[20:21]
	v_mov_b32_e32 v16, v239
	s_andn2_b64 vcc, exec, s[62:63]
	s_cbranch_vccnz .LBB0_7021
	s_mov_b32 s2, 0xbfb8aa3b
	s_waitcnt vmcnt(0)
	v_mul_f32_e64 v17, |v16|, s2
	v_exp_f32_e32 v17, v17
	s_mov_b32 s2, 0x800000
	s_mov_b32 s4, 0x7f800000
	v_max_f32_e32 v16, v16, v16
	v_add_f32_e32 v17, 1.0, v17
	v_cmp_gt_f32_e32 vcc, s2, v17
	s_mov_b32 s2, 0x3f317217
	v_min_f32_e32 v16, 0, v16
	v_cndmask_b32_e64 v18, 0, 32, vcc
	v_ldexp_f32 v17, v17, v18
	v_log_f32_e32 v17, v17
	s_nop 0
	v_mul_f32_e32 v18, 0x3f317217, v17
	v_fma_f32 v18, v17, s2, -v18
	v_fmamk_f32 v18, v17, 0x3377d1cf, v18
	v_fmac_f32_e32 v18, 0x3f317217, v17
	v_cmp_lt_f32_e64 s[38:39], |v17|, s4
	s_nop 1
	v_cndmask_b32_e64 v17, v17, v18, s[38:39]
	v_mov_b32_e32 v18, 0x41b17218
	v_cndmask_b32_e32 v18, 0, v18, vcc
	v_sub_f32_e32 v17, v17, v18
	v_sub_f32_e32 v16, v16, v17

.LBB0_7088:
	s_lshr_b32 s46, s91, 6
	s_add_i32 s46, s46, 4
	s_lshr_b32 s47, s23, 6
	s_xor_b32 s63, s30, 1
	s_min_u32 s46, s46, s47
	s_andn2_b64 vcc, exec, s[38:39]
	v_readlane_b32 s38, v253, 7
	s_mov_b64 s[76:77], -1
	s_lshl_b32 s82, s63, 15
	s_lshl_b32 s47, s46, 6
	v_mbcnt_lo_u32_b32 v2, -1, 0
	v_mbcnt_hi_u32_b32 v2, -1, v2
	s_nop 0
	v_add_u32_e32 v1, s38, v2
	s_cbranch_vccz .LBB0_7236
	v_lshlrev_b32_e32 v50, 4, v1
	s_xor_b64 s[76:77], s[36:37], -1
	v_cmp_gt_i32_e64 s[36:37], s47, v50
	v_mov_b32_e32 v3, 0
	v_mov_b32_e32 v6, 0
	s_and_saveexec_b64 s[98:99], s[36:37]
	v_mov_b32_e32 v247, 0
	v_subrev_u32_e32 v246, s28, v50
	v_mad_i64_i32 v[244:245], s[100:101], s22, v50, 0
	v_lshl_add_u64 v[242:243], v[246:247], 2, s[26:27]
	v_cmp_le_i32_e64 s[100:101], s28, v50
	v_lshl_add_u64 v[244:245], v[244:245], 2, s[0:1]
	s_nop 1
	v_cndmask_b32_e64 v242, v244, v242, s[100:101]
	v_cndmask_b32_e64 v243, v245, v243, s[100:101]
	global_load_dword v224, v[242:243], off
	v_or_b32_e32 v240, 1, v50
	v_subrev_u32_e32 v246, s28, v240
	v_mad_i64_i32 v[244:245], s[100:101], s22, v240, 0
	v_lshl_add_u64 v[242:243], v[246:247], 2, s[26:27]
	v_cmp_le_i32_e64 s[100:101], s28, v240
	v_lshl_add_u64 v[244:245], v[244:245], 2, s[0:1]
	s_nop 1
	v_cndmask_b32_e64 v242, v244, v242, s[100:101]
	v_cndmask_b32_e64 v243, v245, v243, s[100:101]
	global_load_dword v225, v[242:243], off
	v_or_b32_e32 v240, 2, v50
	v_subrev_u32_e32 v246, s28, v240
	v_mad_i64_i32 v[244:245], s[100:101], s22, v240, 0
	v_lshl_add_u64 v[242:243], v[246:247], 2, s[26:27]
	v_cmp_le_i32_e64 s[100:101], s28, v240
	v_lshl_add_u64 v[244:245], v[244:245], 2, s[0:1]
	s_nop 1
	v_cndmask_b32_e64 v242, v244, v242, s[100:101]
	v_cndmask_b32_e64 v243, v245, v243, s[100:101]
	global_load_dword v226, v[242:243], off
	v_or_b32_e32 v240, 3, v50
	v_subrev_u32_e32 v246, s28, v240
	v_mad_i64_i32 v[244:245], s[100:101], s22, v240, 0
	v_lshl_add_u64 v[242:243], v[246:247], 2, s[26:27]
	v_cmp_le_i32_e64 s[100:101], s28, v240
	v_lshl_add_u64 v[244:245], v[244:245], 2, s[0:1]
	s_nop 1
	v_cndmask_b32_e64 v242, v244, v242, s[100:101]
	v_cndmask_b32_e64 v243, v245, v243, s[100:101]
	global_load_dword v227, v[242:243], off
	v_or_b32_e32 v240, 4, v50
	v_subrev_u32_e32 v246, s28, v240
	v_mad_i64_i32 v[244:245], s[100:101], s22, v240, 0
	v_lshl_add_u64 v[242:243], v[246:247], 2, s[26:27]
	v_cmp_le_i32_e64 s[100:101], s28, v240
	v_lshl_add_u64 v[244:245], v[244:245], 2, s[0:1]
	s_nop 1
	v_cndmask_b32_e64 v242, v244, v242, s[100:101]
	v_cndmask_b32_e64 v243, v245, v243, s[100:101]
	global_load_dword v228, v[242:243], off
	v_or_b32_e32 v240, 5, v50
	v_subrev_u32_e32 v246, s28, v240
	v_mad_i64_i32 v[244:245], s[100:101], s22, v240, 0
	v_lshl_add_u64 v[242:243], v[246:247], 2, s[26:27]
	v_cmp_le_i32_e64 s[100:101], s28, v240
	v_lshl_add_u64 v[244:245], v[244:245], 2, s[0:1]
	s_nop 1
	v_cndmask_b32_e64 v242, v244, v242, s[100:101]
	v_cndmask_b32_e64 v243, v245, v243, s[100:101]
	global_load_dword v229, v[242:243], off
	v_or_b32_e32 v240, 6, v50
	v_subrev_u32_e32 v246, s28, v240
	v_mad_i64_i32 v[244:245], s[100:101], s22, v240, 0
	v_lshl_add_u64 v[242:243], v[246:247], 2, s[26:27]
	v_cmp_le_i32_e64 s[100:101], s28, v240
	v_lshl_add_u64 v[244:245], v[244:245], 2, s[0:1]
	s_nop 1
	v_cndmask_b32_e64 v242, v244, v242, s[100:101]
	v_cndmask_b32_e64 v243, v245, v243, s[100:101]
	global_load_dword v230, v[242:243], off
	v_or_b32_e32 v240, 7, v50
	v_subrev_u32_e32 v246, s28, v240
	v_mad_i64_i32 v[244:245], s[100:101], s22, v240, 0
	v_lshl_add_u64 v[242:243], v[246:247], 2, s[26:27]
	v_cmp_le_i32_e64 s[100:101], s28, v240
	v_lshl_add_u64 v[244:245], v[244:245], 2, s[0:1]
	s_nop 1
	v_cndmask_b32_e64 v242, v244, v242, s[100:101]
	v_cndmask_b32_e64 v243, v245, v243, s[100:101]
	global_load_dword v231, v[242:243], off
	v_or_b32_e32 v240, 8, v50
	v_subrev_u32_e32 v246, s28, v240
	v_mad_i64_i32 v[244:245], s[100:101], s22, v240, 0
	v_lshl_add_u64 v[242:243], v[246:247], 2, s[26:27]
	v_cmp_le_i32_e64 s[100:101], s28, v240
	v_lshl_add_u64 v[244:245], v[244:245], 2, s[0:1]
	s_nop 1
	v_cndmask_b32_e64 v242, v244, v242, s[100:101]
	v_cndmask_b32_e64 v243, v245, v243, s[100:101]
	global_load_dword v232, v[242:243], off
	v_or_b32_e32 v240, 9, v50
	v_subrev_u32_e32 v246, s28, v240
	v_mad_i64_i32 v[244:245], s[100:101], s22, v240, 0
	v_lshl_add_u64 v[242:243], v[246:247], 2, s[26:27]
	v_cmp_le_i32_e64 s[100:101], s28, v240
	v_lshl_add_u64 v[244:245], v[244:245], 2, s[0:1]
	s_nop 1
	v_cndmask_b32_e64 v242, v244, v242, s[100:101]
	v_cndmask_b32_e64 v243, v245, v243, s[100:101]
	global_load_dword v233, v[242:243], off
	v_or_b32_e32 v240, 10, v50
	v_subrev_u32_e32 v246, s28, v240
	v_mad_i64_i32 v[244:245], s[100:101], s22, v240, 0
	v_lshl_add_u64 v[242:243], v[246:247], 2, s[26:27]
	v_cmp_le_i32_e64 s[100:101], s28, v240
	v_lshl_add_u64 v[244:245], v[244:245], 2, s[0:1]
	s_nop 1
	v_cndmask_b32_e64 v242, v244, v242, s[100:101]
	v_cndmask_b32_e64 v243, v245, v243, s[100:101]
	global_load_dword v234, v[242:243], off
	v_or_b32_e32 v240, 11, v50
	v_subrev_u32_e32 v246, s28, v240
	v_mad_i64_i32 v[244:245], s[100:101], s22, v240, 0
	v_lshl_add_u64 v[242:243], v[246:247], 2, s[26:27]
	v_cmp_le_i32_e64 s[100:101], s28, v240
	v_lshl_add_u64 v[244:245], v[244:245], 2, s[0:1]
	s_nop 1
	v_cndmask_b32_e64 v242, v244, v242, s[100:101]
	v_cndmask_b32_e64 v243, v245, v243, s[100:101]
	global_load_dword v235, v[242:243], off
	v_or_b32_e32 v240, 12, v50
	v_subrev_u32_e32 v246, s28, v240
	v_mad_i64_i32 v[244:245], s[100:101], s22, v240, 0
	v_lshl_add_u64 v[242:243], v[246:247], 2, s[26:27]
	v_cmp_le_i32_e64 s[100:101], s28, v240
	v_lshl_add_u64 v[244:245], v[244:245], 2, s[0:1]
	s_nop 1
	v_cndmask_b32_e64 v242, v244, v242, s[100:101]
	v_cndmask_b32_e64 v243, v245, v243, s[100:101]
	global_load_dword v236, v[242:243], off
	v_or_b32_e32 v240, 13, v50
	v_subrev_u32_e32 v246, s28, v240
	v_mad_i64_i32 v[244:245], s[100:101], s22, v240, 0
	v_lshl_add_u64 v[242:243], v[246:247], 2, s[26:27]
	v_cmp_le_i32_e64 s[100:101], s28, v240
	v_lshl_add_u64 v[244:245], v[244:245], 2, s[0:1]
	s_nop 1
	v_cndmask_b32_e64 v242, v244, v242, s[100:101]
	v_cndmask_b32_e64 v243, v245, v243, s[100:101]
	global_load_dword v237, v[242:243], off
	v_or_b32_e32 v240, 14, v50
	v_subrev_u32_e32 v246, s28, v240
	v_mad_i64_i32 v[244:245], s[100:101], s22, v240, 0
	v_lshl_add_u64 v[242:243], v[246:247], 2, s[26:27]
	v_cmp_le_i32_e64 s[100:101], s28, v240
	v_lshl_add_u64 v[244:245], v[244:245], 2, s[0:1]
	s_nop 1
	v_cndmask_b32_e64 v242, v244, v242, s[100:101]
	v_cndmask_b32_e64 v243, v245, v243, s[100:101]
	global_load_dword v238, v[242:243], off
	v_or_b32_e32 v240, 15, v50
	v_subrev_u32_e32 v246, s28, v240
	v_mad_i64_i32 v[244:245], s[100:101], s22, v240, 0
	v_lshl_add_u64 v[242:243], v[246:247], 2, s[26:27]
	v_cmp_le_i32_e64 s[100:101], s28, v240
	v_lshl_add_u64 v[244:245], v[244:245], 2, s[0:1]
	s_nop 1
	v_cndmask_b32_e64 v242, v244, v242, s[100:101]
	v_cndmask_b32_e64 v243, v245, v243, s[100:101]
	global_load_dword v239, v[242:243], off
	s_mov_b64 exec, s[98:99]
	s_waitcnt vmcnt(0)
	s_and_saveexec_b64 s[78:79], s[36:37]
	s_cbranch_execz .LBB0_7096
	v_cmp_le_i32_e32 vcc, s28, v50
	s_and_saveexec_b64 s[38:39], vcc
	s_xor_b64 s[80:81], exec, s[38:39]
	s_cbranch_execz .LBB0_7092
	v_subrev_u32_e32 v196, s28, v50
	v_lshl_add_u64 v[4:5], v[196:197], 2, s[26:27]
	v_mov_b32_e32 v4, v224
	s_waitcnt vmcnt(0)
	v_mul_f32_e64 v5, |v4|, s10
	v_exp_f32_e32 v5, v5
	v_max_f32_e32 v4, v4, v4
	v_min_f32_e32 v4, 0, v4
	v_add_f32_e32 v5, 1.0, v5
	v_cmp_gt_f32_e32 vcc, s11, v5
	s_nop 1
	v_cndmask_b32_e64 v6, 0, 32, vcc
	v_ldexp_f32 v5, v5, v6
	v_log_f32_e32 v5, v5
	s_nop 0
	v_mul_f32_e32 v6, 0x3f317217, v5
	v_fma_f32 v6, v5, s12, -v6
	v_fmac_f32_e32 v6, 0x3377d1cf, v5
	v_fmac_f32_e32 v6, 0x3f317217, v5
	v_cmp_lt_f32_e64 s[38:39], |v5|, s13
	s_nop 1
	v_cndmask_b32_e64 v5, v5, v6, s[38:39]
	v_cndmask_b32_e32 v6, 0, v207, vcc
	v_sub_f32_e32 v5, v5, v6
	v_sub_f32_e32 v6, v4, v5
.LBB0_7092:
	s_andn2_saveexec_b64 s[80:81], s[80:81]
	s_cbranch_execz .LBB0_7095
	v_mad_i64_i32 v[4:5], s[38:39], s22, v50, 0
	v_lshl_add_u64 v[4:5], v[4:5], 2, s[0:1]
	v_mov_b32_e32 v6, v224
	s_andn2_b64 vcc, exec, s[76:77]
	s_cbranch_vccnz .LBB0_7095
	s_waitcnt vmcnt(0)
	v_mul_f32_e64 v4, |v6|, s10
	v_exp_f32_e32 v4, v4
	s_nop 0
	v_add_f32_e32 v4, 1.0, v4
	v_cmp_gt_f32_e32 vcc, s11, v4
	s_nop 1
	v_cndmask_b32_e64 v5, 0, 32, vcc
	v_ldexp_f32 v4, v4, v5
	v_log_f32_e32 v4, v4
	v_max_f32_e32 v5, v6, v6
	v_min_f32_e32 v5, 0, v5
	v_mul_f32_e32 v6, 0x3f317217, v4
	v_fma_f32 v6, v4, s12, -v6
	v_fmac_f32_e32 v6, 0x3377d1cf, v4
	v_fmac_f32_e32 v6, 0x3f317217, v4
	v_cmp_lt_f32_e64 s[38:39], |v4|, s13
	s_nop 1
	v_cndmask_b32_e64 v4, v4, v6, s[38:39]
	v_cndmask_b32_e32 v6, 0, v207, vcc
	v_sub_f32_e32 v4, v4, v6
	v_sub_f32_e32 v6, v5, v4

.LBB0_7096:
	s_or_b64 exec, exec, s[78:79]
	v_or_b32_e32 v51, 1, v50
	s_and_saveexec_b64 s[78:79], s[36:37]
	s_cbranch_execz .LBB0_7103
	v_cmp_le_i32_e32 vcc, s28, v51
	s_and_saveexec_b64 s[38:39], vcc
	s_xor_b64 s[80:81], exec, s[38:39]
	s_cbranch_execz .LBB0_7099
	v_subrev_u32_e32 v196, s28, v51
	v_lshl_add_u64 v[4:5], v[196:197], 2, s[26:27]
	v_mov_b32_e32 v3, v225
	s_waitcnt vmcnt(0)
	v_mul_f32_e64 v4, |v3|, s10
	v_exp_f32_e32 v4, v4
	v_max_f32_e32 v3, v3, v3
	v_min_f32_e32 v3, 0, v3
	v_add_f32_e32 v4, 1.0, v4
	v_cmp_gt_f32_e32 vcc, s11, v4
	s_nop 1
	v_cndmask_b32_e64 v5, 0, 32, vcc
	v_ldexp_f32 v4, v4, v5
	v_log_f32_e32 v4, v4
	s_nop 0
	v_mul_f32_e32 v5, 0x3f317217, v4
	v_fma_f32 v5, v4, s12, -v5
	v_fmac_f32_e32 v5, 0x3377d1cf, v4
	v_fmac_f32_e32 v5, 0x3f317217, v4
	v_cmp_lt_f32_e64 s[38:39], |v4|, s13
	s_nop 1
	v_cndmask_b32_e64 v4, v4, v5, s[38:39]
	v_cndmask_b32_e32 v5, 0, v207, vcc
	v_sub_f32_e32 v4, v4, v5
	v_sub_f32_e32 v3, v3, v4
.LBB0_7099:
	s_andn2_saveexec_b64 s[80:81], s[80:81]
	s_cbranch_execz .LBB0_7102
	v_mad_i64_i32 v[4:5], s[38:39], s22, v51, 0
	v_lshl_add_u64 v[4:5], v[4:5], 2, s[0:1]
	v_mov_b32_e32 v3, v225
	s_andn2_b64 vcc, exec, s[76:77]
	s_cbranch_vccnz .LBB0_7102
	s_waitcnt vmcnt(0)
	v_mul_f32_e64 v4, |v3|, s10
	v_exp_f32_e32 v4, v4
	v_max_f32_e32 v3, v3, v3
	v_min_f32_e32 v3, 0, v3
	v_add_f32_e32 v4, 1.0, v4
	v_cmp_gt_f32_e32 vcc, s11, v4
	s_nop 1
	v_cndmask_b32_e64 v5, 0, 32, vcc
	v_ldexp_f32 v4, v4, v5
	v_log_f32_e32 v4, v4
	s_nop 0
	v_mul_f32_e32 v5, 0x3f317217, v4
	v_fma_f32 v5, v4, s12, -v5
	v_fmac_f32_e32 v5, 0x3377d1cf, v4
	v_fmac_f32_e32 v5, 0x3f317217, v4
	v_cmp_lt_f32_e64 s[38:39], |v4|, s13
	s_nop 1
	v_cndmask_b32_e64 v4, v4, v5, s[38:39]
	v_cndmask_b32_e32 v5, 0, v207, vcc
	v_sub_f32_e32 v4, v4, v5
	v_sub_f32_e32 v3, v3, v4

.LBB0_7103:
	s_or_b64 exec, exec, s[78:79]
	v_or_b32_e32 v52, 2, v50
	v_mov_b32_e32 v5, 0
	v_mov_b32_e32 v4, 0
	s_and_saveexec_b64 s[78:79], s[36:37]
	s_cbranch_execz .LBB0_7110
	v_cmp_le_i32_e32 vcc, s28, v52
	s_and_saveexec_b64 s[38:39], vcc
	s_xor_b64 s[80:81], exec, s[38:39]
	s_cbranch_execz .LBB0_7106
	v_subrev_u32_e32 v196, s28, v52
	v_lshl_add_u64 v[8:9], v[196:197], 2, s[26:27]
	v_mov_b32_e32 v4, v226
	s_waitcnt vmcnt(0)
	v_mul_f32_e64 v7, |v4|, s10
	v_exp_f32_e32 v7, v7
	v_max_f32_e32 v4, v4, v4
	v_min_f32_e32 v4, 0, v4
	v_add_f32_e32 v7, 1.0, v7
	v_cmp_gt_f32_e32 vcc, s11, v7
	s_nop 1
	v_cndmask_b32_e64 v8, 0, 32, vcc
	v_ldexp_f32 v7, v7, v8
	v_log_f32_e32 v7, v7
	s_nop 0
	v_mul_f32_e32 v8, 0x3f317217, v7
	v_fma_f32 v8, v7, s12, -v8
	v_fmac_f32_e32 v8, 0x3377d1cf, v7
	v_fmac_f32_e32 v8, 0x3f317217, v7
	v_cmp_lt_f32_e64 s[38:39], |v7|, s13
	s_nop 1
	v_cndmask_b32_e64 v7, v7, v8, s[38:39]
	v_cndmask_b32_e32 v8, 0, v207, vcc
	v_sub_f32_e32 v7, v7, v8
	v_sub_f32_e32 v4, v4, v7
.LBB0_7106:
	s_andn2_saveexec_b64 s[80:81], s[80:81]
	s_cbranch_execz .LBB0_7109
	v_mad_i64_i32 v[8:9], s[38:39], s22, v52, 0
	v_lshl_add_u64 v[8:9], v[8:9], 2, s[0:1]
	v_mov_b32_e32 v4, v226
	s_andn2_b64 vcc, exec, s[76:77]
	s_cbranch_vccnz .LBB0_7109
	s_waitcnt vmcnt(0)
	v_mul_f32_e64 v7, |v4|, s10
	v_exp_f32_e32 v7, v7
	v_max_f32_e32 v4, v4, v4
	v_min_f32_e32 v4, 0, v4
	v_add_f32_e32 v7, 1.0, v7
	v_cmp_gt_f32_e32 vcc, s11, v7
	s_nop 1
	v_cndmask_b32_e64 v8, 0, 32, vcc
	v_ldexp_f32 v7, v7, v8
	v_log_f32_e32 v7, v7
	s_nop 0
	v_mul_f32_e32 v8, 0x3f317217, v7
	v_fma_f32 v8, v7, s12, -v8
	v_fmac_f32_e32 v8, 0x3377d1cf, v7
	v_fmac_f32_e32 v8, 0x3f317217, v7
	v_cmp_lt_f32_e64 s[38:39], |v7|, s13
	s_nop 1
	v_cndmask_b32_e64 v7, v7, v8, s[38:39]
	v_cndmask_b32_e32 v8, 0, v207, vcc
	v_sub_f32_e32 v7, v7, v8
	v_sub_f32_e32 v4, v4, v7

.LBB0_7110:
	s_or_b64 exec, exec, s[78:79]
	v_or_b32_e32 v53, 3, v50
	s_and_saveexec_b64 s[78:79], s[36:37]
	s_cbranch_execz .LBB0_7117
	v_cmp_le_i32_e32 vcc, s28, v53
	s_and_saveexec_b64 s[38:39], vcc
	s_xor_b64 s[80:81], exec, s[38:39]
	s_cbranch_execz .LBB0_7113
	v_subrev_u32_e32 v196, s28, v53
	v_lshl_add_u64 v[8:9], v[196:197], 2, s[26:27]
	v_mov_b32_e32 v5, v227
	s_waitcnt vmcnt(0)
	v_mul_f32_e64 v7, |v5|, s10
	v_exp_f32_e32 v7, v7
	v_max_f32_e32 v5, v5, v5
	v_min_f32_e32 v5, 0, v5
	v_add_f32_e32 v7, 1.0, v7
	v_cmp_gt_f32_e32 vcc, s11, v7
	s_nop 1
	v_cndmask_b32_e64 v8, 0, 32, vcc
	v_ldexp_f32 v7, v7, v8
	v_log_f32_e32 v7, v7
	s_nop 0
	v_mul_f32_e32 v8, 0x3f317217, v7
	v_fma_f32 v8, v7, s12, -v8
	v_fmac_f32_e32 v8, 0x3377d1cf, v7
	v_fmac_f32_e32 v8, 0x3f317217, v7
	v_cmp_lt_f32_e64 s[38:39], |v7|, s13
	s_nop 1
	v_cndmask_b32_e64 v7, v7, v8, s[38:39]
	v_cndmask_b32_e32 v8, 0, v207, vcc
	v_sub_f32_e32 v7, v7, v8
	v_sub_f32_e32 v5, v5, v7
.LBB0_7113:
	s_andn2_saveexec_b64 s[80:81], s[80:81]
	s_cbranch_execz .LBB0_7116
	v_mad_i64_i32 v[8:9], s[38:39], s22, v53, 0
	v_lshl_add_u64 v[8:9], v[8:9], 2, s[0:1]
	v_mov_b32_e32 v5, v227
	s_andn2_b64 vcc, exec, s[76:77]
	s_cbranch_vccnz .LBB0_7116
	s_waitcnt vmcnt(0)
	v_mul_f32_e64 v7, |v5|, s10
	v_exp_f32_e32 v7, v7
	v_max_f32_e32 v5, v5, v5
	v_min_f32_e32 v5, 0, v5
	v_add_f32_e32 v7, 1.0, v7
	v_cmp_gt_f32_e32 vcc, s11, v7
	s_nop 1
	v_cndmask_b32_e64 v8, 0, 32, vcc
	v_ldexp_f32 v7, v7, v8
	v_log_f32_e32 v7, v7
	s_nop 0
	v_mul_f32_e32 v8, 0x3f317217, v7
	v_fma_f32 v8, v7, s12, -v8
	v_fmac_f32_e32 v8, 0x3377d1cf, v7
	v_fmac_f32_e32 v8, 0x3f317217, v7
	v_cmp_lt_f32_e64 s[38:39], |v7|, s13
	s_nop 1
	v_cndmask_b32_e64 v7, v7, v8, s[38:39]
	v_cndmask_b32_e32 v8, 0, v207, vcc
	v_sub_f32_e32 v7, v7, v8
	v_sub_f32_e32 v5, v5, v7

.LBB0_7117:
	s_or_b64 exec, exec, s[78:79]
	v_or_b32_e32 v54, 4, v50
	v_mov_b32_e32 v8, 0
	v_mov_b32_e32 v7, 0
	s_and_saveexec_b64 s[78:79], s[36:37]
	s_cbranch_execz .LBB0_7124
	v_cmp_le_i32_e32 vcc, s28, v54
	s_and_saveexec_b64 s[38:39], vcc
	s_xor_b64 s[80:81], exec, s[38:39]
	s_cbranch_execz .LBB0_7120
	v_subrev_u32_e32 v196, s28, v54
	v_lshl_add_u64 v[10:11], v[196:197], 2, s[26:27]
	v_mov_b32_e32 v7, v228
	s_waitcnt vmcnt(0)
	v_mul_f32_e64 v9, |v7|, s10
	v_exp_f32_e32 v9, v9
	v_max_f32_e32 v7, v7, v7
	v_min_f32_e32 v7, 0, v7
	v_add_f32_e32 v9, 1.0, v9
	v_cmp_gt_f32_e32 vcc, s11, v9
	s_nop 1
	v_cndmask_b32_e64 v10, 0, 32, vcc
	v_ldexp_f32 v9, v9, v10
	v_log_f32_e32 v9, v9
	s_nop 0
	v_mul_f32_e32 v10, 0x3f317217, v9
	v_fma_f32 v10, v9, s12, -v10
	v_fmac_f32_e32 v10, 0x3377d1cf, v9
	v_fmac_f32_e32 v10, 0x3f317217, v9
	v_cmp_lt_f32_e64 s[38:39], |v9|, s13
	s_nop 1
	v_cndmask_b32_e64 v9, v9, v10, s[38:39]
	v_cndmask_b32_e32 v10, 0, v207, vcc
	v_sub_f32_e32 v9, v9, v10
	v_sub_f32_e32 v7, v7, v9
.LBB0_7120:
	s_andn2_saveexec_b64 s[80:81], s[80:81]
	s_cbranch_execz .LBB0_7123
	v_mad_i64_i32 v[10:11], s[38:39], s22, v54, 0
	v_lshl_add_u64 v[10:11], v[10:11], 2, s[0:1]
	v_mov_b32_e32 v7, v228
	s_andn2_b64 vcc, exec, s[76:77]
	s_cbranch_vccnz .LBB0_7123
	s_waitcnt vmcnt(0)
	v_mul_f32_e64 v9, |v7|, s10
	v_exp_f32_e32 v9, v9
	v_max_f32_e32 v7, v7, v7
	v_min_f32_e32 v7, 0, v7
	v_add_f32_e32 v9, 1.0, v9
	v_cmp_gt_f32_e32 vcc, s11, v9
	s_nop 1
	v_cndmask_b32_e64 v10, 0, 32, vcc
	v_ldexp_f32 v9, v9, v10
	v_log_f32_e32 v9, v9
	s_nop 0
	v_mul_f32_e32 v10, 0x3f317217, v9
	v_fma_f32 v10, v9, s12, -v10
	v_fmac_f32_e32 v10, 0x3377d1cf, v9
	v_fmac_f32_e32 v10, 0x3f317217, v9
	v_cmp_lt_f32_e64 s[38:39], |v9|, s13
	s_nop 1
	v_cndmask_b32_e64 v9, v9, v10, s[38:39]
	v_cndmask_b32_e32 v10, 0, v207, vcc
	v_sub_f32_e32 v9, v9, v10
	v_sub_f32_e32 v7, v7, v9

.LBB0_7124:
	s_or_b64 exec, exec, s[78:79]
	v_or_b32_e32 v55, 5, v50
	s_and_saveexec_b64 s[78:79], s[36:37]
	s_cbranch_execz .LBB0_7131
	v_cmp_le_i32_e32 vcc, s28, v55
	s_and_saveexec_b64 s[38:39], vcc
	s_xor_b64 s[80:81], exec, s[38:39]
	s_cbranch_execz .LBB0_7127
	v_subrev_u32_e32 v196, s28, v55
	v_lshl_add_u64 v[8:9], v[196:197], 2, s[26:27]
	v_mov_b32_e32 v8, v229
	s_waitcnt vmcnt(0)
	v_mul_f32_e64 v9, |v8|, s10
	v_exp_f32_e32 v9, v9
	v_max_f32_e32 v8, v8, v8
	v_min_f32_e32 v8, 0, v8
	v_add_f32_e32 v9, 1.0, v9
	v_cmp_gt_f32_e32 vcc, s11, v9
	s_nop 1
	v_cndmask_b32_e64 v10, 0, 32, vcc
	v_ldexp_f32 v9, v9, v10
	v_log_f32_e32 v9, v9
	s_nop 0
	v_mul_f32_e32 v10, 0x3f317217, v9
	v_fma_f32 v10, v9, s12, -v10
	v_fmac_f32_e32 v10, 0x3377d1cf, v9
	v_fmac_f32_e32 v10, 0x3f317217, v9
	v_cmp_lt_f32_e64 s[38:39], |v9|, s13
	s_nop 1
	v_cndmask_b32_e64 v9, v9, v10, s[38:39]
	v_cndmask_b32_e32 v10, 0, v207, vcc
	v_sub_f32_e32 v9, v9, v10
	v_sub_f32_e32 v8, v8, v9
.LBB0_7127:
	s_andn2_saveexec_b64 s[80:81], s[80:81]
	s_cbranch_execz .LBB0_7130
	v_mad_i64_i32 v[8:9], s[38:39], s22, v55, 0
	v_lshl_add_u64 v[8:9], v[8:9], 2, s[0:1]
	v_mov_b32_e32 v8, v229
	s_andn2_b64 vcc, exec, s[76:77]
	s_cbranch_vccnz .LBB0_7130
	s_waitcnt vmcnt(0)
	v_mul_f32_e64 v9, |v8|, s10
	v_exp_f32_e32 v9, v9
	v_max_f32_e32 v8, v8, v8
	v_min_f32_e32 v8, 0, v8
	v_add_f32_e32 v9, 1.0, v9
	v_cmp_gt_f32_e32 vcc, s11, v9
	s_nop 1
	v_cndmask_b32_e64 v10, 0, 32, vcc
	v_ldexp_f32 v9, v9, v10
	v_log_f32_e32 v9, v9
	s_nop 0
	v_mul_f32_e32 v10, 0x3f317217, v9
	v_fma_f32 v10, v9, s12, -v10
	v_fmac_f32_e32 v10, 0x3377d1cf, v9
	v_fmac_f32_e32 v10, 0x3f317217, v9
	v_cmp_lt_f32_e64 s[38:39], |v9|, s13
	s_nop 1
	v_cndmask_b32_e64 v9, v9, v10, s[38:39]
	v_cndmask_b32_e32 v10, 0, v207, vcc
	v_sub_f32_e32 v9, v9, v10
	v_sub_f32_e32 v8, v8, v9

.LBB0_7131:
	s_or_b64 exec, exec, s[78:79]
	v_or_b32_e32 v56, 6, v50
	v_mov_b32_e32 v10, 0
	v_mov_b32_e32 v9, 0
	s_and_saveexec_b64 s[78:79], s[36:37]
	s_cbranch_execz .LBB0_7138
	v_cmp_le_i32_e32 vcc, s28, v56
	s_and_saveexec_b64 s[38:39], vcc
	s_xor_b64 s[80:81], exec, s[38:39]
	s_cbranch_execz .LBB0_7134
	v_subrev_u32_e32 v196, s28, v56
	v_lshl_add_u64 v[12:13], v[196:197], 2, s[26:27]
	v_mov_b32_e32 v9, v230
	s_waitcnt vmcnt(0)
	v_mul_f32_e64 v11, |v9|, s10
	v_exp_f32_e32 v11, v11
	v_max_f32_e32 v9, v9, v9
	v_min_f32_e32 v9, 0, v9
	v_add_f32_e32 v11, 1.0, v11
	v_cmp_gt_f32_e32 vcc, s11, v11
	s_nop 1
	v_cndmask_b32_e64 v12, 0, 32, vcc
	v_ldexp_f32 v11, v11, v12
	v_log_f32_e32 v11, v11
	s_nop 0
	v_mul_f32_e32 v12, 0x3f317217, v11
	v_fma_f32 v12, v11, s12, -v12
	v_fmac_f32_e32 v12, 0x3377d1cf, v11
	v_fmac_f32_e32 v12, 0x3f317217, v11
	v_cmp_lt_f32_e64 s[38:39], |v11|, s13
	s_nop 1
	v_cndmask_b32_e64 v11, v11, v12, s[38:39]
	v_cndmask_b32_e32 v12, 0, v207, vcc
	v_sub_f32_e32 v11, v11, v12
	v_sub_f32_e32 v9, v9, v11
.LBB0_7134:
	s_andn2_saveexec_b64 s[80:81], s[80:81]
	s_cbranch_execz .LBB0_7137
	v_mad_i64_i32 v[12:13], s[38:39], s22, v56, 0
	v_lshl_add_u64 v[12:13], v[12:13], 2, s[0:1]
	v_mov_b32_e32 v9, v230
	s_andn2_b64 vcc, exec, s[76:77]
	s_cbranch_vccnz .LBB0_7137
	s_waitcnt vmcnt(0)
	v_mul_f32_e64 v11, |v9|, s10
	v_exp_f32_e32 v11, v11
	v_max_f32_e32 v9, v9, v9
	v_min_f32_e32 v9, 0, v9
	v_add_f32_e32 v11, 1.0, v11
	v_cmp_gt_f32_e32 vcc, s11, v11
	s_nop 1
	v_cndmask_b32_e64 v12, 0, 32, vcc
	v_ldexp_f32 v11, v11, v12
	v_log_f32_e32 v11, v11
	s_nop 0
	v_mul_f32_e32 v12, 0x3f317217, v11
	v_fma_f32 v12, v11, s12, -v12
	v_fmac_f32_e32 v12, 0x3377d1cf, v11
	v_fmac_f32_e32 v12, 0x3f317217, v11
	v_cmp_lt_f32_e64 s[38:39], |v11|, s13
	s_nop 1
	v_cndmask_b32_e64 v11, v11, v12, s[38:39]
	v_cndmask_b32_e32 v12, 0, v207, vcc
	v_sub_f32_e32 v11, v11, v12
	v_sub_f32_e32 v9, v9, v11

.LBB0_7138:
	s_or_b64 exec, exec, s[78:79]
	v_or_b32_e32 v57, 7, v50
	s_and_saveexec_b64 s[78:79], s[36:37]
	s_cbranch_execz .LBB0_7145
	v_cmp_le_i32_e32 vcc, s28, v57
	s_and_saveexec_b64 s[38:39], vcc
	s_xor_b64 s[80:81], exec, s[38:39]
	s_cbranch_execz .LBB0_7141
	v_subrev_u32_e32 v196, s28, v57
	v_lshl_add_u64 v[10:11], v[196:197], 2, s[26:27]
	v_mov_b32_e32 v10, v231
	s_waitcnt vmcnt(0)
	v_mul_f32_e64 v11, |v10|, s10
	v_exp_f32_e32 v11, v11
	v_max_f32_e32 v10, v10, v10
	v_min_f32_e32 v10, 0, v10
	v_add_f32_e32 v11, 1.0, v11
	v_cmp_gt_f32_e32 vcc, s11, v11
	s_nop 1
	v_cndmask_b32_e64 v12, 0, 32, vcc
	v_ldexp_f32 v11, v11, v12
	v_log_f32_e32 v11, v11
	s_nop 0
	v_mul_f32_e32 v12, 0x3f317217, v11
	v_fma_f32 v12, v11, s12, -v12
	v_fmac_f32_e32 v12, 0x3377d1cf, v11
	v_fmac_f32_e32 v12, 0x3f317217, v11
	v_cmp_lt_f32_e64 s[38:39], |v11|, s13
	s_nop 1
	v_cndmask_b32_e64 v11, v11, v12, s[38:39]
	v_cndmask_b32_e32 v12, 0, v207, vcc
	v_sub_f32_e32 v11, v11, v12
	v_sub_f32_e32 v10, v10, v11
.LBB0_7141:
	s_andn2_saveexec_b64 s[80:81], s[80:81]
	s_cbranch_execz .LBB0_7144
	v_mad_i64_i32 v[10:11], s[38:39], s22, v57, 0
	v_lshl_add_u64 v[10:11], v[10:11], 2, s[0:1]
	v_mov_b32_e32 v10, v231
	s_andn2_b64 vcc, exec, s[76:77]
	s_cbranch_vccnz .LBB0_7144
	s_waitcnt vmcnt(0)
	v_mul_f32_e64 v11, |v10|, s10
	v_exp_f32_e32 v11, v11
	v_max_f32_e32 v10, v10, v10
	v_min_f32_e32 v10, 0, v10
	v_add_f32_e32 v11, 1.0, v11
	v_cmp_gt_f32_e32 vcc, s11, v11
	s_nop 1
	v_cndmask_b32_e64 v12, 0, 32, vcc
	v_ldexp_f32 v11, v11, v12
	v_log_f32_e32 v11, v11
	s_nop 0
	v_mul_f32_e32 v12, 0x3f317217, v11
	v_fma_f32 v12, v11, s12, -v12
	v_fmac_f32_e32 v12, 0x3377d1cf, v11
	v_fmac_f32_e32 v12, 0x3f317217, v11
	v_cmp_lt_f32_e64 s[38:39], |v11|, s13
	s_nop 1
	v_cndmask_b32_e64 v11, v11, v12, s[38:39]
	v_cndmask_b32_e32 v12, 0, v207, vcc
	v_sub_f32_e32 v11, v11, v12
	v_sub_f32_e32 v10, v10, v11

.LBB0_7145:
	s_or_b64 exec, exec, s[78:79]
	v_or_b32_e32 v58, 8, v50
	v_mov_b32_e32 v12, 0
	v_mov_b32_e32 v11, 0
	s_and_saveexec_b64 s[78:79], s[36:37]
	s_cbranch_execz .LBB0_7152
	v_cmp_le_i32_e32 vcc, s28, v58
	s_and_saveexec_b64 s[38:39], vcc
	s_xor_b64 s[80:81], exec, s[38:39]
	s_cbranch_execz .LBB0_7148
	v_subrev_u32_e32 v196, s28, v58
	v_lshl_add_u64 v[14:15], v[196:197], 2, s[26:27]
	v_mov_b32_e32 v11, v232
	s_waitcnt vmcnt(0)
	v_mul_f32_e64 v13, |v11|, s10
	v_exp_f32_e32 v13, v13
	v_max_f32_e32 v11, v11, v11
	v_min_f32_e32 v11, 0, v11
	v_add_f32_e32 v13, 1.0, v13
	v_cmp_gt_f32_e32 vcc, s11, v13
	s_nop 1
	v_cndmask_b32_e64 v14, 0, 32, vcc
	v_ldexp_f32 v13, v13, v14
	v_log_f32_e32 v13, v13
	s_nop 0
	v_mul_f32_e32 v14, 0x3f317217, v13
	v_fma_f32 v14, v13, s12, -v14
	v_fmac_f32_e32 v14, 0x3377d1cf, v13
	v_fmac_f32_e32 v14, 0x3f317217, v13
	v_cmp_lt_f32_e64 s[38:39], |v13|, s13
	s_nop 1
	v_cndmask_b32_e64 v13, v13, v14, s[38:39]
	v_cndmask_b32_e32 v14, 0, v207, vcc
	v_sub_f32_e32 v13, v13, v14
	v_sub_f32_e32 v11, v11, v13
.LBB0_7148:
	s_andn2_saveexec_b64 s[80:81], s[80:81]
	s_cbranch_execz .LBB0_7151
	v_mad_i64_i32 v[14:15], s[38:39], s22, v58, 0
	v_lshl_add_u64 v[14:15], v[14:15], 2, s[0:1]
	v_mov_b32_e32 v11, v232
	s_andn2_b64 vcc, exec, s[76:77]
	s_cbranch_vccnz .LBB0_7151
	s_waitcnt vmcnt(0)
	v_mul_f32_e64 v13, |v11|, s10
	v_exp_f32_e32 v13, v13
	v_max_f32_e32 v11, v11, v11
	v_min_f32_e32 v11, 0, v11
	v_add_f32_e32 v13, 1.0, v13
	v_cmp_gt_f32_e32 vcc, s11, v13
	s_nop 1
	v_cndmask_b32_e64 v14, 0, 32, vcc
	v_ldexp_f32 v13, v13, v14
	v_log_f32_e32 v13, v13
	s_nop 0
	v_mul_f32_e32 v14, 0x3f317217, v13
	v_fma_f32 v14, v13, s12, -v14
	v_fmac_f32_e32 v14, 0x3377d1cf, v13
	v_fmac_f32_e32 v14, 0x3f317217, v13
	v_cmp_lt_f32_e64 s[38:39], |v13|, s13
	s_nop 1
	v_cndmask_b32_e64 v13, v13, v14, s[38:39]
	v_cndmask_b32_e32 v14, 0, v207, vcc
	v_sub_f32_e32 v13, v13, v14
	v_sub_f32_e32 v11, v11, v13

.LBB0_7152:
	s_or_b64 exec, exec, s[78:79]
	v_or_b32_e32 v60, 9, v50
	s_and_saveexec_b64 s[78:79], s[36:37]
	s_cbranch_execz .LBB0_7159
	v_cmp_le_i32_e32 vcc, s28, v60
	s_and_saveexec_b64 s[38:39], vcc
	s_xor_b64 s[80:81], exec, s[38:39]
	s_cbranch_execz .LBB0_7155
	v_subrev_u32_e32 v196, s28, v60
	v_lshl_add_u64 v[12:13], v[196:197], 2, s[26:27]
	v_mov_b32_e32 v12, v233
	s_waitcnt vmcnt(0)
	v_mul_f32_e64 v13, |v12|, s10
	v_exp_f32_e32 v13, v13
	v_max_f32_e32 v12, v12, v12
	v_min_f32_e32 v12, 0, v12
	v_add_f32_e32 v13, 1.0, v13
	v_cmp_gt_f32_e32 vcc, s11, v13
	s_nop 1
	v_cndmask_b32_e64 v14, 0, 32, vcc
	v_ldexp_f32 v13, v13, v14
	v_log_f32_e32 v13, v13
	s_nop 0
	v_mul_f32_e32 v14, 0x3f317217, v13
	v_fma_f32 v14, v13, s12, -v14
	v_fmac_f32_e32 v14, 0x3377d1cf, v13
	v_fmac_f32_e32 v14, 0x3f317217, v13
	v_cmp_lt_f32_e64 s[38:39], |v13|, s13
	s_nop 1
	v_cndmask_b32_e64 v13, v13, v14, s[38:39]
	v_cndmask_b32_e32 v14, 0, v207, vcc
	v_sub_f32_e32 v13, v13, v14
	v_sub_f32_e32 v12, v12, v13
.LBB0_7155:
	s_andn2_saveexec_b64 s[80:81], s[80:81]
	s_cbranch_execz .LBB0_7158
	v_mad_i64_i32 v[12:13], s[38:39], s22, v60, 0
	v_lshl_add_u64 v[12:13], v[12:13], 2, s[0:1]
	v_mov_b32_e32 v12, v233
	s_andn2_b64 vcc, exec, s[76:77]
	s_cbranch_vccnz .LBB0_7158
	s_waitcnt vmcnt(0)
	v_mul_f32_e64 v13, |v12|, s10
	v_exp_f32_e32 v13, v13
	v_max_f32_e32 v12, v12, v12
	v_min_f32_e32 v12, 0, v12
	v_add_f32_e32 v13, 1.0, v13
	v_cmp_gt_f32_e32 vcc, s11, v13
	s_nop 1
	v_cndmask_b32_e64 v14, 0, 32, vcc
	v_ldexp_f32 v13, v13, v14
	v_log_f32_e32 v13, v13
	s_nop 0
	v_mul_f32_e32 v14, 0x3f317217, v13
	v_fma_f32 v14, v13, s12, -v14
	v_fmac_f32_e32 v14, 0x3377d1cf, v13
	v_fmac_f32_e32 v14, 0x3f317217, v13
	v_cmp_lt_f32_e64 s[38:39], |v13|, s13
	s_nop 1
	v_cndmask_b32_e64 v13, v13, v14, s[38:39]
	v_cndmask_b32_e32 v14, 0, v207, vcc
	v_sub_f32_e32 v13, v13, v14
	v_sub_f32_e32 v12, v12, v13

.LBB0_7159:
	s_or_b64 exec, exec, s[78:79]
	v_or_b32_e32 v62, 10, v50
	v_mov_b32_e32 v14, 0
	v_mov_b32_e32 v13, 0
	s_and_saveexec_b64 s[78:79], s[36:37]
	s_cbranch_execz .LBB0_7166
	v_cmp_le_i32_e32 vcc, s28, v62
	s_and_saveexec_b64 s[38:39], vcc
	s_xor_b64 s[80:81], exec, s[38:39]
	s_cbranch_execz .LBB0_7162
	v_subrev_u32_e32 v196, s28, v62
	v_lshl_add_u64 v[16:17], v[196:197], 2, s[26:27]
	v_mov_b32_e32 v13, v234
	s_waitcnt vmcnt(0)
	v_mul_f32_e64 v15, |v13|, s10
	v_exp_f32_e32 v15, v15
	v_max_f32_e32 v13, v13, v13
	v_min_f32_e32 v13, 0, v13
	v_add_f32_e32 v15, 1.0, v15
	v_cmp_gt_f32_e32 vcc, s11, v15
	s_nop 1
	v_cndmask_b32_e64 v16, 0, 32, vcc
	v_ldexp_f32 v15, v15, v16
	v_log_f32_e32 v15, v15
	s_nop 0
	v_mul_f32_e32 v16, 0x3f317217, v15
	v_fma_f32 v16, v15, s12, -v16
	v_fmac_f32_e32 v16, 0x3377d1cf, v15
	v_fmac_f32_e32 v16, 0x3f317217, v15
	v_cmp_lt_f32_e64 s[38:39], |v15|, s13
	s_nop 1
	v_cndmask_b32_e64 v15, v15, v16, s[38:39]
	v_cndmask_b32_e32 v16, 0, v207, vcc
	v_sub_f32_e32 v15, v15, v16
	v_sub_f32_e32 v13, v13, v15
.LBB0_7162:
	s_andn2_saveexec_b64 s[80:81], s[80:81]
	s_cbranch_execz .LBB0_7165
	v_mad_i64_i32 v[16:17], s[38:39], s22, v62, 0
	v_lshl_add_u64 v[16:17], v[16:17], 2, s[0:1]
	v_mov_b32_e32 v13, v234
	s_andn2_b64 vcc, exec, s[76:77]
	s_cbranch_vccnz .LBB0_7165
	s_waitcnt vmcnt(0)
	v_mul_f32_e64 v15, |v13|, s10
	v_exp_f32_e32 v15, v15
	v_max_f32_e32 v13, v13, v13
	v_min_f32_e32 v13, 0, v13
	v_add_f32_e32 v15, 1.0, v15
	v_cmp_gt_f32_e32 vcc, s11, v15
	s_nop 1
	v_cndmask_b32_e64 v16, 0, 32, vcc
	v_ldexp_f32 v15, v15, v16
	v_log_f32_e32 v15, v15
	s_nop 0
	v_mul_f32_e32 v16, 0x3f317217, v15
	v_fma_f32 v16, v15, s12, -v16
	v_fmac_f32_e32 v16, 0x3377d1cf, v15
	v_fmac_f32_e32 v16, 0x3f317217, v15
	v_cmp_lt_f32_e64 s[38:39], |v15|, s13
	s_nop 1
	v_cndmask_b32_e64 v15, v15, v16, s[38:39]
	v_cndmask_b32_e32 v16, 0, v207, vcc
	v_sub_f32_e32 v15, v15, v16
	v_sub_f32_e32 v13, v13, v15

.LBB0_7166:
	s_or_b64 exec, exec, s[78:79]
	v_or_b32_e32 v63, 11, v50
	s_and_saveexec_b64 s[78:79], s[36:37]
	s_cbranch_execz .LBB0_7173
	v_cmp_le_i32_e32 vcc, s28, v63
	s_and_saveexec_b64 s[38:39], vcc
	s_xor_b64 s[80:81], exec, s[38:39]
	s_cbranch_execz .LBB0_7169
	v_subrev_u32_e32 v196, s28, v63
	v_lshl_add_u64 v[14:15], v[196:197], 2, s[26:27]
	v_mov_b32_e32 v14, v235
	s_waitcnt vmcnt(0)
	v_mul_f32_e64 v15, |v14|, s10
	v_exp_f32_e32 v15, v15
	v_max_f32_e32 v14, v14, v14
	v_min_f32_e32 v14, 0, v14
	v_add_f32_e32 v15, 1.0, v15
	v_cmp_gt_f32_e32 vcc, s11, v15
	s_nop 1
	v_cndmask_b32_e64 v16, 0, 32, vcc
	v_ldexp_f32 v15, v15, v16
	v_log_f32_e32 v15, v15
	s_nop 0
	v_mul_f32_e32 v16, 0x3f317217, v15
	v_fma_f32 v16, v15, s12, -v16
	v_fmac_f32_e32 v16, 0x3377d1cf, v15
	v_fmac_f32_e32 v16, 0x3f317217, v15
	v_cmp_lt_f32_e64 s[38:39], |v15|, s13
	s_nop 1
	v_cndmask_b32_e64 v15, v15, v16, s[38:39]
	v_cndmask_b32_e32 v16, 0, v207, vcc
	v_sub_f32_e32 v15, v15, v16
	v_sub_f32_e32 v14, v14, v15
.LBB0_7169:
	s_andn2_saveexec_b64 s[80:81], s[80:81]
	s_cbranch_execz .LBB0_7172
	v_mad_i64_i32 v[14:15], s[38:39], s22, v63, 0
	v_lshl_add_u64 v[14:15], v[14:15], 2, s[0:1]
	v_mov_b32_e32 v14, v235
	s_andn2_b64 vcc, exec, s[76:77]
	s_cbranch_vccnz .LBB0_7172
	s_waitcnt vmcnt(0)
	v_mul_f32_e64 v15, |v14|, s10
	v_exp_f32_e32 v15, v15
	v_max_f32_e32 v14, v14, v14
	v_min_f32_e32 v14, 0, v14
	v_add_f32_e32 v15, 1.0, v15
	v_cmp_gt_f32_e32 vcc, s11, v15
	s_nop 1
	v_cndmask_b32_e64 v16, 0, 32, vcc
	v_ldexp_f32 v15, v15, v16
	v_log_f32_e32 v15, v15
	s_nop 0
	v_mul_f32_e32 v16, 0x3f317217, v15
	v_fma_f32 v16, v15, s12, -v16
	v_fmac_f32_e32 v16, 0x3377d1cf, v15
	v_fmac_f32_e32 v16, 0x3f317217, v15
	v_cmp_lt_f32_e64 s[38:39], |v15|, s13
	s_nop 1
	v_cndmask_b32_e64 v15, v15, v16, s[38:39]
	v_cndmask_b32_e32 v16, 0, v207, vcc
	v_sub_f32_e32 v15, v15, v16
	v_sub_f32_e32 v14, v14, v15

.LBB0_7173:
	s_or_b64 exec, exec, s[78:79]
	v_or_b32_e32 v59, 12, v50
	v_mov_b32_e32 v16, 0
	v_mov_b32_e32 v15, 0
	s_and_saveexec_b64 s[78:79], s[36:37]
	s_cbranch_execz .LBB0_7180
	v_cmp_le_i32_e32 vcc, s28, v59
	s_and_saveexec_b64 s[38:39], vcc
	s_xor_b64 s[80:81], exec, s[38:39]
	s_cbranch_execz .LBB0_7176
	v_subrev_u32_e32 v196, s28, v59
	v_lshl_add_u64 v[18:19], v[196:197], 2, s[26:27]
	v_mov_b32_e32 v15, v236
	s_waitcnt vmcnt(0)
	v_mul_f32_e64 v17, |v15|, s10
	v_exp_f32_e32 v17, v17
	v_max_f32_e32 v15, v15, v15
	v_min_f32_e32 v15, 0, v15
	v_add_f32_e32 v17, 1.0, v17
	v_cmp_gt_f32_e32 vcc, s11, v17
	s_nop 1
	v_cndmask_b32_e64 v18, 0, 32, vcc
	v_ldexp_f32 v17, v17, v18
	v_log_f32_e32 v17, v17
	s_nop 0
	v_mul_f32_e32 v18, 0x3f317217, v17
	v_fma_f32 v18, v17, s12, -v18
	v_fmac_f32_e32 v18, 0x3377d1cf, v17
	v_fmac_f32_e32 v18, 0x3f317217, v17
	v_cmp_lt_f32_e64 s[38:39], |v17|, s13
	s_nop 1
	v_cndmask_b32_e64 v17, v17, v18, s[38:39]
	v_cndmask_b32_e32 v18, 0, v207, vcc
	v_sub_f32_e32 v17, v17, v18
	v_sub_f32_e32 v15, v15, v17
.LBB0_7176:
	s_andn2_saveexec_b64 s[80:81], s[80:81]
	s_cbranch_execz .LBB0_7179
	v_mad_i64_i32 v[18:19], s[38:39], s22, v59, 0
	v_lshl_add_u64 v[18:19], v[18:19], 2, s[0:1]
	v_mov_b32_e32 v15, v236
	s_andn2_b64 vcc, exec, s[76:77]
	s_cbranch_vccnz .LBB0_7179
	s_waitcnt vmcnt(0)
	v_mul_f32_e64 v17, |v15|, s10
	v_exp_f32_e32 v17, v17
	v_max_f32_e32 v15, v15, v15
	v_min_f32_e32 v15, 0, v15
	v_add_f32_e32 v17, 1.0, v17
	v_cmp_gt_f32_e32 vcc, s11, v17
	s_nop 1
	v_cndmask_b32_e64 v18, 0, 32, vcc
	v_ldexp_f32 v17, v17, v18
	v_log_f32_e32 v17, v17
	s_nop 0
	v_mul_f32_e32 v18, 0x3f317217, v17
	v_fma_f32 v18, v17, s12, -v18
	v_fmac_f32_e32 v18, 0x3377d1cf, v17
	v_fmac_f32_e32 v18, 0x3f317217, v17
	v_cmp_lt_f32_e64 s[38:39], |v17|, s13
	s_nop 1
	v_cndmask_b32_e64 v17, v17, v18, s[38:39]
	v_cndmask_b32_e32 v18, 0, v207, vcc
	v_sub_f32_e32 v17, v17, v18
	v_sub_f32_e32 v15, v15, v17

.LBB0_7180:
	s_or_b64 exec, exec, s[78:79]
	v_or_b32_e32 v61, 13, v50
	s_and_saveexec_b64 s[78:79], s[36:37]
	s_cbranch_execz .LBB0_7187
	v_cmp_le_i32_e32 vcc, s28, v61
	s_and_saveexec_b64 s[38:39], vcc
	s_xor_b64 s[80:81], exec, s[38:39]
	s_cbranch_execz .LBB0_7183
	v_subrev_u32_e32 v196, s28, v61
	v_lshl_add_u64 v[16:17], v[196:197], 2, s[26:27]
	v_mov_b32_e32 v16, v237
	s_waitcnt vmcnt(0)
	v_mul_f32_e64 v17, |v16|, s10
	v_exp_f32_e32 v17, v17
	v_max_f32_e32 v16, v16, v16
	v_min_f32_e32 v16, 0, v16
	v_add_f32_e32 v17, 1.0, v17
	v_cmp_gt_f32_e32 vcc, s11, v17
	s_nop 1
	v_cndmask_b32_e64 v18, 0, 32, vcc
	v_ldexp_f32 v17, v17, v18
	v_log_f32_e32 v17, v17
	s_nop 0
	v_mul_f32_e32 v18, 0x3f317217, v17
	v_fma_f32 v18, v17, s12, -v18
	v_fmac_f32_e32 v18, 0x3377d1cf, v17
	v_fmac_f32_e32 v18, 0x3f317217, v17
	v_cmp_lt_f32_e64 s[38:39], |v17|, s13
	s_nop 1
	v_cndmask_b32_e64 v17, v17, v18, s[38:39]
	v_cndmask_b32_e32 v18, 0, v207, vcc
	v_sub_f32_e32 v17, v17, v18
	v_sub_f32_e32 v16, v16, v17
.LBB0_7183:
	s_andn2_saveexec_b64 s[80:81], s[80:81]
	s_cbranch_execz .LBB0_7186
	v_mad_i64_i32 v[16:17], s[38:39], s22, v61, 0
	v_lshl_add_u64 v[16:17], v[16:17], 2, s[0:1]
	v_mov_b32_e32 v16, v237
	s_andn2_b64 vcc, exec, s[76:77]
	s_cbranch_vccnz .LBB0_7186
	s_waitcnt vmcnt(0)
	v_mul_f32_e64 v17, |v16|, s10
	v_exp_f32_e32 v17, v17
	v_max_f32_e32 v16, v16, v16
	v_min_f32_e32 v16, 0, v16
	v_add_f32_e32 v17, 1.0, v17
	v_cmp_gt_f32_e32 vcc, s11, v17
	s_nop 1
	v_cndmask_b32_e64 v18, 0, 32, vcc
	v_ldexp_f32 v17, v17, v18
	v_log_f32_e32 v17, v17
	s_nop 0
	v_mul_f32_e32 v18, 0x3f317217, v17
	v_fma_f32 v18, v17, s12, -v18
	v_fmac_f32_e32 v18, 0x3377d1cf, v17
	v_fmac_f32_e32 v18, 0x3f317217, v17
	v_cmp_lt_f32_e64 s[38:39], |v17|, s13
	s_nop 1
	v_cndmask_b32_e64 v17, v17, v18, s[38:39]
	v_cndmask_b32_e32 v18, 0, v207, vcc
	v_sub_f32_e32 v17, v17, v18
	v_sub_f32_e32 v16, v16, v17

.LBB0_7187:
	s_or_b64 exec, exec, s[78:79]
	v_or_b32_e32 v64, 14, v50
	v_mov_b32_e32 v18, 0
	v_mov_b32_e32 v17, 0
	s_and_saveexec_b64 s[78:79], s[36:37]
	s_cbranch_execz .LBB0_7194
	v_cmp_le_i32_e32 vcc, s28, v64
	s_and_saveexec_b64 s[38:39], vcc
	s_xor_b64 s[80:81], exec, s[38:39]
	s_cbranch_execz .LBB0_7190
	v_subrev_u32_e32 v196, s28, v64
	v_lshl_add_u64 v[20:21], v[196:197], 2, s[26:27]
	v_mov_b32_e32 v17, v238
	s_waitcnt vmcnt(0)
	v_mul_f32_e64 v19, |v17|, s10
	v_exp_f32_e32 v19, v19
	v_max_f32_e32 v17, v17, v17
	v_min_f32_e32 v17, 0, v17
	v_add_f32_e32 v19, 1.0, v19
	v_cmp_gt_f32_e32 vcc, s11, v19
	s_nop 1
	v_cndmask_b32_e64 v20, 0, 32, vcc
	v_ldexp_f32 v19, v19, v20
	v_log_f32_e32 v19, v19
	s_nop 0
	v_mul_f32_e32 v20, 0x3f317217, v19
	v_fma_f32 v20, v19, s12, -v20
	v_fmac_f32_e32 v20, 0x3377d1cf, v19
	v_fmac_f32_e32 v20, 0x3f317217, v19
	v_cmp_lt_f32_e64 s[38:39], |v19|, s13
	s_nop 1
	v_cndmask_b32_e64 v19, v19, v20, s[38:39]
	v_cndmask_b32_e32 v20, 0, v207, vcc
	v_sub_f32_e32 v19, v19, v20
	v_sub_f32_e32 v17, v17, v19
.LBB0_7190:
	s_andn2_saveexec_b64 s[80:81], s[80:81]
	s_cbranch_execz .LBB0_7193
	v_mad_i64_i32 v[20:21], s[38:39], s22, v64, 0
	v_lshl_add_u64 v[20:21], v[20:21], 2, s[0:1]
	v_mov_b32_e32 v17, v238
	s_andn2_b64 vcc, exec, s[76:77]
	s_cbranch_vccnz .LBB0_7193
	s_waitcnt vmcnt(0)
	v_mul_f32_e64 v19, |v17|, s10
	v_exp_f32_e32 v19, v19
	v_max_f32_e32 v17, v17, v17
	v_min_f32_e32 v17, 0, v17
	v_add_f32_e32 v19, 1.0, v19
	v_cmp_gt_f32_e32 vcc, s11, v19
	s_nop 1
	v_cndmask_b32_e64 v20, 0, 32, vcc
	v_ldexp_f32 v19, v19, v20
	v_log_f32_e32 v19, v19
	s_nop 0
	v_mul_f32_e32 v20, 0x3f317217, v19
	v_fma_f32 v20, v19, s12, -v20
	v_fmac_f32_e32 v20, 0x3377d1cf, v19
	v_fmac_f32_e32 v20, 0x3f317217, v19
	v_cmp_lt_f32_e64 s[38:39], |v19|, s13
	s_nop 1
	v_cndmask_b32_e64 v19, v19, v20, s[38:39]
	v_cndmask_b32_e32 v20, 0, v207, vcc
	v_sub_f32_e32 v19, v19, v20
	v_sub_f32_e32 v17, v17, v19

.LBB0_7194:
	s_or_b64 exec, exec, s[78:79]
	v_or_b32_e32 v65, 15, v50
	s_and_saveexec_b64 s[78:79], s[36:37]
	s_cbranch_execz .LBB0_7201
	v_cmp_le_i32_e32 vcc, s28, v65
	s_and_saveexec_b64 s[38:39], vcc
	s_xor_b64 s[80:81], exec, s[38:39]
	s_cbranch_execz .LBB0_7197
	v_subrev_u32_e32 v196, s28, v65
	v_lshl_add_u64 v[18:19], v[196:197], 2, s[26:27]
	v_mov_b32_e32 v18, v239
	s_waitcnt vmcnt(0)
	v_mul_f32_e64 v19, |v18|, s10
	v_exp_f32_e32 v19, v19
	v_max_f32_e32 v18, v18, v18
	v_min_f32_e32 v18, 0, v18
	v_add_f32_e32 v19, 1.0, v19
	v_cmp_gt_f32_e32 vcc, s11, v19
	s_nop 1
	v_cndmask_b32_e64 v20, 0, 32, vcc
	v_ldexp_f32 v19, v19, v20
	v_log_f32_e32 v19, v19
	s_nop 0
	v_mul_f32_e32 v20, 0x3f317217, v19
	v_fma_f32 v20, v19, s12, -v20
	v_fmac_f32_e32 v20, 0x3377d1cf, v19
	v_fmac_f32_e32 v20, 0x3f317217, v19
	v_cmp_lt_f32_e64 s[38:39], |v19|, s13
	s_nop 1
	v_cndmask_b32_e64 v19, v19, v20, s[38:39]
	v_cndmask_b32_e32 v20, 0, v207, vcc
	v_sub_f32_e32 v19, v19, v20
	v_sub_f32_e32 v18, v18, v19
.LBB0_7197:
	s_andn2_saveexec_b64 s[26:27], s[80:81]
	s_cbranch_execz .LBB0_7200
	v_mad_i64_i32 v[18:19], s[38:39], s22, v65, 0
	v_lshl_add_u64 v[18:19], v[18:19], 2, s[0:1]
	v_mov_b32_e32 v18, v239
	s_andn2_b64 vcc, exec, s[76:77]
	s_cbranch_vccnz .LBB0_7200
	s_waitcnt vmcnt(0)
	v_mul_f32_e64 v19, |v18|, s10
	v_exp_f32_e32 v19, v19
	v_max_f32_e32 v18, v18, v18
	v_min_f32_e32 v18, 0, v18
	v_add_f32_e32 v19, 1.0, v19
	v_cmp_gt_f32_e32 vcc, s11, v19
	s_nop 1
	v_cndmask_b32_e64 v20, 0, 32, vcc
	v_ldexp_f32 v19, v19, v20
	v_log_f32_e32 v19, v19
	s_nop 0
	v_mul_f32_e32 v20, 0x3f317217, v19
	v_fma_f32 v20, v19, s12, -v20
	v_fmac_f32_e32 v20, 0x3377d1cf, v19
	v_fmac_f32_e32 v20, 0x3f317217, v19
	v_cmp_lt_f32_e64 s[38:39], |v19|, s13
	s_nop 1
	v_cndmask_b32_e64 v19, v19, v20, s[38:39]
	v_cndmask_b32_e32 v20, 0, v207, vcc
	v_sub_f32_e32 v19, v19, v20
	v_sub_f32_e32 v18, v18, v19
